# M1: RG-LRU conv inputs prefetched one unit ahead, RWKV pre-pass output stores deferred behind next unit staging; adaLN GEMM epilogue bias loads hoisted
# speedup vs baseline: 1.0295x; 1.0037x over previous
; __device__ __forceinline__ float bf2f(bf16_t h) { return __uint_as_float((unsigned)h << 16); }
; __device__ __forceinline__ bf16_t f2bf(float f) { return (bf16_t)(cvt_pk_bf16(f, 0.f) & 0xffffu); }
; __device__ __forceinline__ void phase_m1(PP P, int l, LAS unsigned char* lds, const Ids I) {
;     ...
;             const float* cw = P->in[I_CONVW] + (size_t)l * 4 * 512; const float cwv[4] = {cw[chg], cw[512 + chg], cw[1024 + chg], cw[1536 + chg]}; const float cb = P->in[I_CONVB][l * 512 + chg];
; #pragma unroll
;             for (int i = 0; i < 8; ++i) { const int r = r0 + tg * 8 + i, t = t_in_seq(r); float a = cb;
; #pragma unroll
;                 for (int j = 0; j < 4; ++j) { const int ts = t - 3 + j; float xv;
;                     if (ts >= 0) xv = bf2f(PR[(size_t)(r - 3 + j) * INW + chg]);
;                     else xv = (r < MTP) ? 0.f : P->in[I_SCONV][(((size_t)l * 128 + ((r - MTP) >> 2)) * 3 + (ts + 3)) * 512 + chg];
;                     a += xv * cwv[j]; }
;                 XC[d * 68 + tg * 8 + i] = a; XB[(tg * 8 + i) * 72 + d] = f2bf(a); }
.LBB0_94:
	s_and_b32 s25, s0, 0xffffffc0
	v_or_b32_e32 v40, s3, v66
	v_lshlrev_b32_e32 v144, 2, v40
	v_lshlrev_b32_e32 v41, 1, v40
	s_lshr_b32 s4, s62, 3
	s_add_i32 s26, s25, s4
	s_cmp_lg_u32 s22, 0
	s_cbranch_scc1 .Lcv_top_wait
	s_load_dwordx4 s[28:31], s[88:89], 0x88
	v_or_b32_e32 v32, s27, v40
	v_lshlrev_b32_e32 v32, 2, v32
	s_waitcnt lgkmcnt(0)
	s_add_u32 s4, s28, s24
	s_addc_u32 s5, s29, 0
	global_load_dword v153, v144, s[4:5]
	global_load_dword v152, v144, s[4:5] offset:2048
	s_add_u32 s4, s4, 0x1000
	s_addc_u32 s5, s5, 0
	global_load_dword v154, v144, s[4:5]
	global_load_dword v155, v144, s[4:5] offset:2048
	global_load_dword v156, v32, s[30:31]
	s_cmp_ge_i32 s26, s91
	s_cbranch_scc1 .Lcv_ld_sample_a
	s_add_i32 s18, s26, -3
	s_mul_hi_i32 s19, s18, s73
	s_mul_i32 s18, s18, s73
	s_add_u32 s18, s60, s18
	s_addc_u32 s19, s61, s19
	global_load_ushort v116, v41, s[18:19]
	s_add_u32 s18, s18, 0x1600
	s_addc_u32 s19, s19, 0
	global_load_ushort v117, v41, s[18:19]
	s_add_u32 s18, s18, 0x1600
	s_addc_u32 s19, s19, 0
	global_load_ushort v118, v41, s[18:19]
	s_add_u32 s18, s18, 0x1600
	s_addc_u32 s19, s19, 0
	global_load_ushort v119, v41, s[18:19]
	s_add_u32 s18, s18, 0x1600
	s_addc_u32 s19, s19, 0
	global_load_ushort v120, v41, s[18:19]
	s_add_u32 s18, s18, 0x1600
	s_addc_u32 s19, s19, 0
	global_load_ushort v121, v41, s[18:19]
	s_add_u32 s18, s18, 0x1600
	s_addc_u32 s19, s19, 0
	global_load_ushort v122, v41, s[18:19]
	s_add_u32 s18, s18, 0x1600
	s_addc_u32 s19, s19, 0
	global_load_ushort v126, v41, s[18:19]
	s_add_u32 s18, s18, 0x1600
	s_addc_u32 s19, s19, 0
	global_load_ushort v127, v41, s[18:19]
	s_add_u32 s18, s18, 0x1600
	s_addc_u32 s19, s19, 0
	global_load_ushort v128, v41, s[18:19]
	s_add_u32 s18, s18, 0x1600
	s_addc_u32 s19, s19, 0
	global_load_ushort v129, v41, s[18:19]
	s_branch .Lcv_ld_done_a
.Lcv_ld_sample_a:
	s_load_dwordx2 s[20:21], s[88:89], 0x20
	s_mul_hi_u32 s19, s26, s73
	s_mul_i32 s18, s26, s73
	s_add_u32 s18, s60, s18
	s_addc_u32 s19, s61, s19
	global_load_ushort v119, v41, s[18:19]
	s_add_u32 s18, s18, 0x1600
	s_addc_u32 s19, s19, 0
	global_load_ushort v120, v41, s[18:19]
	s_add_u32 s18, s18, 0x1600
	s_addc_u32 s19, s19, 0
	global_load_ushort v121, v41, s[18:19]
	s_add_u32 s18, s18, 0x1600
	s_addc_u32 s19, s19, 0
	global_load_ushort v122, v41, s[18:19]
	s_add_u32 s18, s18, 0x1600
	s_addc_u32 s19, s19, 0
	global_load_ushort v126, v41, s[18:19]
	s_add_u32 s18, s18, 0x1600
	s_addc_u32 s19, s19, 0
	global_load_ushort v127, v41, s[18:19]
	s_add_u32 s18, s18, 0x1600
	s_addc_u32 s19, s19, 0
	global_load_ushort v128, v41, s[18:19]
	s_add_u32 s18, s18, 0x1600
	s_addc_u32 s19, s19, 0
	global_load_ushort v129, v41, s[18:19]
	s_sub_i32 s4, s26, s91
	s_lshr_b32 s4, s4, 2
	s_add_i32 s4, s4, s34
	s_mul_i32 s4, s4, 0x1800
	s_waitcnt lgkmcnt(0)
	s_add_u32 s18, s20, s4
	s_addc_u32 s19, s21, 0
	global_load_dword v116, v144, s[18:19]
	global_load_dword v117, v144, s[18:19] offset:2048
	s_add_u32 s18, s18, 0x1000
	s_addc_u32 s19, s19, 0
	global_load_dword v118, v144, s[18:19]
	global_load_dword v123, v144, s[18:19] offset:2048
	s_add_u32 s18, s18, 0x1000
	s_addc_u32 s19, s19, 0
	global_load_dword v124, v144, s[18:19]
	global_load_dword v125, v144, s[18:19] offset:2048
.Lcv_ld_done_a:
	s_waitcnt vmcnt(0)
	s_branch .Lcv_convert
.Lcv_top_wait:
	s_waitcnt vmcnt(2)
.Lcv_convert:
	s_cmp_ge_i32 s26, s91
	s_cbranch_scc1 .Lcv_conv_sample
	v_lshlrev_b32_e32 v116, 16, v116
	v_lshlrev_b32_e32 v117, 16, v117
	v_lshlrev_b32_e32 v118, 16, v118
	v_lshlrev_b32_e32 v119, 16, v119
	v_lshlrev_b32_e32 v120, 16, v120
	v_lshlrev_b32_e32 v121, 16, v121
	v_lshlrev_b32_e32 v122, 16, v122
	v_lshlrev_b32_e32 v126, 16, v126
	v_lshlrev_b32_e32 v127, 16, v127
	v_lshlrev_b32_e32 v128, 16, v128
	v_lshlrev_b32_e32 v129, 16, v129
	s_and_b32 s4, s26, 0x7ff
	s_cmp_lg_u32 s4, 0
	s_cbranch_scc1 .Lcv_nozero
	v_mov_b32_e32 v116, 0
	v_mov_b32_e32 v117, 0
	v_mov_b32_e32 v118, 0

; __device__ __forceinline__ float bf2f(bf16_t h) { return __uint_as_float((unsigned)h << 16); }
; __device__ __forceinline__ bf16_t f2bf(float f) { return (bf16_t)(cvt_pk_bf16(f, 0.f) & 0xffffu); }
; __device__ __forceinline__ void phase_m1(PP P, int l, LAS unsigned char* lds, const Ids I) {
;     ...
;         for (int u = BID; u < 264 * 8; u += NB) {
;             const int tt = u >> 3, n = u & 7, r0 = tt * 64, chg = n * 64 + d;
;     ...
;             const float* cw = P->in[I_CONVW] + (size_t)l * 4 * 512; const float cwv[4] = {cw[chg], cw[512 + chg], cw[1024 + chg], cw[1536 + chg]}; const float cb = P->in[I_CONVB][l * 512 + chg];
; #pragma unroll
;             for (int i = 0; i < 8; ++i) { const int r = r0 + tg * 8 + i, t = t_in_seq(r); float a = cb;
; #pragma unroll
;                 for (int j = 0; j < 4; ++j) { const int ts = t - 3 + j; float xv;
;                     if (ts >= 0) xv = bf2f(PR[(size_t)(r - 3 + j) * INW + chg]);
;                     else xv = (r < MTP) ? 0.f : P->in[I_SCONV][(((size_t)l * 128 + ((r - MTP) >> 2)) * 3 + (ts + 3)) * 512 + chg];
;                     a += xv * cwv[j]; }
;                 XC[d * 68 + tg * 8 + i] = a; XB[(tg * 8 + i) * 72 + d] = f2bf(a); }
.Lcv_conv_sample:
	v_lshlrev_b32_e32 v119, 16, v119
	v_lshlrev_b32_e32 v120, 16, v120
	v_lshlrev_b32_e32 v121, 16, v121
	v_lshlrev_b32_e32 v122, 16, v122
	v_lshlrev_b32_e32 v126, 16, v126
	v_lshlrev_b32_e32 v127, 16, v127
	v_lshlrev_b32_e32 v128, 16, v128
	v_lshlrev_b32_e32 v129, 16, v129
.Lcv_fma:
	v_fma_f32 v130, v153, v116, v156
	v_fmac_f32_e32 v130, v152, v117
	v_fmac_f32_e32 v130, v154, v118
	v_fmac_f32_e32 v130, v155, v119
	v_fma_f32 v131, v153, v117, v156
	v_fmac_f32_e32 v131, v152, v118
	v_fmac_f32_e32 v131, v154, v119
	v_fmac_f32_e32 v131, v155, v120
	v_fma_f32 v132, v153, v118, v156
	v_fmac_f32_e32 v132, v152, v119
	v_fmac_f32_e32 v132, v154, v120
	v_fmac_f32_e32 v132, v155, v121
	v_fma_f32 v133, v153, v119, v156
	v_fmac_f32_e32 v133, v152, v120
	v_fmac_f32_e32 v133, v154, v121
	v_fmac_f32_e32 v133, v155, v122
	v_fma_f32 v134, v153, v123, v156
	v_fmac_f32_e32 v134, v152, v124
	v_fmac_f32_e32 v134, v154, v125
	v_fmac_f32_e32 v134, v155, v126
	v_fma_f32 v135, v153, v124, v156
	v_fmac_f32_e32 v135, v152, v125
	v_fmac_f32_e32 v135, v154, v126
	v_fmac_f32_e32 v135, v155, v127
	v_fma_f32 v136, v153, v125, v156
	v_fmac_f32_e32 v136, v152, v126
	v_fmac_f32_e32 v136, v154, v127
	v_fmac_f32_e32 v136, v155, v128
	v_fma_f32 v137, v153, v126, v156
	v_fmac_f32_e32 v137, v152, v127
	v_fmac_f32_e32 v137, v154, v128
	v_fmac_f32_e32 v137, v155, v129
	s_add_i32 s18, s1, s72
	s_cmpk_gt_i32 s18, 0x83f
	s_cbranch_scc1 .Lcv_pf_done
	s_add_i32 s18, s0, s44
	s_and_b32 s18, s18, 0xffffffc0
	s_lshr_b32 s4, s62, 3
	s_add_i32 s100, s18, s4
	v_or_b32_e32 v142, s3, v66
	v_lshlrev_b32_e32 v143, 2, v142
	v_lshlrev_b32_e32 v142, 1, v142
	s_cmp_ge_i32 s100, s91
	s_cbranch_scc1 .Lcv_ld_sample_b
	s_add_i32 s18, s100, -3
	s_mul_hi_i32 s19, s18, s73
	s_mul_i32 s18, s18, s73
	s_add_u32 s18, s60, s18
	s_addc_u32 s19, s61, s19
	global_load_ushort v116, v142, s[18:19]
	s_add_u32 s18, s18, 0x1600
	s_addc_u32 s19, s19, 0
	global_load_ushort v117, v142, s[18:19]
	s_add_u32 s18, s18, 0x1600
	s_addc_u32 s19, s19, 0
	global_load_ushort v118, v142, s[18:19]
	s_add_u32 s18, s18, 0x1600
	s_addc_u32 s19, s19, 0
	global_load_ushort v119, v142, s[18:19]
	s_add_u32 s18, s18, 0x1600
	s_addc_u32 s19, s19, 0
	global_load_ushort v120, v142, s[18:19]
	s_add_u32 s18, s18, 0x1600
	s_addc_u32 s19, s19, 0
	global_load_ushort v121, v142, s[18:19]
	s_add_u32 s18, s18, 0x1600
	s_addc_u32 s19, s19, 0
	global_load_ushort v122, v142, s[18:19]
	s_add_u32 s18, s18, 0x1600
	s_addc_u32 s19, s19, 0
	global_load_ushort v126, v142, s[18:19]
	s_add_u32 s18, s18, 0x1600
	s_addc_u32 s19, s19, 0
	global_load_ushort v127, v142, s[18:19]
	s_add_u32 s18, s18, 0x1600
	s_addc_u32 s19, s19, 0
	global_load_ushort v128, v142, s[18:19]
	s_add_u32 s18, s18, 0x1600
	s_addc_u32 s19, s19, 0
	global_load_ushort v129, v142, s[18:19]
	s_branch .Lcv_ld_done_b
.Lcv_ld_sample_b:
	s_load_dwordx2 s[20:21], s[88:89], 0x20
	s_mul_hi_u32 s19, s100, s73
	s_mul_i32 s18, s100, s73
	s_add_u32 s18, s60, s18
	s_addc_u32 s19, s61, s19
	global_load_ushort v119, v142, s[18:19]
	s_add_u32 s18, s18, 0x1600
	s_addc_u32 s19, s19, 0
	global_load_ushort v120, v142, s[18:19]
	s_add_u32 s18, s18, 0x1600
	s_addc_u32 s19, s19, 0
	global_load_ushort v121, v142, s[18:19]
	s_add_u32 s18, s18, 0x1600
	s_addc_u32 s19, s19, 0
	global_load_ushort v122, v142, s[18:19]
	s_add_u32 s18, s18, 0x1600
	s_addc_u32 s19, s19, 0
	global_load_ushort v126, v142, s[18:19]
	s_add_u32 s18, s18, 0x1600
	s_addc_u32 s19, s19, 0
	global_load_ushort v127, v142, s[18:19]
	s_add_u32 s18, s18, 0x1600
	s_addc_u32 s19, s19, 0
	global_load_ushort v128, v142, s[18:19]
	s_add_u32 s18, s18, 0x1600
	s_addc_u32 s19, s19, 0
	global_load_ushort v129, v142, s[18:19]
	s_sub_i32 s4, s100, s91
	s_lshr_b32 s4, s4, 2
	s_add_i32 s4, s4, s34
	s_mul_i32 s4, s4, 0x1800
	s_waitcnt lgkmcnt(0)
	s_add_u32 s18, s20, s4
	s_addc_u32 s19, s21, 0
	global_load_dword v116, v143, s[18:19]
	global_load_dword v117, v143, s[18:19] offset:2048
	s_add_u32 s18, s18, 0x1000
	s_addc_u32 s19, s19, 0
	global_load_dword v118, v143, s[18:19]
	global_load_dword v123, v143, s[18:19] offset:2048
	s_add_u32 s18, s18, 0x1000
	s_addc_u32 s19, s19, 0
	global_load_dword v124, v143, s[18:19]
	global_load_dword v125, v143, s[18:19] offset:2048
.Lcv_ld_done_b:
	s_branch .Lcv_pf_done
	s_nop 0
	s_nop 0
	s_nop 0
	s_nop 0
	s_nop 0
	s_nop 0
	s_nop 0
	s_nop 0
	s_nop 0
	s_nop 0
	s_nop 0
	s_nop 0
	s_nop 0
	s_nop 0
	s_nop 0
	s_nop 0
	s_nop 0
	s_nop 0
	s_nop 0
	s_nop 0
	s_nop 0
	s_nop 0
	s_nop 0
	s_nop 0
	s_nop 0
	s_nop 0
	s_nop 0
	s_nop 0
	s_nop 0
	s_nop 0
	s_nop 0
	s_nop 0
	s_nop 0
	s_nop 0
	s_nop 0
	s_nop 0
	s_nop 0
	s_nop 0
	s_nop 0
	s_nop 0
	s_nop 0
	s_nop 0
	s_nop 0
	s_nop 0
.Lcv_pf_done:
	ds_write_b128 v68, v[130:133]
	ds_write_b128 v68, v[134:137] offset:16
	v_cvt_pk_bf16_f32 v138, v130, v145
	ds_write_b16 v81, v138 offset:17408
	v_cvt_pk_bf16_f32 v139, v131, v145
	ds_write_b16 v81, v139 offset:17552
	v_cvt_pk_bf16_f32 v140, v132, v145
	ds_write_b16 v81, v140 offset:17696
	v_cvt_pk_bf16_f32 v141, v133, v145
	ds_write_b16 v81, v141 offset:17840
	v_cvt_pk_bf16_f32 v138, v134, v145
	ds_write_b16 v81, v138 offset:17984
	v_cvt_pk_bf16_f32 v139, v135, v145
	ds_write_b16 v81, v139 offset:18128
	v_cvt_pk_bf16_f32 v140, v136, v145
	ds_write_b16 v81, v140 offset:18272
	v_cvt_pk_bf16_f32 v141, v137, v145
	ds_write_b16 v81, v141 offset:18416
	v_cndmask_b32_e64 v55, 0, 1, s[8:9]
	s_mov_b64 s[18:19], -1
	v_cmp_ne_u32_e64 s[4:5], 1, v55
	s_andn2_b64 vcc, exec, s[8:9]
	v_add_u32_e32 v55, v85, v70
	s_waitcnt lgkmcnt(0)
	s_barrier
	ds_read_b128 v[32:35], v79 offset:17408
	ds_read_b128 v[86:89], v79 offset:17472
	s_waitcnt lgkmcnt(1)
	v_mfma_f32_16x16x32_bf16 v[36:39], v[32:35], v[0:3], 0
	s_waitcnt lgkmcnt(0)
	v_mfma_f32_16x16x32_bf16 v[44:47], v[86:89], v[4:7], v[36:39]
	v_mfma_f32_16x16x32_bf16 v[40:43], v[32:35], v[8:11], 0
	v_mfma_f32_16x16x32_bf16 v[90:93], v[32:35], v[16:19], 0
	s_nop 5
	v_add_f32_e32 v44, v49, v44
	v_mul_f32_e32 v44, 0xbfb8aa3b, v44
	v_exp_f32_e32 v44, v44
	v_mfma_f32_16x16x32_bf16 v[32:35], v[32:35], v[24:27], 0
	v_add_f32_e32 v44, 1.0, v44
	v_mfma_f32_16x16x32_bf16 v[40:43], v[86:89], v[12:15], v[40:43]
	v_rcp_f32_e32 v44, v44
	v_mfma_f32_16x16x32_bf16 v[36:39], v[86:89], v[20:23], v[90:93]
	v_mfma_f32_16x16x32_bf16 v[32:35], v[86:89], v[28:31], v[32:35]
	s_cbranch_vccnz .LBB0_142
	v_mul_f32_e32 v57, 0xc1000000, v44
	v_mul_f32_e32 v57, v60, v57
	s_mov_b64 s[18:19], 0
	v_cvt_pk_bf16_f32 v57, v57, v145
	ds_write_b16 v55, v57 offset:26624

; __device__ __forceinline__ unsigned cvt_pk_bf16(float lo, float hi) { unsigned r; asm("v_cvt_pk_bf16_f32 %0, %1, %2" : "=v"(r) : "v"(lo), "v"(hi)); return r; }
; __device__ __forceinline__ void phase_m1(PP P, int l, LAS unsigned char* lds, const Ids I) {
;     ...
;         const int lane = tid & 63, quad = lane >> 4, l15 = lane & 15, hd = __builtin_amdgcn_readfirstlane(tid >> 6); const float* mu = P->in[I_MU] + (size_t)l * PW;
;         bf16x8 bfw[4][2], bfa[4][2]; float w0v[4], a0v[4], kkv[4], kav[4];
; #pragma unroll
;         for (int nt = 0; nt < 4; ++nt) { const int dd = hd * 64 + nt * 16 + l15;
;             w0v[nt] = P->in[I_W0][l * 512 + dd]; a0v[nt] = P->in[I_A0][l * 512 + dd]; kkv[nt] = P->in[I_KK][l * 512 + dd]; kav[nt] = P->in[I_KA][l * 512 + dd];
; #pragma unroll
;             for (int ks = 0; ks < 2; ++ks) { const float* wp = P->in[I_W2] + ((size_t)l * 64 + ks * 32 + quad * 8) * 512 + dd; const float* ap = P->in[I_A2] + ((size_t)l * 64 + ks * 32 + quad * 8) * 512 + dd; u32x4 pk;
;                 pk.x = cvt_pk_bf16(wp[0], wp[512]); pk.y = cvt_pk_bf16(wp[1024], wp[1536]); pk.z = cvt_pk_bf16(wp[2048], wp[2560]); pk.w = cvt_pk_bf16(wp[3072], wp[3584]); bfw[nt][ks] = __builtin_bit_cast(bf16x8, pk);
;                 pk.x = cvt_pk_bf16(ap[0], ap[512]); pk.y = cvt_pk_bf16(ap[1024], ap[1536]); pk.z = cvt_pk_bf16(ap[2048], ap[2560]); pk.w = cvt_pk_bf16(ap[3072], ap[3584]); bfa[nt][ks] = __builtin_bit_cast(bf16x8, pk); } }
.LBB0_224:
	v_writelane_b32 v254, s36, 50
	v_readfirstlane_b32 s0, v96
	s_load_dwordx8 s[4:11], s[88:89], 0xc8
	v_writelane_b32 v254, s37, 51
	s_andn2_b32 s0, s0, 63
	v_writelane_b32 v254, s42, 52
	v_or_b32_e32 v66, s0, v64
	v_ashrrev_i32_e32 v67, 31, v66
	v_writelane_b32 v254, s43, 53
	v_writelane_b32 v254, s47, 54
	v_lshlrev_b64 v[0:1], 2, v[66:67]
	s_waitcnt lgkmcnt(0)
	v_lshl_add_u64 v[8:9], s[6:7], 0, v[0:1]
	v_lshl_add_u64 v[10:11], s[10:11], 0, v[0:1]
	v_lshlrev_b32_e32 v0, 14, v65
	v_readlane_b32 s1, v254, 41
	s_movk_i32 s6, 0x2000
	s_movk_i32 s7, 0x3000
	v_lshl_or_b32 v144, s1, 17, v0
	v_lshl_add_u64 v[48:49], v[8:9], 0, v[144:145]
	global_load_dword v0, v[48:49], off
	global_load_dword v152, v[48:49], off offset:2048
	s_movk_i32 s1, 0x1000
	v_add_co_u32_e32 v54, vcc, s1, v48
	v_lshl_add_u64 v[52:53], v[10:11], 0, v[144:145]
	s_nop 0
	v_addc_co_u32_e32 v55, vcc, 0, v49, vcc
	v_add_co_u32_e32 v50, vcc, s6, v48
	v_or_b32_e32 v144, 0x10000, v144
	s_nop 0
	v_addc_co_u32_e32 v51, vcc, 0, v49, vcc
	v_add_co_u32_e32 v58, vcc, s7, v48
	v_lshl_add_u64 v[72:73], v[8:9], 0, v[144:145]
	s_nop 0
	v_addc_co_u32_e32 v59, vcc, 0, v49, vcc
	v_add_co_u32_e32 v62, vcc, s1, v52
	v_lshl_add_u64 v[60:61], v[10:11], 0, v[144:145]
	s_nop 0
	v_addc_co_u32_e32 v63, vcc, 0, v53, vcc
	v_add_co_u32_e32 v56, vcc, s6, v52
	s_movk_i32 s3, 0xb00
	s_nop 0
	v_addc_co_u32_e32 v57, vcc, 0, v53, vcc
	v_add_co_u32_e32 v68, vcc, s7, v52
	s_cmpk_lt_i32 s93, 0x420
	s_nop 0
	v_addc_co_u32_e32 v69, vcc, 0, v53, vcc
	v_add_co_u32_e32 v74, vcc, s1, v72
	global_load_dword v1, v[50:51], off offset:-4096
	global_load_dword v153, v[54:55], off offset:2048
	v_addc_co_u32_e32 v75, vcc, 0, v73, vcc
	v_add_co_u32_e32 v70, vcc, s6, v72
	global_load_dword v2, v[50:51], off
	global_load_dword v154, v[50:51], off offset:2048
	v_addc_co_u32_e32 v71, vcc, 0, v73, vcc
	v_add_co_u32_e32 v76, vcc, s7, v72
	global_load_dword v3, v[58:59], off
	global_load_dword v155, v[58:59], off offset:2048
	v_addc_co_u32_e32 v77, vcc, 0, v73, vcc
	v_add_co_u32_e32 v80, vcc, s1, v60
	global_load_dword v4, v[52:53], off
	global_load_dword v156, v[52:53], off offset:2048
	v_addc_co_u32_e32 v81, vcc, 0, v61, vcc
	v_add_co_u32_e32 v78, vcc, s6, v60
	global_load_dword v5, v[56:57], off offset:-4096
	global_load_dword v157, v[62:63], off offset:2048
	v_addc_co_u32_e32 v79, vcc, 0, v61, vcc
	v_add_co_u32_e32 v82, vcc, s7, v60
	global_load_dword v6, v[56:57], off
	global_load_dword v158, v[56:57], off offset:2048
	v_addc_co_u32_e32 v83, vcc, 0, v61, vcc
	global_load_dword v7, v[68:69], off
	global_load_dword v160, v[68:69], off offset:2048
	global_load_dword v8, v[72:73], off
	global_load_dword v159, v[72:73], off offset:2048
	global_load_dword v9, v[70:71], off offset:-4096
	global_load_dword v161, v[74:75], off offset:2048
	global_load_dword v10, v[70:71], off
	global_load_dword v162, v[70:71], off offset:2048
	global_load_dword v11, v[76:77], off
	global_load_dword v163, v[76:77], off offset:2048
	global_load_dword v12, v[60:61], off
	global_load_dword v164, v[60:61], off offset:2048
	global_load_dword v13, v[78:79], off offset:-4096
	global_load_dword v165, v[80:81], off offset:2048
	global_load_dword v14, v[78:79], off
	global_load_dword v166, v[78:79], off offset:2048
	global_load_dword v15, v[82:83], off
	global_load_dword v167, v[82:83], off offset:2048
	global_load_dword v16, v[48:49], off offset:64
	global_load_dword v168, v[48:49], off offset:2112
	global_load_dword v17, v[54:55], off offset:64
	global_load_dword v169, v[54:55], off offset:2112
	global_load_dword v18, v[50:51], off offset:64
	global_load_dword v170, v[50:51], off offset:2112
	global_load_dword v19, v[58:59], off offset:64
	global_load_dword v171, v[58:59], off offset:2112
	global_load_dword v20, v[52:53], off offset:64
	global_load_dword v172, v[52:53], off offset:2112
	global_load_dword v21, v[62:63], off offset:64
	global_load_dword v173, v[62:63], off offset:2112
	global_load_dword v22, v[56:57], off offset:64
	global_load_dword v176, v[56:57], off offset:2112
	global_load_dword v23, v[68:69], off offset:64
	global_load_dword v177, v[68:69], off offset:2112
	global_load_dword v24, v[72:73], off offset:64
	global_load_dword v178, v[72:73], off offset:2112
	global_load_dword v25, v[74:75], off offset:64
	global_load_dword v179, v[74:75], off offset:2112
	global_load_dword v26, v[70:71], off offset:64
	global_load_dword v180, v[70:71], off offset:2112
	global_load_dword v27, v[76:77], off offset:64
	global_load_dword v181, v[76:77], off offset:2112
	global_load_dword v28, v[60:61], off offset:64
	global_load_dword v182, v[60:61], off offset:2112
	global_load_dword v29, v[80:81], off offset:64
	global_load_dword v183, v[80:81], off offset:2112
	global_load_dword v30, v[78:79], off offset:64
	global_load_dword v187, v[78:79], off offset:2112
	global_load_dword v31, v[82:83], off offset:64
	global_load_dword v188, v[82:83], off offset:2112
	global_load_dword v32, v[48:49], off offset:128
	global_load_dword v189, v[48:49], off offset:2176
	global_load_dword v33, v[54:55], off offset:128
	global_load_dword v190, v[54:55], off offset:2176
	global_load_dword v34, v[50:51], off offset:128
	global_load_dword v191, v[50:51], off offset:2176
	global_load_dword v35, v[58:59], off offset:128
	global_load_dword v192, v[58:59], off offset:2176
	global_load_dword v36, v[52:53], off offset:128
	global_load_dword v193, v[52:53], off offset:2176
	global_load_dword v37, v[62:63], off offset:128
	global_load_dword v194, v[62:63], off offset:2176
	global_load_dword v38, v[56:57], off offset:128
	global_load_dword v195, v[56:57], off offset:2176
; __device__ __forceinline__ unsigned cvt_pk_bf16(float lo, float hi) { unsigned r; asm("v_cvt_pk_bf16_f32 %0, %1, %2" : "=v"(r) : "v"(lo), "v"(hi)); return r; }
; __device__ __forceinline__ void phase_m1(PP P, int l, LAS unsigned char* lds, const Ids I) {
;     ...
; #pragma unroll
;             for (int ks = 0; ks < 2; ++ks) { const float* wp = P->in[I_W2] + ((size_t)l * 64 + ks * 32 + quad * 8) * 512 + dd; const float* ap = P->in[I_A2] + ((size_t)l * 64 + ks * 32 + quad * 8) * 512 + dd; u32x4 pk;
;                 pk.x = cvt_pk_bf16(wp[0], wp[512]); pk.y = cvt_pk_bf16(wp[1024], wp[1536]); pk.z = cvt_pk_bf16(wp[2048], wp[2560]); pk.w = cvt_pk_bf16(wp[3072], wp[3584]); bfw[nt][ks] = __builtin_bit_cast(bf16x8, pk);
;                 pk.x = cvt_pk_bf16(ap[0], ap[512]); pk.y = cvt_pk_bf16(ap[1024], ap[1536]); pk.z = cvt_pk_bf16(ap[2048], ap[2560]); pk.w = cvt_pk_bf16(ap[3072], ap[3584]); bfa[nt][ks] = __builtin_bit_cast(bf16x8, pk); } }
	global_load_dword v39, v[68:69], off offset:128
	global_load_dword v196, v[68:69], off offset:2176
	global_load_dword v40, v[72:73], off offset:128
	global_load_dword v197, v[72:73], off offset:2176
	global_load_dword v41, v[74:75], off offset:128
	global_load_dword v198, v[74:75], off offset:2176
	global_load_dword v42, v[70:71], off offset:128
	global_load_dword v199, v[70:71], off offset:2176
	global_load_dword v43, v[76:77], off offset:128
	global_load_dword v200, v[76:77], off offset:2176
	global_load_dword v44, v[60:61], off offset:128
	global_load_dword v201, v[60:61], off offset:2176
	global_load_dword v45, v[80:81], off offset:128
	global_load_dword v202, v[80:81], off offset:2176
	global_load_dword v46, v[78:79], off offset:128
	global_load_dword v203, v[78:79], off offset:2176
	global_load_dword v47, v[82:83], off offset:128
	global_load_dword v204, v[82:83], off offset:2176
	global_load_dword v206, v[48:49], off offset:192
	s_nop 0
	global_load_dword v48, v[48:49], off offset:2240
	s_nop 0
	global_load_dword v49, v[54:55], off offset:192
	s_nop 0
	global_load_dword v205, v[54:55], off offset:2240
	global_load_dword v207, v[50:51], off offset:192
	s_nop 0
	global_load_dword v50, v[50:51], off offset:2240
	global_load_dword v51, v[58:59], off offset:192
	global_load_dword v208, v[58:59], off offset:2240
	global_load_dword v209, v[52:53], off offset:192
	s_nop 0
	global_load_dword v52, v[52:53], off offset:2240
	global_load_dword v53, v[62:63], off offset:192
	global_load_dword v210, v[62:63], off offset:2240
	global_load_dword v54, v[56:57], off offset:192
	global_load_dword v211, v[56:57], off offset:2240
	global_load_dword v55, v[68:69], off offset:192
	global_load_dword v212, v[68:69], off offset:2240
	global_load_dword v56, v[72:73], off offset:192
	global_load_dword v213, v[72:73], off offset:2240
	global_load_dword v57, v[74:75], off offset:192
	global_load_dword v214, v[74:75], off offset:2240
	global_load_dword v58, v[70:71], off offset:192
	global_load_dword v215, v[70:71], off offset:2240
	global_load_dword v59, v[76:77], off offset:192
	global_load_dword v216, v[76:77], off offset:2240
	global_load_dword v217, v[60:61], off offset:192
	s_nop 0
	global_load_dword v60, v[60:61], off offset:2240
	global_load_dword v61, v[80:81], off offset:192
	global_load_dword v218, v[80:81], off offset:2240
	global_load_dword v62, v[78:79], off offset:192
	global_load_dword v219, v[78:79], off offset:2240
	global_load_dword v63, v[82:83], off offset:192
	global_load_dword v67, v[82:83], off offset:2240
	s_waitcnt vmcnt(0)
	v_cvt_pk_bf16_f32 v0, v0, v152
	v_cvt_pk_bf16_f32 v1, v1, v153
	v_cvt_pk_bf16_f32 v2, v2, v154
	v_cvt_pk_bf16_f32 v3, v3, v155
	v_cvt_pk_bf16_f32 v4, v4, v156
	v_cvt_pk_bf16_f32 v5, v5, v157
	v_cvt_pk_bf16_f32 v6, v6, v158
	v_cvt_pk_bf16_f32 v8, v8, v159
	v_cvt_pk_bf16_f32 v7, v7, v160
	v_cvt_pk_bf16_f32 v9, v9, v161
	v_cvt_pk_bf16_f32 v10, v10, v162
	v_cvt_pk_bf16_f32 v11, v11, v163
	v_cvt_pk_bf16_f32 v12, v12, v164
	v_cvt_pk_bf16_f32 v13, v13, v165
	v_cvt_pk_bf16_f32 v14, v14, v166
	v_cvt_pk_bf16_f32 v15, v15, v167
	v_cvt_pk_bf16_f32 v16, v16, v168
	v_cvt_pk_bf16_f32 v17, v17, v169
	v_cvt_pk_bf16_f32 v18, v18, v170
	v_cvt_pk_bf16_f32 v19, v19, v171
	v_cvt_pk_bf16_f32 v20, v20, v172
	v_cvt_pk_bf16_f32 v21, v21, v173
	v_cvt_pk_bf16_f32 v22, v22, v176
	v_cvt_pk_bf16_f32 v23, v23, v177
	v_cvt_pk_bf16_f32 v24, v24, v178
	v_cvt_pk_bf16_f32 v25, v25, v179
	v_cvt_pk_bf16_f32 v26, v26, v180
	v_cvt_pk_bf16_f32 v27, v27, v181
	v_cvt_pk_bf16_f32 v28, v28, v182
	v_cvt_pk_bf16_f32 v29, v29, v183
	v_cvt_pk_bf16_f32 v30, v30, v187
	v_cvt_pk_bf16_f32 v31, v31, v188
	v_cvt_pk_bf16_f32 v32, v32, v189
	v_cvt_pk_bf16_f32 v33, v33, v190
	v_cvt_pk_bf16_f32 v34, v34, v191
	v_cvt_pk_bf16_f32 v35, v35, v192
	v_cvt_pk_bf16_f32 v36, v36, v193
	v_cvt_pk_bf16_f32 v37, v37, v194
	v_cvt_pk_bf16_f32 v38, v38, v195
	v_cvt_pk_bf16_f32 v39, v39, v196
	v_cvt_pk_bf16_f32 v40, v40, v197
	v_cvt_pk_bf16_f32 v41, v41, v198
	v_cvt_pk_bf16_f32 v42, v42, v199
	v_cvt_pk_bf16_f32 v43, v43, v200
	v_cvt_pk_bf16_f32 v44, v44, v201
	v_cvt_pk_bf16_f32 v45, v45, v202
	v_cvt_pk_bf16_f32 v46, v46, v203
	v_cvt_pk_bf16_f32 v47, v47, v204
	v_cvt_pk_bf16_f32 v49, v49, v205
	v_cvt_pk_bf16_f32 v48, v206, v48
	v_cvt_pk_bf16_f32 v50, v207, v50
	v_cvt_pk_bf16_f32 v51, v51, v208
	v_cvt_pk_bf16_f32 v52, v209, v52
	v_cvt_pk_bf16_f32 v53, v53, v210
	v_cvt_pk_bf16_f32 v54, v54, v211
	v_cvt_pk_bf16_f32 v55, v55, v212
	v_cvt_pk_bf16_f32 v56, v56, v213
	v_cvt_pk_bf16_f32 v57, v57, v214
	v_cvt_pk_bf16_f32 v58, v58, v215
	v_cvt_pk_bf16_f32 v59, v59, v216
	v_cvt_pk_bf16_f32 v60, v217, v60
	v_cvt_pk_bf16_f32 v61, v61, v218
	v_cvt_pk_bf16_f32 v62, v62, v219
	v_cvt_pk_bf16_f32 v63, v63, v67
	s_cbranch_scc0 .LBB0_318
; __device__ __forceinline__ unsigned cvt_pk_bf16(float lo, float hi) { unsigned r; asm("v_cvt_pk_bf16_f32 %0, %1, %2" : "=v"(r) : "v"(lo), "v"(hi)); return r; }
; __device__ __forceinline__ void phase_m1(PP P, int l, LAS unsigned char* lds, const Ids I) {
;     ...
;         for (int nt = 0; nt < 4; ++nt) { const int dd = hd * 64 + nt * 16 + l15;
;             w0v[nt] = P->in[I_W0][l * 512 + dd]; a0v[nt] = P->in[I_A0][l * 512 + dd]; kkv[nt] = P->in[I_KK][l * 512 + dd]; kav[nt] = P->in[I_KA][l * 512 + dd];
; #pragma unroll
;             for (int ks = 0; ks < 2; ++ks) { const float* wp = P->in[I_W2] + ((size_t)l * 64 + ks * 32 + quad * 8) * 512 + dd; const float* ap = P->in[I_A2] + ((size_t)l * 64 + ks * 32 + quad * 8) * 512 + dd; u32x4 pk;
;                 pk.x = cvt_pk_bf16(wp[0], wp[512]); pk.y = cvt_pk_bf16(wp[1024], wp[1536]); pk.z = cvt_pk_bf16(wp[2048], wp[2560]); pk.w = cvt_pk_bf16(wp[3072], wp[3584]); bfw[nt][ks] = __builtin_bit_cast(bf16x8, pk);
;                 pk.x = cvt_pk_bf16(ap[0], ap[512]); pk.y = cvt_pk_bf16(ap[1024], ap[1536]); pk.z = cvt_pk_bf16(ap[2048], ap[2560]); pk.w = cvt_pk_bf16(ap[3072], ap[3584]); bfa[nt][ks] = __builtin_bit_cast(bf16x8, pk); } }
;         for (int u = BID; u < MT / 16; u += NB) {
;             const int r0 = u * 16;
; #pragma unroll
;             for (int it = 0; it < 7; ++it) { const int e = tid + 512 * it;
;                 if (e < 16 * 208) { const int tok = e / 208, col = (e - tok * 208) * 8, r = r0 + tok, t = t_in_seq(r);
	s_load_dwordx4 s[16:19], s[88:89], 0xf0
	v_readlane_b32 s1, v254, 47
	v_mul_u32_u24_e32 v64, 0x10e, v64
	s_mov_b32 s7, 0x4ec4ec4f
	v_add_u32_e32 v66, s1, v66
	v_ashrrev_i32_e32 v67, 31, v66
	v_lshlrev_b64 v[66:67], 2, v[66:67]
	v_lshl_add_u64 v[68:69], s[4:5], 0, v[66:67]
	v_lshl_add_u64 v[70:71], s[8:9], 0, v[66:67]
	s_load_dwordx2 s[4:5], s[88:89], 0xc0
	s_waitcnt lgkmcnt(0)
	v_lshl_add_u64 v[72:73], s[16:17], 0, v[66:67]
	v_lshl_add_u64 v[66:67], s[18:19], 0, v[66:67]
	global_load_dword v103, v[68:69], off
	global_load_dword v111, v[68:69], off offset:64
	global_load_dword v119, v[68:69], off offset:128
	global_load_dword v127, v[68:69], off offset:192
	global_load_dword v135, v[70:71], off
	global_load_dword v143, v[70:71], off offset:64
	global_load_dword v147, v[70:71], off offset:128
	global_load_dword v187, v[70:71], off offset:192
	global_load_dword v188, v[72:73], off
	global_load_dword v189, v[72:73], off offset:64
	global_load_dword v190, v[72:73], off offset:128
	global_load_dword v191, v[72:73], off offset:192
	global_load_dword v192, v[66:67], off
	global_load_dword v193, v[66:67], off offset:64
	global_load_dword v194, v[66:67], off offset:128
	global_load_dword v195, v[66:67], off offset:192
	v_lshlrev_b32_e32 v66, 4, v65
	v_add3_u32 v196, v85, v64, v66
	v_mul_hi_i32 v66, v96, s7
	v_readlane_b32 s1, v254, 42
	v_lshrrev_b32_e32 v67, 31, v66
	v_ashrrev_i32_e32 v66, 6, v66
	s_add_u32 s44, s4, s1
	v_lshl_add_u32 v70, s0, 1, v85
	s_movk_i32 s0, 0xd00
	v_add_u32_e32 v197, v66, v67
	s_movk_i32 s46, 0xff30
	s_addc_u32 s45, s5, 0
	v_cmp_gt_i32_e64 s[4:5], s0, v96
	v_mad_u64_u32 v[66:67], s[0:1], v197, s46, v[96:97]
	v_and_b32_e32 v67, -8, v66
	s_movk_i32 s47, 0xc0
	v_cmp_eq_u32_e64 s[0:1], s47, v67
	s_movk_i32 s50, 0xbf
	s_movk_i32 s6, 0x110
	v_writelane_b32 v254, s0, 55
	v_lshlrev_b32_e32 v98, 3, v66
	v_mul_lo_u32 v67, v197, s6
	v_writelane_b32 v254, s1, 56
	v_cmp_lt_i32_e64 s[0:1], s50, v66
	v_lshlrev_b32_e32 v66, 4, v66
	v_add3_u32 v102, 0, v67, v66
	v_add_u32_e32 v66, 0x200, v96
	v_writelane_b32 v254, s0, 57
	s_movk_i32 s51, 0xaf0
	v_mul_hi_i32 v67, v66, s7
	v_writelane_b32 v254, s1, 58
	v_lshrrev_b32_e32 v68, 31, v67
	v_ashrrev_i32_e32 v67, 6, v67
	v_ashrrev_i32_e32 v99, 31, v98
	v_and_b32_e32 v64, 0x1f8, v84
	v_lshl_add_u64 v[100:101], v[98:99], 2, s[44:45]
	v_lshlrev_b32_e32 v74, 12, v65
	v_lshl_add_u32 v71, v64, 1, 0
	v_ashrrev_i32_e32 v235, 6, v66
	v_cmp_gt_i32_e64 s[10:11], s3, v96
	v_lshl_add_u64 v[160:161], v[98:99], 1, s[60:61]
	s_lshl_b32 s54, s93, 4
	v_lshlrev_b32_e32 v241, 1, v64
	s_mov_b32 s90, s93
	s_waitcnt vmcnt(15)
	v_mad_u64_u32 v[104:105], s[0:1], v197, s51, v[102:103]
	v_add_u32_e32 v105, v67, v68
	v_mad_u64_u32 v[68:69], s[0:1], v105, s46, v[66:67]
	v_and_b32_e32 v67, -8, v68
	v_lshlrev_b32_e32 v106, 3, v68
	v_cmp_eq_u32_e64 s[0:1], s47, v67
	v_cmp_lt_i32_e64 s[8:9], s50, v68
	v_mul_lo_u32 v67, v105, s6
	v_lshlrev_b32_e32 v68, 4, v68
	v_add3_u32 v110, 0, v67, v68
	v_add_u32_e32 v68, 0x400, v96
	v_writelane_b32 v254, s0, 59
	v_mul_hi_i32 v67, v68, s7
	v_lshrrev_b32_e32 v69, 31, v67
	v_writelane_b32 v254, s1, 60
	s_waitcnt vmcnt(14)
	v_mad_u64_u32 v[112:113], s[0:1], v105, s51, v[110:111]
	v_ashrrev_i32_e32 v67, 6, v67
	s_movk_i32 s0, 0x900
	v_add_u32_e32 v113, v67, v69
	v_cmp_gt_i32_e64 s[16:17], s0, v96
	v_mad_u64_u32 v[68:69], s[0:1], v113, s46, v[68:69]
	v_and_b32_e32 v67, -8, v68
	v_lshlrev_b32_e32 v114, 3, v68
	v_cmp_eq_u32_e64 s[18:19], s47, v67
	v_cmp_lt_i32_e64 s[20:21], s50, v68
	v_mul_lo_u32 v67, v113, s6
	v_lshlrev_b32_e32 v68, 4, v68
	v_add3_u32 v118, 0, v67, v68
	v_add_u32_e32 v68, 0x600, v96
	v_mul_hi_i32 v67, v68, s7
	s_waitcnt vmcnt(13)
	v_mad_u64_u32 v[120:121], s[0:1], v113, s51, v[118:119]
	v_lshrrev_b32_e32 v69, 31, v67
	v_ashrrev_i32_e32 v67, 6, v67
	s_movk_i32 s0, 0x700
	v_add_u32_e32 v121, v67, v69
	v_cmp_gt_i32_e64 s[22:23], s0, v96
	v_mad_u64_u32 v[68:69], s[0:1], v121, s46, v[68:69]
	v_and_b32_e32 v67, -8, v68
	v_lshlrev_b32_e32 v122, 3, v68
	v_cmp_eq_u32_e64 s[24:25], s47, v67
	v_cmp_lt_i32_e64 s[26:27], s50, v68
	v_mul_lo_u32 v67, v121, s6
	v_lshlrev_b32_e32 v68, 4, v68
	v_add3_u32 v126, 0, v67, v68
	v_add_u32_e32 v68, 0x800, v96
	v_mul_hi_i32 v67, v68, s7
	s_waitcnt vmcnt(12)
	v_mad_u64_u32 v[128:129], s[0:1], v121, s51, v[126:127]
	v_lshrrev_b32_e32 v69, 31, v67
	v_ashrrev_i32_e32 v67, 6, v67
	s_movk_i32 s0, 0x500
	v_add_u32_e32 v129, v67, v69
	v_cmp_gt_i32_e64 s[28:29], s0, v96
	v_mad_u64_u32 v[68:69], s[0:1], v129, s46, v[68:69]
	v_and_b32_e32 v67, -8, v68
	v_lshlrev_b32_e32 v130, 3, v68
	v_cmp_eq_u32_e64 s[30:31], s47, v67
	v_cmp_lt_i32_e64 s[34:35], s50, v68
	v_mul_lo_u32 v67, v129, s6
	v_lshlrev_b32_e32 v68, 4, v68
	v_add3_u32 v134, 0, v67, v68
	v_add_u32_e32 v68, 0xa00, v96
	v_mul_hi_i32 v67, v68, s7
	s_waitcnt vmcnt(11)
	v_mad_u64_u32 v[136:137], s[0:1], v129, s51, v[134:135]
	v_lshrrev_b32_e32 v69, 31, v67
	v_ashrrev_i32_e32 v67, 6, v67
	s_movk_i32 s0, 0x300
	v_add_u32_e32 v137, v67, v69
	v_cmp_gt_i32_e64 s[36:37], s0, v96
	v_mad_u64_u32 v[68:69], s[0:1], v137, s46, v[68:69]
	v_and_b32_e32 v67, -8, v68
	v_lshlrev_b32_e32 v138, 3, v68
	v_cmp_eq_u32_e64 s[38:39], s47, v67
	v_cmp_lt_i32_e64 s[40:41], s50, v68
	v_mul_lo_u32 v67, v137, s6
	v_lshlrev_b32_e32 v68, 4, v68
	v_add3_u32 v142, 0, v67, v68
	v_add_u32_e32 v68, 0xc00, v96
	v_mul_hi_i32 v67, v68, s7
	s_waitcnt vmcnt(10)
; #define LAS __attribute__((address_space(3)))
; __device__ __forceinline__ float bf2f(bf16_t h) { return __uint_as_float((unsigned)h << 16); }
; __device__ __forceinline__ bf16_t f2bf(float f) { return (bf16_t)(cvt_pk_bf16(f, 0.f) & 0xffffu); }
; __device__ __forceinline__ float sigmoidf(float x) { return rcpf(1.0f + __expf(-x)); }
; __device__ __forceinline__ void phase_m1(PP P, int l, LAS unsigned char* lds, const Ids I) {
;     ...
;             f32x4 aw[4], aa[4];
; #pragma unroll
;             for (int nt = 0; nt < 4; ++nt) { aw[nt] = (f32x4){0.f, 0.f, 0.f, 0.f}; aa[nt] = (f32x4){0.f, 0.f, 0.f, 0.f}; }
; #pragma unroll
;             for (int ks = 0; ks < 2; ++ks) { const bf16x8 fw = *(const LAS bf16x8*)(AL + l15 * 136 + ks * 32 + quad * 8), fa = *(const LAS bf16x8*)(AL + l15 * 136 + 64 + ks * 32 + quad * 8);
; #pragma unroll
;                 for (int nt = 0; nt < 4; ++nt) { aw[nt] = __builtin_amdgcn_mfma_f32_16x16x32_bf16(fw, bfw[nt][ks], aw[nt], 0, 0, 0); aa[nt] = __builtin_amdgcn_mfma_f32_16x16x32_bf16(fa, bfa[nt][ks], aa[nt], 0, 0, 0); } }
; #pragma unroll
;             for (int j = 0; j < 4; ++j) { const int tk = quad * 4 + j; const LAS bf16_t* xp = XSB + tk * 1536 + hd * 64 + l15; float xk[4], ar[4], kk[4]; float ssq = 0.f;
; #pragma unroll
;                 for (int nt = 0; nt < 4; ++nt) { xk[nt] = bf2f(xp[512 + nt * 16]); ar[nt] = sigmoidf(a0v[nt] + aa[nt][j]); kk[nt] = xk[nt] * kkv[nt]; ssq += kk[nt] * kk[nt]; }
;                 const float rn = 1.0f / fmaxf(sqrtf(row16_allsum(ssq)), 1e-12f);
; #pragma unroll
;                 for (int nt = 0; nt < 4; ++nt) { LAS bf16_t* ob = OR + tk * 512 + hd * 64 + nt * 16 + l15; const float kn = kk[nt] * rn;
;                     ob[0] = xp[nt * 16];
;                     ob[8192] = f2bf(0.60653066f * sigmoidf(w0v[nt] + aw[nt][j]));
;                     ob[2 * 8192] = f2bf(xk[nt] * (1.0f + (ar[nt] - 1.0f) * kav[nt]));
;                     ob[3 * 8192] = xp[1024 + nt * 16];
;                     ob[4 * 8192] = f2bf(kn); ob[5 * 8192] = f2bf(kn * ar[nt]); } }
	v_mad_u64_u32 v[152:153], s[0:1], v137, s51, v[142:143]
	v_lshrrev_b32_e32 v69, 31, v67
	v_ashrrev_i32_e32 v67, 6, v67
	s_movk_i32 s0, 0x100
	v_add_u32_e32 v153, v67, v69
	v_cmp_gt_i32_e64 s[42:43], s0, v96
	v_mad_u64_u32 v[68:69], s[0:1], v153, s46, v[68:69]
	v_lshlrev_b32_e32 v154, 3, v68
	v_ashrrev_i32_e32 v107, 31, v106
	v_ashrrev_i32_e32 v115, 31, v114
	v_ashrrev_i32_e32 v123, 31, v122
	v_ashrrev_i32_e32 v131, 31, v130
	v_ashrrev_i32_e32 v139, 31, v138
	v_ashrrev_i32_e32 v155, 31, v154
	v_and_b32_e32 v67, -8, v68
	v_lshl_add_u64 v[108:109], v[106:107], 2, s[44:45]
	v_lshl_add_u64 v[116:117], v[114:115], 2, s[44:45]
	v_lshl_add_u64 v[124:125], v[122:123], 2, s[44:45]
	v_lshl_add_u64 v[132:133], v[130:131], 2, s[44:45]
	v_lshl_add_u64 v[140:141], v[138:139], 2, s[44:45]
	v_lshl_add_u64 v[156:157], v[154:155], 2, s[44:45]
	v_cmp_eq_u32_e64 s[44:45], s47, v67
	v_cmp_lt_i32_e64 s[46:47], s50, v68
	v_mul_lo_u32 v67, v153, s6
	v_lshlrev_b32_e32 v68, 4, v68
	v_add3_u32 v144, 0, v67, v68
	v_mul_u32_u24_e32 v67, 0x3000, v65
	v_lshl_or_b32 v68, v65, 2, 1
	v_lshl_add_u32 v65, v65, 12, v70
	v_mad_u64_u32 v[158:159], s[0:1], v153, s51, v[144:145]
	v_add_u32_e32 v212, 0x800, v65
	v_add_u32_e32 v213, 0xd900, v65
	v_add_u32_e32 v214, 0x1d900, v65
	v_add_u32_e32 v215, 0x21900, v65
	v_add_u32_e32 v216, 0x1d920, v65
	v_add_u32_e32 v217, 0x21920, v65
	v_add_u32_e32 v218, 0x1d940, v65
	v_add_u32_e32 v219, 0x21940, v65
	v_add_u32_e32 v220, 0x1d960, v65
	v_add_u32_e32 v221, 0x21960, v65
	v_add_u32_e32 v222, 0xc00, v65
	v_add_u32_e32 v223, 0xdd00, v65
	v_add_u32_e32 v224, 0x1dd00, v65
	v_add_u32_e32 v225, 0x21d00, v65
	v_add_u32_e32 v226, 0x1dd20, v65
	v_add_u32_e32 v227, 0x21d20, v65
	v_add_u32_e32 v228, 0x1dd40, v65
	v_add_u32_e32 v229, 0x21d40, v65
	v_add_u32_e32 v230, 0x1dd60, v65
	v_add_u32_e32 v231, 0x21d60, v65
	v_lshl_add_u32 v65, v97, 10, v71
	v_add_u32_e32 v159, v70, v74
	v_mul_u32_u24_e32 v69, 0xc00, v68
	v_lshl_add_u32 v202, v68, 10, v70
	v_add_u32_e32 v232, 0xd100, v65
	v_add_u32_e32 v233, 0x1d100, v65
	v_add_u32_e32 v234, 0x21100, v65
	v_lshl_add_u32 v65, v235, 10, v71
	v_add_u32_e32 v198, 0xd100, v159
	v_add_u32_e32 v199, 0x21140, v159
	v_add_u32_e32 v200, 0x1d160, v159
	v_add_u32_e32 v201, 0x21160, v159
	v_add_u32_e32 v203, 0xd100, v202
	v_add_u32_e32 v204, 0x1d100, v202
	v_add_u32_e32 v205, 0x21100, v202
	v_add_u32_e32 v206, 0x1d120, v202
	v_add_u32_e32 v207, 0x21120, v202
	v_add_u32_e32 v208, 0x1d140, v202
	v_add_u32_e32 v209, 0x21140, v202
	v_add_u32_e32 v210, 0x1d160, v202
	v_add_u32_e32 v211, 0x21160, v202
	v_add_u32_e32 v236, 0xd100, v65
	v_add_u32_e32 v237, 0x1d100, v65
	v_add_u32_e32 v238, 0x21100, v65
	v_lshl_add_u64 v[162:163], v[106:107], 1, s[60:61]
	v_lshl_add_u64 v[164:165], v[114:115], 1, s[60:61]
	v_lshl_add_u64 v[166:167], v[122:123], 1, s[60:61]
	v_lshl_add_u64 v[168:169], v[130:131], 1, s[60:61]
	v_lshl_add_u64 v[170:171], v[138:139], 1, s[60:61]
	v_lshl_add_u64 v[172:173], v[154:155], 1, s[60:61]
	v_add_u32_e32 v239, v70, v67
	v_add_u32_e32 v240, v70, v69
	s_mov_b32 s100, 0
	s_branch .LBB0_227
.LBB0_226:
	s_or_b64 exec, exec, s[68:69]
	s_waitcnt lgkmcnt(0)
	s_barrier
	ds_read_b128 v[64:67], v196 offset:49152
	ds_read_b128 v[68:71], v196 offset:49280
	ds_read_b128 v[180:183], v196 offset:49216
	ds_read_b128 v[176:179], v196 offset:49344
	s_waitcnt lgkmcnt(2)
	v_mfma_f32_16x16x32_bf16 v[80:83], v[68:71], v[4:7], 0
	s_mov_b32 s3, 0xf800000
	v_readlane_b32 s6, v254, 37
	v_readlane_b32 s7, v254, 38
	v_mfma_f32_16x16x32_bf16 v[88:91], v[68:71], v[20:23], 0
	s_add_i32 s90, s90, s72
	v_add_u32_e32 v197, s2, v197
	v_add_u32_e32 v105, s2, v105
	s_waitcnt lgkmcnt(0)
	v_mfma_f32_16x16x32_bf16 v[92:95], v[176:179], v[12:15], v[80:83]
	v_add_u32_e32 v113, s2, v113
	v_add_u32_e32 v121, s2, v121
	v_add_u32_e32 v129, s2, v129
	v_mfma_f32_16x16x32_bf16 v[88:91], v[176:179], v[28:31], v[88:91]
	v_add_u32_e32 v137, s2, v137
	s_nop 2
	v_add_f32_e32 v92, v135, v92
	v_mul_f32_e32 v92, 0xbfb8aa3b, v92
	v_mfma_f32_16x16x32_bf16 v[72:75], v[64:67], v[0:3], 0
	v_exp_f32_e32 v92, v92
	v_add_f32_e32 v88, v143, v88
	v_mul_f32_e32 v88, 0xbfb8aa3b, v88
	v_mfma_f32_16x16x32_bf16 v[84:87], v[64:67], v[16:19], 0
	v_exp_f32_e32 v88, v88
	v_add_f32_e32 v92, 1.0, v92
	v_add_u32_e32 v153, s2, v153
	v_mfma_f32_16x16x32_bf16 v[246:249], v[68:71], v[36:39], 0
	v_add_f32_e32 v88, 1.0, v88
	s_cmpk_gt_i32 s90, 0x41f
	v_mfma_f32_16x16x32_bf16 v[76:79], v[180:183], v[8:11], v[72:75]
	v_mfma_f32_16x16x32_bf16 v[72:75], v[180:183], v[24:27], v[84:87]
	v_mfma_f32_16x16x32_bf16 v[84:87], v[176:179], v[44:47], v[246:249]
	s_nop 5
	v_add_f32_e32 v76, v103, v76
	v_mul_f32_e32 v76, 0xbfb8aa3b, v76
	v_exp_f32_e32 v76, v76
	v_mfma_f32_16x16x32_bf16 v[242:245], v[64:67], v[32:35], 0
	v_rcp_f32_e32 v246, v92
	v_add_f32_e32 v84, v147, v84
	v_mul_f32_e32 v84, 0xbfb8aa3b, v84
	v_mfma_f32_16x16x32_bf16 v[250:253], v[68:71], v[52:55], 0
	ds_read_u16 v92, v239 offset:1056
	v_exp_f32_e32 v84, v84
	v_add_f32_e32 v76, 1.0, v76
	v_mfma_f32_16x16x32_bf16 v[68:71], v[180:183], v[40:43], v[242:245]
	v_rcp_f32_e32 v76, v76
	v_add_f32_e32 v84, 1.0, v84
	v_add_f32_e32 v72, v111, v72
	v_mfma_f32_16x16x32_bf16 v[80:83], v[176:179], v[60:63], v[250:253]
	ds_read_u16 v176, v239 offset:1024
	v_rcp_f32_e32 v242, v88
	ds_read_u16 v88, v239 offset:1088
	s_waitcnt lgkmcnt(2)
	v_lshlrev_b32_e32 v244, 16, v92
	s_nop 0
	v_mul_f32_e32 v249, v189, v244
	s_waitcnt lgkmcnt(1)
	v_lshlrev_b32_e32 v248, 16, v176
	v_mul_f32_e32 v176, v188, v248
	s_waitcnt lgkmcnt(0)
	v_lshlrev_b32_e32 v92, 16, v88
	v_rcp_f32_e32 v88, v84
	ds_read_u16 v84, v239 offset:1120
	v_mul_f32_e32 v177, v249, v249
	v_fmac_f32_e32 v177, v176, v176
	s_nop 0
	v_mul_f32_e32 v247, v190, v92
	v_fmac_f32_e32 v177, v247, v247
	s_waitcnt lgkmcnt(0)
; #define LAS __attribute__((address_space(3)))
; __device__ __forceinline__ float bf2f(bf16_t h) { return __uint_as_float((unsigned)h << 16); }
; __device__ __forceinline__ bf16_t f2bf(float f) { return (bf16_t)(cvt_pk_bf16(f, 0.f) & 0xffffu); }
; __device__ __forceinline__ float sigmoidf(float x) { return rcpf(1.0f + __expf(-x)); }
; __device__ __forceinline__ void phase_m1(PP P, int l, LAS unsigned char* lds, const Ids I) {
;     ...
;             for (int j = 0; j < 4; ++j) { const int tk = quad * 4 + j; const LAS bf16_t* xp = XSB + tk * 1536 + hd * 64 + l15; float xk[4], ar[4], kk[4]; float ssq = 0.f;
; #pragma unroll
;                 for (int nt = 0; nt < 4; ++nt) { xk[nt] = bf2f(xp[512 + nt * 16]); ar[nt] = sigmoidf(a0v[nt] + aa[nt][j]); kk[nt] = xk[nt] * kkv[nt]; ssq += kk[nt] * kk[nt]; }
;                 const float rn = 1.0f / fmaxf(sqrtf(row16_allsum(ssq)), 1e-12f);
; #pragma unroll
;                 for (int nt = 0; nt < 4; ++nt) { LAS bf16_t* ob = OR + tk * 512 + hd * 64 + nt * 16 + l15; const float kn = kk[nt] * rn;
;                     ob[0] = xp[nt * 16];
;                     ob[8192] = f2bf(0.60653066f * sigmoidf(w0v[nt] + aw[nt][j]));
;                     ob[2 * 8192] = f2bf(xk[nt] * (1.0f + (ar[nt] - 1.0f) * kav[nt]));
;                     ob[3 * 8192] = xp[1024 + nt * 16];
;                     ob[4 * 8192] = f2bf(kn); ob[5 * 8192] = f2bf(kn * ar[nt]); } }
	v_lshlrev_b32_e32 v84, 16, v84
	s_nop 0
	v_mul_f32_e32 v243, v191, v84
	v_fmac_f32_e32 v177, v243, v243
	v_mfma_f32_16x16x32_bf16 v[64:67], v[64:67], v[48:51], 0
	v_mul_f32_e32 v76, 0x3f1b4598, v76
	v_add_f32_dpp v177, v177, v177 quad_perm:[1,0,3,2] row_mask:0xf bank_mask:0xf bound_ctrl:1
	v_cvt_pk_bf16_f32 v76, v76, v145
	v_mfma_f32_16x16x32_bf16 v[64:67], v[180:183], v[56:59], v[64:67]
	v_mul_f32_e32 v72, 0xbfb8aa3b, v72
	v_add_f32_dpp v177, v177, v177 quad_perm:[2,3,0,1] row_mask:0xf bank_mask:0xf bound_ctrl:1
	v_exp_f32_e32 v72, v72
	v_add_f32_e32 v68, v119, v68
	v_add_f32_dpp v177, v177, v177 row_half_mirror row_mask:0xf bank_mask:0xf bound_ctrl:1
	v_mul_f32_e32 v68, 0xbfb8aa3b, v68
	v_add_f32_e32 v72, 1.0, v72
	v_add_f32_dpp v177, v177, v177 row_mirror row_mask:0xf bank_mask:0xf bound_ctrl:1
	v_cmp_gt_f32_e32 vcc, s3, v177
	v_mul_f32_e32 v178, 0x4f800000, v177
	v_rcp_f32_e32 v72, v72
	v_cndmask_b32_e32 v177, v177, v178, vcc
	v_sqrt_f32_e32 v178, v177
	v_exp_f32_e32 v68, v68
	v_mul_f32_e32 v72, 0x3f1b4598, v72
	v_cvt_pk_bf16_f32 v72, v72, v145
	v_add_u32_e32 v179, -1, v178
	v_fma_f32 v180, -v179, v178, v177
	v_cmp_ge_f32_e64 s[50:51], 0, v180
	v_add_u32_e32 v180, 1, v178
	v_add_f32_e32 v68, 1.0, v68
	v_cndmask_b32_e64 v179, v178, v179, s[50:51]
	v_fma_f32 v178, -v180, v178, v177
	v_cmp_lt_f32_e64 s[50:51], 0, v178
	v_rcp_f32_e32 v68, v68
	v_add_f32_e32 v64, v127, v64
	v_cndmask_b32_e64 v178, v179, v180, s[50:51]
	v_mul_f32_e32 v179, 0x37800000, v178
	v_cndmask_b32_e32 v178, v178, v179, vcc
	v_cmp_class_f32_e32 vcc, v177, v175
	v_mul_f32_e32 v68, 0x3f1b4598, v68
	v_cvt_pk_bf16_f32 v68, v68, v145
	v_mul_f32_e32 v64, 0xbfb8aa3b, v64
	v_cndmask_b32_e32 v177, v178, v177, vcc
	v_max_f32_e32 v177, 0x2b8cbccc, v177
	v_div_scale_f32 v178, s[0:1], v177, v177, 1.0
	v_rcp_f32_e32 v179, v178
	v_add_f32_e32 v80, v187, v80
	v_exp_f32_e32 v64, v64
	v_mul_f32_e32 v80, 0xbfb8aa3b, v80
	v_fma_f32 v180, -v178, v179, 1.0
	v_fmac_f32_e32 v179, v180, v179
	v_div_scale_f32 v180, vcc, 1.0, v177, 1.0
	v_mul_f32_e32 v181, v180, v179
	v_fma_f32 v182, -v178, v181, v180
	v_fmac_f32_e32 v181, v182, v179
	v_fma_f32 v178, -v178, v181, v180
	v_div_fmas_f32 v178, v178, v179, v181
	v_div_fixup_f32 v245, v178, v177, 1.0
	ds_read_u16 v177, v239
	ds_write_b16 v198, v76 offset:16384
	v_add_f32_e32 v76, -1.0, v246
	s_nop 0
	v_fma_f32 v76, v192, v76, 1.0
	v_mul_f32_e32 v76, v76, v248
	s_waitcnt lgkmcnt(1)
	ds_write_b16 v159, v177 offset:53504
	v_cvt_pk_bf16_f32 v76, v76, v145
	ds_write_b16 v198, v76 offset:32768
	ds_read_u16 v76, v239 offset:2048
	v_mul_f32_e32 v176, v176, v245
	v_add_u32_e32 v177, 0x1d100, v159
	v_exp_f32_e32 v80, v80
	v_add_f32_e32 v64, 1.0, v64
	s_waitcnt lgkmcnt(0)
	ds_write_b16 v198, v76 offset:49152
	v_cvt_pk_bf16_f32 v76, v176, v145
	ds_write_b16 v177, v76
	v_mul_f32_e32 v76, v246, v176
	v_add_u32_e32 v176, 0x21100, v159
	v_cvt_pk_bf16_f32 v76, v76, v145
	ds_write_b16 v176, v76
	ds_read_u16 v176, v239 offset:32
	ds_write_b16 v198, v72 offset:16416
	v_add_f32_e32 v72, -1.0, v242
	s_nop 0
	v_fma_f32 v72, v193, v72, 1.0
	v_mul_f32_e32 v72, v72, v244
	s_waitcnt lgkmcnt(1)
	ds_write_b16 v159, v176 offset:53536
	v_cvt_pk_bf16_f32 v72, v72, v145
	ds_write_b16 v198, v72 offset:32800
	ds_read_u16 v72, v239 offset:2080
	v_mul_f32_e32 v76, v249, v245
	v_add_u32_e32 v176, 0x1d120, v159
	v_rcp_f32_e32 v64, v64
	v_add_f32_e32 v80, 1.0, v80
	s_waitcnt lgkmcnt(0)
	ds_write_b16 v198, v72 offset:49184
	v_cvt_pk_bf16_f32 v72, v76, v145
	ds_write_b16 v176, v72
	v_mul_f32_e32 v72, v242, v76
	v_add_u32_e32 v76, 0x21120, v159
	v_cvt_pk_bf16_f32 v72, v72, v145
	ds_write_b16 v76, v72
	ds_read_u16 v76, v239 offset:64
	ds_write_b16 v198, v68 offset:16448
	v_add_f32_e32 v68, -1.0, v88
	s_nop 0
	v_fma_f32 v68, v194, v68, 1.0
	v_mul_f32_e32 v68, v68, v92
	s_waitcnt lgkmcnt(1)
	ds_write_b16 v159, v76 offset:53568
	v_cvt_pk_bf16_f32 v68, v68, v145
	ds_write_b16 v198, v68 offset:32832
	ds_read_u16 v68, v239 offset:2112
	v_mul_f32_e32 v72, v247, v245
	v_add_u32_e32 v76, 0x1d140, v159
	v_rcp_f32_e32 v80, v80
	v_mul_f32_e32 v64, 0x3f1b4598, v64
	s_waitcnt lgkmcnt(0)
	ds_write_b16 v198, v68 offset:49216
	v_cvt_pk_bf16_f32 v68, v72, v145
	ds_write_b16 v76, v68
	v_mul_f32_e32 v68, v88, v72
	v_cvt_pk_bf16_f32 v68, v68, v145
	ds_write_b16 v199, v68
	ds_read_u16 v72, v239 offset:96
	v_cvt_pk_bf16_f32 v64, v64, v145
	ds_write_b16 v198, v64 offset:16480
	v_add_f32_e32 v64, -1.0, v80
	s_nop 0
	v_fma_f32 v64, v195, v64, 1.0
	v_mul_f32_e32 v64, v64, v84
	s_waitcnt lgkmcnt(1)
	ds_write_b16 v159, v72 offset:53600
	v_cvt_pk_bf16_f32 v64, v64, v145
	ds_write_b16 v198, v64 offset:32864
	ds_read_u16 v64, v239 offset:2144
	v_mul_f32_e32 v68, v243, v245
	v_add_f32_e32 v77, v103, v77
	v_mul_f32_e32 v77, 0xbfb8aa3b, v77
	v_exp_f32_e32 v77, v77
	s_waitcnt lgkmcnt(0)
	ds_write_b16 v198, v64 offset:49248
	v_cvt_pk_bf16_f32 v64, v68, v145
	ds_write_b16 v200, v64
	v_mul_f32_e32 v64, v80, v68
	v_cvt_pk_bf16_f32 v64, v64, v145
	ds_write_b16 v201, v64
	ds_read_u16 v64, v240 offset:1024
	v_add_f32_e32 v77, 1.0, v77
	v_rcp_f32_e32 v77, v77
	v_add_f32_e32 v73, v111, v73
	v_mul_f32_e32 v73, 0xbfb8aa3b, v73
	s_waitcnt lgkmcnt(0)
	v_lshlrev_b32_e32 v92, 16, v64
	v_add_f32_e32 v64, v135, v93
	v_mul_f32_e32 v64, 0xbfb8aa3b, v64
	v_exp_f32_e32 v64, v64
	v_mul_f32_e32 v93, v188, v92
	v_mul_f32_e32 v77, 0x3f1b4598, v77
	v_cvt_pk_bf16_f32 v77, v77, v145
	v_add_f32_e32 v64, 1.0, v64
	v_rcp_f32_e32 v88, v64
	ds_read_u16 v64, v240 offset:1056
	v_exp_f32_e32 v73, v73
	v_add_f32_e32 v69, v119, v69
	v_mul_f32_e32 v69, 0xbfb8aa3b, v69
	v_exp_f32_e32 v69, v69
	s_waitcnt lgkmcnt(0)
; #define LAS __attribute__((address_space(3)))
; __device__ __forceinline__ float bf2f(bf16_t h) { return __uint_as_float((unsigned)h << 16); }
; __device__ __forceinline__ bf16_t f2bf(float f) { return (bf16_t)(cvt_pk_bf16(f, 0.f) & 0xffffu); }
; __device__ __forceinline__ float sigmoidf(float x) { return rcpf(1.0f + __expf(-x)); }
; __device__ __forceinline__ void phase_m1(PP P, int l, LAS unsigned char* lds, const Ids I) {
;     ...
;             for (int j = 0; j < 4; ++j) { const int tk = quad * 4 + j; const LAS bf16_t* xp = XSB + tk * 1536 + hd * 64 + l15; float xk[4], ar[4], kk[4]; float ssq = 0.f;
; #pragma unroll
;                 for (int nt = 0; nt < 4; ++nt) { xk[nt] = bf2f(xp[512 + nt * 16]); ar[nt] = sigmoidf(a0v[nt] + aa[nt][j]); kk[nt] = xk[nt] * kkv[nt]; ssq += kk[nt] * kk[nt]; }
;                 const float rn = 1.0f / fmaxf(sqrtf(row16_allsum(ssq)), 1e-12f);
; #pragma unroll
;                 for (int nt = 0; nt < 4; ++nt) { LAS bf16_t* ob = OR + tk * 512 + hd * 64 + nt * 16 + l15; const float kn = kk[nt] * rn;
;                     ob[0] = xp[nt * 16];
;                     ob[8192] = f2bf(0.60653066f * sigmoidf(w0v[nt] + aw[nt][j]));
;                     ob[2 * 8192] = f2bf(xk[nt] * (1.0f + (ar[nt] - 1.0f) * kav[nt]));
;                     ob[3 * 8192] = xp[1024 + nt * 16];
;                     ob[4 * 8192] = f2bf(kn); ob[5 * 8192] = f2bf(kn * ar[nt]); } }
	v_lshlrev_b32_e32 v84, 16, v64
	v_add_f32_e32 v64, v143, v89
	v_mul_f32_e32 v64, 0xbfb8aa3b, v64
	v_exp_f32_e32 v64, v64
	v_mul_f32_e32 v176, v189, v84
	v_mul_f32_e32 v177, v176, v176
	v_fmac_f32_e32 v177, v93, v93
	v_add_f32_e32 v64, 1.0, v64
	v_rcp_f32_e32 v80, v64
	ds_read_u16 v64, v240 offset:1088
	v_add_f32_e32 v73, 1.0, v73
	v_rcp_f32_e32 v73, v73
	v_add_f32_e32 v69, 1.0, v69
	v_rcp_f32_e32 v69, v69
	s_waitcnt lgkmcnt(0)
	v_lshlrev_b32_e32 v76, 16, v64
	v_add_f32_e32 v64, v147, v85
	v_mul_f32_e32 v64, 0xbfb8aa3b, v64
	v_exp_f32_e32 v64, v64
	v_mul_f32_e32 v89, v190, v76
	v_fmac_f32_e32 v177, v89, v89
	v_mul_f32_e32 v73, 0x3f1b4598, v73
	v_add_f32_e32 v64, 1.0, v64
	v_rcp_f32_e32 v72, v64
	ds_read_u16 v64, v240 offset:1120
	v_cvt_pk_bf16_f32 v73, v73, v145
	v_mul_f32_e32 v69, 0x3f1b4598, v69
	v_cvt_pk_bf16_f32 v69, v69, v145
	v_add_f32_e32 v65, v127, v65
	s_waitcnt lgkmcnt(0)
	v_lshlrev_b32_e32 v68, 16, v64
	v_add_f32_e32 v64, v187, v81
	v_mul_f32_e32 v81, v191, v68
	v_fmac_f32_e32 v177, v81, v81
	v_mul_f32_e32 v65, 0xbfb8aa3b, v65
	v_exp_f32_e32 v65, v65
	v_add_f32_dpp v85, v177, v177 quad_perm:[1,0,3,2] row_mask:0xf bank_mask:0xf bound_ctrl:1
	v_mul_f32_e32 v64, 0xbfb8aa3b, v64
	v_exp_f32_e32 v64, v64
	v_add_f32_dpp v85, v85, v85 quad_perm:[2,3,0,1] row_mask:0xf bank_mask:0xf bound_ctrl:1
	v_add_f32_e32 v65, 1.0, v65
	v_rcp_f32_e32 v65, v65
	v_add_f32_dpp v85, v85, v85 row_half_mirror row_mask:0xf bank_mask:0xf bound_ctrl:1
	v_add_f32_e32 v64, 1.0, v64
	v_rcp_f32_e32 v64, v64
	v_add_f32_dpp v85, v85, v85 row_mirror row_mask:0xf bank_mask:0xf bound_ctrl:1
	v_cmp_gt_f32_e32 vcc, s3, v85
	v_mul_f32_e32 v177, 0x4f800000, v85
	v_mul_f32_e32 v65, 0x3f1b4598, v65
	v_cndmask_b32_e32 v85, v85, v177, vcc
	v_sqrt_f32_e32 v177, v85
	v_cvt_pk_bf16_f32 v65, v65, v145
	v_add_f32_e32 v78, v103, v78
	v_mul_f32_e32 v78, 0xbfb8aa3b, v78
	v_add_u32_e32 v178, -1, v177
	v_fma_f32 v179, -v178, v177, v85
	v_cmp_ge_f32_e64 s[50:51], 0, v179
	v_add_u32_e32 v179, 1, v177
	v_exp_f32_e32 v78, v78
	v_cndmask_b32_e64 v178, v177, v178, s[50:51]
	v_fma_f32 v177, -v179, v177, v85
	v_cmp_lt_f32_e64 s[50:51], 0, v177
	v_add_f32_e32 v78, 1.0, v78
	v_rcp_f32_e32 v78, v78
	v_cndmask_b32_e64 v177, v178, v179, s[50:51]
	v_mul_f32_e32 v178, 0x37800000, v177
	v_cndmask_b32_e32 v177, v177, v178, vcc
	v_cmp_class_f32_e32 vcc, v85, v175
	v_mul_f32_e32 v78, 0x3f1b4598, v78
	v_cvt_pk_bf16_f32 v78, v78, v145
	v_add_f32_e32 v74, v111, v74
	v_cndmask_b32_e32 v85, v177, v85, vcc
	v_max_f32_e32 v85, 0x2b8cbccc, v85
	v_div_scale_f32 v177, s[0:1], v85, v85, 1.0
	v_rcp_f32_e32 v178, v177
	v_mul_f32_e32 v74, 0xbfb8aa3b, v74
	v_exp_f32_e32 v74, v74
	v_add_f32_e32 v70, v119, v70
	v_fma_f32 v179, -v177, v178, 1.0
	v_fmac_f32_e32 v178, v179, v178
	v_div_scale_f32 v179, vcc, 1.0, v85, 1.0
	v_mul_f32_e32 v180, v179, v178
	v_fma_f32 v181, -v177, v180, v179
	v_fmac_f32_e32 v180, v181, v178
	v_fma_f32 v177, -v177, v180, v179
	v_div_fmas_f32 v177, v177, v178, v180
	v_div_fixup_f32 v85, v177, v85, 1.0
	ds_read_u16 v177, v240
	ds_write_b16 v203, v77 offset:16384
	v_add_f32_e32 v77, -1.0, v88
	v_fma_f32 v77, v192, v77, 1.0
	v_mul_f32_e32 v77, v77, v92
	s_waitcnt lgkmcnt(1)
	ds_write_b16 v202, v177 offset:53504
	v_cvt_pk_bf16_f32 v77, v77, v145
	ds_write_b16 v203, v77 offset:32768
	ds_read_u16 v77, v240 offset:2048
	v_mul_f32_e32 v93, v93, v85
	v_add_f32_e32 v74, 1.0, v74
	v_rcp_f32_e32 v74, v74
	v_mul_f32_e32 v70, 0xbfb8aa3b, v70
	s_waitcnt lgkmcnt(0)
	ds_write_b16 v203, v77 offset:49152
	v_cvt_pk_bf16_f32 v77, v93, v145
	ds_write_b16 v204, v77
	v_mul_f32_e32 v77, v88, v93
	v_cvt_pk_bf16_f32 v77, v77, v145
	ds_write_b16 v205, v77
	ds_read_u16 v88, v240 offset:32
	ds_write_b16 v203, v73 offset:16416
	v_add_f32_e32 v73, -1.0, v80
	v_fma_f32 v73, v193, v73, 1.0
	v_mul_f32_e32 v73, v73, v84
	s_waitcnt lgkmcnt(1)
	ds_write_b16 v202, v88 offset:53536
	v_cvt_pk_bf16_f32 v73, v73, v145
	ds_write_b16 v203, v73 offset:32800
	ds_read_u16 v73, v240 offset:2080
	v_mul_f32_e32 v77, v176, v85
	v_mul_f32_e32 v74, 0x3f1b4598, v74
	v_cvt_pk_bf16_f32 v74, v74, v145
	v_exp_f32_e32 v70, v70
	s_waitcnt lgkmcnt(0)
	ds_write_b16 v203, v73 offset:49184
	v_cvt_pk_bf16_f32 v73, v77, v145
	ds_write_b16 v206, v73
	v_mul_f32_e32 v73, v80, v77
	v_cvt_pk_bf16_f32 v73, v73, v145
	ds_write_b16 v207, v73
	ds_read_u16 v77, v240 offset:64
	ds_write_b16 v203, v69 offset:16448
	v_add_f32_e32 v69, -1.0, v72
	v_fma_f32 v69, v194, v69, 1.0
	v_mul_f32_e32 v69, v69, v76
	s_waitcnt lgkmcnt(1)
	ds_write_b16 v202, v77 offset:53568
	v_cvt_pk_bf16_f32 v69, v69, v145
	ds_write_b16 v203, v69 offset:32832
	ds_read_u16 v69, v240 offset:2112
	v_mul_f32_e32 v73, v89, v85
	v_add_f32_e32 v70, 1.0, v70
	v_rcp_f32_e32 v70, v70
	v_add_f32_e32 v66, v127, v66
	s_waitcnt lgkmcnt(0)
	ds_write_b16 v203, v69 offset:49216
	v_cvt_pk_bf16_f32 v69, v73, v145
	ds_write_b16 v208, v69
	v_mul_f32_e32 v69, v72, v73
	v_cvt_pk_bf16_f32 v69, v69, v145
	ds_write_b16 v209, v69
	ds_read_u16 v72, v240 offset:96
	ds_write_b16 v203, v65 offset:16480
	v_add_f32_e32 v65, -1.0, v64
	v_fma_f32 v65, v195, v65, 1.0
	v_mul_f32_e32 v65, v65, v68
	s_waitcnt lgkmcnt(1)
	ds_write_b16 v202, v72 offset:53600
	v_cvt_pk_bf16_f32 v65, v65, v145
	ds_write_b16 v203, v65 offset:32864
	ds_read_u16 v65, v240 offset:2144
	v_mul_f32_e32 v69, v81, v85
	v_mul_f32_e32 v64, v64, v69
	v_cvt_pk_bf16_f32 v64, v64, v145
	ds_write_b16 v211, v64
	s_waitcnt lgkmcnt(1)
	ds_write_b16 v203, v65 offset:49248
	v_cvt_pk_bf16_f32 v65, v69, v145
	ds_write_b16 v210, v65
	ds_read_u16 v64, v240 offset:4096
	v_mul_f32_e32 v70, 0x3f1b4598, v70
	v_cvt_pk_bf16_f32 v70, v70, v145
	v_mul_f32_e32 v66, 0xbfb8aa3b, v66
	v_exp_f32_e32 v66, v66
	s_waitcnt lgkmcnt(0)
; #define LAS __attribute__((address_space(3)))
; __device__ __forceinline__ float bf2f(bf16_t h) { return __uint_as_float((unsigned)h << 16); }
; __device__ __forceinline__ bf16_t f2bf(float f) { return (bf16_t)(cvt_pk_bf16(f, 0.f) & 0xffffu); }
; __device__ __forceinline__ float sigmoidf(float x) { return rcpf(1.0f + __expf(-x)); }
; __device__ __forceinline__ void phase_m1(PP P, int l, LAS unsigned char* lds, const Ids I) {
;     ...
;             for (int j = 0; j < 4; ++j) { const int tk = quad * 4 + j; const LAS bf16_t* xp = XSB + tk * 1536 + hd * 64 + l15; float xk[4], ar[4], kk[4]; float ssq = 0.f;
; #pragma unroll
;                 for (int nt = 0; nt < 4; ++nt) { xk[nt] = bf2f(xp[512 + nt * 16]); ar[nt] = sigmoidf(a0v[nt] + aa[nt][j]); kk[nt] = xk[nt] * kkv[nt]; ssq += kk[nt] * kk[nt]; }
;                 const float rn = 1.0f / fmaxf(sqrtf(row16_allsum(ssq)), 1e-12f);
; #pragma unroll
;                 for (int nt = 0; nt < 4; ++nt) { LAS bf16_t* ob = OR + tk * 512 + hd * 64 + nt * 16 + l15; const float kn = kk[nt] * rn;
;                     ob[0] = xp[nt * 16];
;                     ob[8192] = f2bf(0.60653066f * sigmoidf(w0v[nt] + aw[nt][j]));
;                     ob[2 * 8192] = f2bf(xk[nt] * (1.0f + (ar[nt] - 1.0f) * kav[nt]));
;                     ob[3 * 8192] = xp[1024 + nt * 16];
;                     ob[4 * 8192] = f2bf(kn); ob[5 * 8192] = f2bf(kn * ar[nt]); } }
	v_lshlrev_b32_e32 v84, 16, v64
	v_add_f32_e32 v64, v135, v94
	v_mul_f32_e32 v64, 0xbfb8aa3b, v64
	v_exp_f32_e32 v64, v64
	v_mul_f32_e32 v85, v188, v84
	v_add_f32_e32 v66, 1.0, v66
	v_rcp_f32_e32 v66, v66
	v_add_f32_e32 v64, 1.0, v64
	v_rcp_f32_e32 v80, v64
	ds_read_u16 v64, v240 offset:4128
	v_mul_f32_e32 v66, 0x3f1b4598, v66
	v_cvt_pk_bf16_f32 v66, v66, v145
	v_add_f32_e32 v79, v103, v79
	v_mul_f32_e32 v79, 0xbfb8aa3b, v79
	s_waitcnt lgkmcnt(0)
	v_lshlrev_b32_e32 v76, 16, v64
	v_add_f32_e32 v64, v143, v90
	v_mul_f32_e32 v64, 0xbfb8aa3b, v64
	v_exp_f32_e32 v64, v64
	v_mul_f32_e32 v88, v189, v76
	v_mul_f32_e32 v77, v88, v88
	v_fmac_f32_e32 v77, v85, v85
	v_add_f32_e32 v64, 1.0, v64
	v_rcp_f32_e32 v72, v64
	ds_read_u16 v64, v240 offset:4160
	v_exp_f32_e32 v79, v79
	v_add_f32_e32 v75, v111, v75
	v_mul_f32_e32 v75, 0xbfb8aa3b, v75
	v_exp_f32_e32 v75, v75
	s_waitcnt lgkmcnt(0)
	v_lshlrev_b32_e32 v69, 16, v64
	v_add_f32_e32 v64, v147, v86
	v_mul_f32_e32 v64, 0xbfb8aa3b, v64
	v_exp_f32_e32 v64, v64
	v_mul_f32_e32 v81, v190, v69
	v_fmac_f32_e32 v77, v81, v81
	v_add_f32_e32 v79, 1.0, v79
	v_add_f32_e32 v64, 1.0, v64
	v_rcp_f32_e32 v68, v64
	ds_read_u16 v64, v240 offset:4192
	v_rcp_f32_e32 v79, v79
	v_add_f32_e32 v75, 1.0, v75
	v_rcp_f32_e32 v75, v75
	v_add_f32_e32 v71, v119, v71
	s_waitcnt lgkmcnt(0)
	v_lshlrev_b32_e32 v65, 16, v64
	v_mul_f32_e32 v73, v191, v65
	v_fmac_f32_e32 v77, v73, v73
	v_add_f32_e32 v64, v187, v82
	v_mul_f32_e32 v64, 0xbfb8aa3b, v64
	v_add_f32_dpp v77, v77, v77 quad_perm:[1,0,3,2] row_mask:0xf bank_mask:0xf bound_ctrl:1
	v_exp_f32_e32 v64, v64
	v_mul_f32_e32 v79, 0x3f1b4598, v79
	v_add_f32_dpp v77, v77, v77 quad_perm:[2,3,0,1] row_mask:0xf bank_mask:0xf bound_ctrl:1
	v_cvt_pk_bf16_f32 v79, v79, v145
	v_add_f32_e32 v64, 1.0, v64
	v_rcp_f32_e32 v64, v64
	v_add_f32_dpp v77, v77, v77 row_half_mirror row_mask:0xf bank_mask:0xf bound_ctrl:1
	v_mul_f32_e32 v75, 0x3f1b4598, v75
	v_cvt_pk_bf16_f32 v75, v75, v145
	v_mul_f32_e32 v71, 0xbfb8aa3b, v71
	v_add_f32_dpp v77, v77, v77 row_mirror row_mask:0xf bank_mask:0xf bound_ctrl:1
	v_cmp_gt_f32_e32 vcc, s3, v77
	v_mul_f32_e32 v82, 0x4f800000, v77
	v_exp_f32_e32 v71, v71
	v_cndmask_b32_e32 v77, v77, v82, vcc
	v_sqrt_f32_e32 v82, v77
	v_add_f32_e32 v67, v127, v67
	v_add_f32_e32 v71, 1.0, v71
	v_rcp_f32_e32 v71, v71
	v_add_u32_e32 v86, -1, v82
	v_fma_f32 v89, -v86, v82, v77
	v_cmp_ge_f32_e64 s[50:51], 0, v89
	v_add_u32_e32 v89, 1, v82
	v_mul_f32_e32 v71, 0x3f1b4598, v71
	v_cndmask_b32_e64 v86, v82, v86, s[50:51]
	v_fma_f32 v82, -v89, v82, v77
	v_cmp_lt_f32_e64 s[50:51], 0, v82
	v_cvt_pk_bf16_f32 v71, v71, v145
	v_mul_f32_e32 v67, 0xbfb8aa3b, v67
	v_exp_f32_e32 v67, v67
	v_cndmask_b32_e64 v82, v86, v89, s[50:51]
	v_mul_f32_e32 v86, 0x37800000, v82
	v_cndmask_b32_e32 v82, v82, v86, vcc
	v_cmp_class_f32_e32 vcc, v77, v175
	v_add_f32_e32 v67, 1.0, v67
	v_rcp_f32_e32 v67, v67
	v_cndmask_b32_e32 v77, v82, v77, vcc
	v_max_f32_e32 v77, 0x2b8cbccc, v77
	v_div_scale_f32 v82, s[0:1], v77, v77, 1.0
	v_rcp_f32_e32 v86, v82
	v_mul_f32_e32 v67, 0x3f1b4598, v67
	v_cvt_pk_bf16_f32 v67, v67, v145
	v_fma_f32 v89, -v82, v86, 1.0
	v_fmac_f32_e32 v86, v89, v86
	v_div_scale_f32 v89, vcc, 1.0, v77, 1.0
	v_mul_f32_e32 v90, v89, v86
	v_fma_f32 v92, -v82, v90, v89
	v_fmac_f32_e32 v90, v92, v86
	v_fma_f32 v82, -v82, v90, v89
	v_div_fmas_f32 v82, v82, v86, v90
	v_div_fixup_f32 v77, v82, v77, 1.0
	v_mul_f32_e32 v82, v85, v77
	ds_read_u16 v85, v240 offset:3072
	ds_write_b16 v213, v78 offset:16384
	v_add_f32_e32 v78, -1.0, v80
	v_fma_f32 v78, v192, v78, 1.0
	v_mul_f32_e32 v78, v78, v84
	s_waitcnt lgkmcnt(1)
	ds_write_b16 v212, v85 offset:53504
	v_cvt_pk_bf16_f32 v78, v78, v145
	ds_write_b16 v213, v78 offset:32768
	ds_read_u16 v78, v240 offset:5120
	s_waitcnt lgkmcnt(0)
	ds_write_b16 v213, v78 offset:49152
	v_cvt_pk_bf16_f32 v78, v82, v145
	ds_write_b16 v214, v78
	v_mul_f32_e32 v78, v80, v82
	v_cvt_pk_bf16_f32 v78, v78, v145
	ds_write_b16 v215, v78
	ds_read_u16 v80, v240 offset:3104
	ds_write_b16 v213, v74 offset:16416
	v_add_f32_e32 v74, -1.0, v72
	v_fma_f32 v74, v193, v74, 1.0
	v_mul_f32_e32 v74, v74, v76
	s_waitcnt lgkmcnt(1)
	ds_write_b16 v212, v80 offset:53536
	v_cvt_pk_bf16_f32 v74, v74, v145
	ds_write_b16 v213, v74 offset:32800
	ds_read_u16 v74, v240 offset:5152
	v_mul_f32_e32 v78, v88, v77
	v_mul_f32_e32 v72, v72, v78
	v_cvt_pk_bf16_f32 v72, v72, v145
	ds_write_b16 v217, v72
	s_waitcnt lgkmcnt(1)
	ds_write_b16 v213, v74 offset:49184
	v_cvt_pk_bf16_f32 v74, v78, v145
	ds_write_b16 v216, v74
	ds_read_u16 v74, v240 offset:3136
	ds_write_b16 v213, v70 offset:16448
	v_add_f32_e32 v70, -1.0, v68
	v_fma_f32 v70, v194, v70, 1.0
	v_mul_f32_e32 v69, v70, v69
	s_waitcnt lgkmcnt(1)
	ds_write_b16 v212, v74 offset:53568
	v_cvt_pk_bf16_f32 v69, v69, v145
	ds_write_b16 v213, v69 offset:32832
	ds_read_u16 v69, v240 offset:5184
	v_mul_f32_e32 v72, v81, v77
	v_mul_f32_e32 v68, v68, v72
	v_cvt_pk_bf16_f32 v68, v68, v145
	ds_write_b16 v219, v68
	s_waitcnt lgkmcnt(1)
	ds_write_b16 v213, v69 offset:49216
	v_cvt_pk_bf16_f32 v69, v72, v145
	ds_write_b16 v218, v69
	ds_read_u16 v69, v240 offset:3168
	ds_write_b16 v213, v66 offset:16480
	v_add_f32_e32 v66, -1.0, v64
	v_fma_f32 v66, v195, v66, 1.0
	v_mul_f32_e32 v65, v66, v65
	s_waitcnt lgkmcnt(1)
	ds_write_b16 v212, v69 offset:53600
	v_cvt_pk_bf16_f32 v65, v65, v145
	ds_write_b16 v213, v65 offset:32864
	ds_read_u16 v65, v240 offset:5216
	v_mul_f32_e32 v68, v73, v77
	v_mul_f32_e32 v64, v64, v68
	v_cvt_pk_bf16_f32 v64, v64, v145
	ds_write_b16 v221, v64
	s_waitcnt lgkmcnt(1)
	ds_write_b16 v213, v65 offset:49248
	v_cvt_pk_bf16_f32 v65, v68, v145
	ds_write_b16 v220, v65
	ds_read_u16 v64, v240 offset:7168
	s_waitcnt lgkmcnt(0)
; #define LAS __attribute__((address_space(3)))
; __device__ __forceinline__ float bf2f(bf16_t h) { return __uint_as_float((unsigned)h << 16); }
; __device__ __forceinline__ bf16_t f2bf(float f) { return (bf16_t)(cvt_pk_bf16(f, 0.f) & 0xffffu); }
; __device__ __forceinline__ float sigmoidf(float x) { return rcpf(1.0f + __expf(-x)); }
; __device__ __forceinline__ void phase_m1(PP P, int l, LAS unsigned char* lds, const Ids I) {
;     ...
;             for (int j = 0; j < 4; ++j) { const int tk = quad * 4 + j; const LAS bf16_t* xp = XSB + tk * 1536 + hd * 64 + l15; float xk[4], ar[4], kk[4]; float ssq = 0.f;
; #pragma unroll
;                 for (int nt = 0; nt < 4; ++nt) { xk[nt] = bf2f(xp[512 + nt * 16]); ar[nt] = sigmoidf(a0v[nt] + aa[nt][j]); kk[nt] = xk[nt] * kkv[nt]; ssq += kk[nt] * kk[nt]; }
;                 const float rn = 1.0f / fmaxf(sqrtf(row16_allsum(ssq)), 1e-12f);
; #pragma unroll
;                 for (int nt = 0; nt < 4; ++nt) { LAS bf16_t* ob = OR + tk * 512 + hd * 64 + nt * 16 + l15; const float kn = kk[nt] * rn;
;                     ob[0] = xp[nt * 16];
;                     ob[8192] = f2bf(0.60653066f * sigmoidf(w0v[nt] + aw[nt][j]));
;                     ob[2 * 8192] = f2bf(xk[nt] * (1.0f + (ar[nt] - 1.0f) * kav[nt]));
;                     ob[3 * 8192] = xp[1024 + nt * 16];
;                     ob[4 * 8192] = f2bf(kn); ob[5 * 8192] = f2bf(kn * ar[nt]); } }
;             __syncthreads();
	v_lshlrev_b32_e32 v77, 16, v64
	v_add_f32_e32 v64, v135, v95
	v_mul_f32_e32 v64, 0xbfb8aa3b, v64
	v_exp_f32_e32 v64, v64
	v_mul_f32_e32 v78, v188, v77
	v_add_f32_e32 v64, 1.0, v64
	v_rcp_f32_e32 v74, v64
	ds_read_u16 v64, v240 offset:7200
	s_waitcnt lgkmcnt(0)
	v_lshlrev_b32_e32 v72, 16, v64
	v_add_f32_e32 v64, v143, v91
	v_mul_f32_e32 v64, 0xbfb8aa3b, v64
	v_exp_f32_e32 v64, v64
	v_mul_f32_e32 v80, v189, v72
	v_mul_f32_e32 v73, v80, v80
	v_fmac_f32_e32 v73, v78, v78
	v_add_f32_e32 v64, 1.0, v64
	v_rcp_f32_e32 v69, v64
	ds_read_u16 v64, v240 offset:7232
	s_waitcnt lgkmcnt(0)
	v_lshlrev_b32_e32 v68, 16, v64
	v_add_f32_e32 v64, v147, v87
	v_mul_f32_e32 v64, 0xbfb8aa3b, v64
	v_exp_f32_e32 v64, v64
	v_mul_f32_e32 v76, v190, v68
	v_fmac_f32_e32 v73, v76, v76
	v_add_f32_e32 v64, 1.0, v64
	v_rcp_f32_e32 v66, v64
	ds_read_u16 v64, v240 offset:7264
	s_waitcnt lgkmcnt(0)
	v_lshlrev_b32_e32 v65, 16, v64
	v_mul_f32_e32 v70, v191, v65
	v_fmac_f32_e32 v73, v70, v70
	v_add_f32_e32 v64, v187, v83
	v_mul_f32_e32 v64, 0xbfb8aa3b, v64
	v_add_f32_dpp v73, v73, v73 quad_perm:[1,0,3,2] row_mask:0xf bank_mask:0xf bound_ctrl:1
	v_exp_f32_e32 v64, v64
	s_nop 0
	v_add_f32_dpp v73, v73, v73 quad_perm:[2,3,0,1] row_mask:0xf bank_mask:0xf bound_ctrl:1
	v_add_f32_e32 v64, 1.0, v64
	s_nop 0
	v_add_f32_dpp v73, v73, v73 row_half_mirror row_mask:0xf bank_mask:0xf bound_ctrl:1
	v_rcp_f32_e32 v64, v64
	s_nop 0
	v_add_f32_dpp v73, v73, v73 row_mirror row_mask:0xf bank_mask:0xf bound_ctrl:1
	v_cmp_gt_f32_e32 vcc, s3, v73
	v_mul_f32_e32 v81, 0x4f800000, v73
	s_nop 0
	v_cndmask_b32_e32 v73, v73, v81, vcc
	v_sqrt_f32_e32 v81, v73
	s_nop 0
	v_add_u32_e32 v82, -1, v81
	v_fma_f32 v83, -v82, v81, v73
	v_cmp_ge_f32_e64 s[50:51], 0, v83
	v_add_u32_e32 v83, 1, v81
	s_nop 0
	v_cndmask_b32_e64 v82, v81, v82, s[50:51]
	v_fma_f32 v81, -v83, v81, v73
	v_cmp_lt_f32_e64 s[50:51], 0, v81
	s_nop 1
	v_cndmask_b32_e64 v81, v82, v83, s[50:51]
	v_mul_f32_e32 v82, 0x37800000, v81
	v_cndmask_b32_e32 v81, v81, v82, vcc
	v_cmp_class_f32_e32 vcc, v73, v175
	v_readlane_b32 s50, v254, 39
	v_readlane_b32 s51, v254, 40
	v_cndmask_b32_e32 v73, v81, v73, vcc
	v_max_f32_e32 v73, 0x2b8cbccc, v73
	v_div_scale_f32 v81, s[0:1], v73, v73, 1.0
	v_rcp_f32_e32 v82, v81
	v_readlane_b32 s0, v254, 35
	v_readlane_b32 s1, v254, 36
	v_fma_f32 v83, -v81, v82, 1.0
	v_fmac_f32_e32 v82, v83, v82
	v_div_scale_f32 v83, vcc, 1.0, v73, 1.0
	v_mul_f32_e32 v84, v83, v82
	v_fma_f32 v85, -v81, v84, v83
	v_fmac_f32_e32 v84, v85, v82
	v_fma_f32 v81, -v81, v84, v83
	v_div_fmas_f32 v81, v81, v82, v84
	v_div_fixup_f32 v73, v81, v73, 1.0
	ds_read_u16 v81, v240 offset:6144
	ds_write_b16 v223, v79 offset:16384
	v_add_f32_e32 v79, -1.0, v74
	v_fma_f32 v79, v192, v79, 1.0
	v_mul_f32_e32 v77, v79, v77
	s_waitcnt lgkmcnt(1)
	ds_write_b16 v222, v81 offset:53504
	v_cvt_pk_bf16_f32 v77, v77, v145
	ds_write_b16 v223, v77 offset:32768
	ds_read_u16 v77, v240 offset:8192
	v_mul_f32_e32 v78, v78, v73
	v_mul_f32_e32 v74, v74, v78
	v_cvt_pk_bf16_f32 v74, v74, v145
	ds_write_b16 v225, v74
	s_waitcnt lgkmcnt(1)
	ds_write_b16 v223, v77 offset:49152
	v_cvt_pk_bf16_f32 v77, v78, v145
	ds_write_b16 v224, v77
	ds_read_u16 v77, v240 offset:6176
	ds_write_b16 v223, v75 offset:16416
	v_add_f32_e32 v75, -1.0, v69
	v_fma_f32 v75, v193, v75, 1.0
	v_mul_f32_e32 v72, v75, v72
	s_waitcnt lgkmcnt(1)
	ds_write_b16 v222, v77 offset:53536
	v_cvt_pk_bf16_f32 v72, v72, v145
	ds_write_b16 v223, v72 offset:32800
	ds_read_u16 v72, v240 offset:8224
	v_mul_f32_e32 v74, v80, v73
	v_mul_f32_e32 v69, v69, v74
	v_cvt_pk_bf16_f32 v69, v69, v145
	ds_write_b16 v227, v69
	s_waitcnt lgkmcnt(1)
	ds_write_b16 v223, v72 offset:49184
	v_cvt_pk_bf16_f32 v72, v74, v145
	ds_write_b16 v226, v72
	ds_read_u16 v72, v240 offset:6208
	ds_write_b16 v223, v71 offset:16448
	v_add_f32_e32 v71, -1.0, v66
	v_fma_f32 v71, v194, v71, 1.0
	v_mul_f32_e32 v68, v71, v68
	s_waitcnt lgkmcnt(1)
	ds_write_b16 v222, v72 offset:53568
	v_cvt_pk_bf16_f32 v68, v68, v145
	ds_write_b16 v223, v68 offset:32832
	ds_read_u16 v68, v240 offset:8256
	v_mul_f32_e32 v69, v76, v73
	v_mul_f32_e32 v66, v66, v69
	v_cvt_pk_bf16_f32 v66, v66, v145
	ds_write_b16 v229, v66
	s_waitcnt lgkmcnt(1)
	ds_write_b16 v223, v68 offset:49216
	v_cvt_pk_bf16_f32 v68, v69, v145
	ds_write_b16 v228, v68
	ds_read_u16 v68, v240 offset:6240
	ds_write_b16 v223, v67 offset:16480
	v_add_f32_e32 v67, -1.0, v64
	v_fma_f32 v67, v195, v67, 1.0
	v_mul_f32_e32 v65, v67, v65
	s_waitcnt lgkmcnt(1)
	ds_write_b16 v222, v68 offset:53600
	v_cvt_pk_bf16_f32 v65, v65, v145
	ds_write_b16 v223, v65 offset:32864
	ds_read_u16 v65, v240 offset:8288
	v_mul_f32_e32 v66, v70, v73
	v_mul_f32_e32 v64, v64, v66
	v_cvt_pk_bf16_f32 v64, v64, v145
	ds_write_b16 v231, v64
	s_waitcnt lgkmcnt(1)
	ds_write_b16 v223, v65 offset:49248
	v_cvt_pk_bf16_f32 v65, v66, v145
	ds_write_b16 v230, v65
	s_waitcnt lgkmcnt(0)
	s_barrier
; #define LAS __attribute__((address_space(3)))
; __device__ __forceinline__ void phase_m1(PP P, int l, LAS unsigned char* lds, const Ids I) {
;     ...
;             __syncthreads();
; #pragma unroll
;             for (int i = 0; i < 2; ++i) { const int idx = tid + 512 * i, tok = idx >> 6, c8 = (idx & 63) * 8; const size_t o = (size_t)(r0 + tok) * 512 + c8; const LAS bf16_t* ob = OR + tok * 512 + c8;
;                 *(u32x4*)(arr + A_R * AS + o) = *(const LAS u32x4*)(ob); *(u32x4*)(arr + A_EW * AS + o) = *(const LAS u32x4*)(ob + 8192); *(u32x4*)(arr + A_KF * AS + o) = *(const LAS u32x4*)(ob + 2 * 8192);
;                 *(u32x4*)(arr + A_V * AS + o) = *(const LAS u32x4*)(ob + 3 * 8192); *(u32x4*)(arr + A_KK * AS + o) = *(const LAS u32x4*)(ob + 4 * 8192); *(u32x4*)(arr + A_BB * AS + o) = *(const LAS u32x4*)(ob + 5 * 8192); }
;         }
	s_mov_b32 s100, 1
	s_cbranch_scc0 .LBB0_227
	v_add_u32_e32 v68, s54, v97
	ds_read_b128 v[64:67], v232
	v_ashrrev_i32_e32 v69, 31, v68
	v_lshlrev_b64 v[68:69], 10, v[68:69]
	v_or_b32_e32 v68, v68, v241
	v_lshl_add_u64 v[70:71], s[0:1], 0, v[68:69]
	s_waitcnt lgkmcnt(0)
	global_store_dwordx4 v[70:71], v[64:67], off
	ds_read_b128 v[64:67], v232 offset:16384
	v_lshl_add_u64 v[70:71], s[74:75], 0, v[68:69]
	v_add_u32_e32 v97, s2, v97
	s_waitcnt lgkmcnt(0)
	global_store_dwordx4 v[70:71], v[64:67], off
	ds_read_b128 v[64:67], v232 offset:32768
	v_lshl_add_u64 v[70:71], s[6:7], 0, v[68:69]
	s_waitcnt lgkmcnt(0)
	global_store_dwordx4 v[70:71], v[64:67], off
	ds_read_b128 v[64:67], v232 offset:49152
	v_lshl_add_u64 v[70:71], s[50:51], 0, v[68:69]
	s_waitcnt lgkmcnt(0)
	global_store_dwordx4 v[70:71], v[64:67], off
	ds_read_b128 v[64:67], v233
	v_lshl_add_u64 v[70:71], s[52:53], 0, v[68:69]
	v_lshl_add_u64 v[68:69], s[70:71], 0, v[68:69]
	s_waitcnt lgkmcnt(0)
	global_store_dwordx4 v[70:71], v[64:67], off
	ds_read_b128 v[64:67], v234
	s_waitcnt lgkmcnt(0)
	global_store_dwordx4 v[68:69], v[64:67], off
	v_add_u32_e32 v68, s54, v235
	ds_read_b128 v[64:67], v236
	v_ashrrev_i32_e32 v69, 31, v68
	v_lshlrev_b64 v[68:69], 10, v[68:69]
	v_or_b32_e32 v68, v68, v241
	v_lshl_add_u64 v[70:71], s[0:1], 0, v[68:69]
	s_waitcnt lgkmcnt(0)
	global_store_dwordx4 v[70:71], v[64:67], off
	ds_read_b128 v[64:67], v236 offset:16384
	v_lshl_add_u64 v[70:71], s[74:75], 0, v[68:69]
	v_add_u32_e32 v235, s2, v235
	s_waitcnt lgkmcnt(0)
	global_store_dwordx4 v[70:71], v[64:67], off
	ds_read_b128 v[64:67], v236 offset:32768
	v_lshl_add_u64 v[70:71], s[6:7], 0, v[68:69]
	s_waitcnt lgkmcnt(0)
	global_store_dwordx4 v[70:71], v[64:67], off
	ds_read_b128 v[64:67], v236 offset:49152
	v_lshl_add_u64 v[70:71], s[50:51], 0, v[68:69]
	s_waitcnt lgkmcnt(0)
	global_store_dwordx4 v[70:71], v[64:67], off
	ds_read_b128 v[64:67], v237
	v_lshl_add_u64 v[70:71], s[52:53], 0, v[68:69]
	v_lshl_add_u64 v[68:69], s[70:71], 0, v[68:69]
	s_waitcnt lgkmcnt(0)
	global_store_dwordx4 v[70:71], v[64:67], off
	ds_read_b128 v[64:67], v238
	s_waitcnt lgkmcnt(0)
	global_store_dwordx4 v[68:69], v[64:67], off
	s_branch .LBB0_318
	s_nop 0
	s_nop 0
	s_nop 0
	s_nop 0
	s_nop 0
	s_nop 0
	s_nop 0
	s_nop 0
	s_nop 0
	s_nop 0
	s_nop 0
	s_nop 0
	s_nop 0
	s_nop 0
	s_nop 0
	s_nop 0
	s_nop 0
	s_nop 0
	s_nop 0
	s_nop 0
	s_nop 0
	s_nop 0
	s_nop 0
	s_nop 0
	s_nop 0
	s_nop 0
	s_nop 0
	s_nop 0
	s_nop 0
	s_nop 0
	s_nop 0
	s_nop 0
	s_nop 0
	s_nop 0
	s_nop 0
	s_nop 0
	s_nop 0
	s_nop 0
	s_nop 0
	s_nop 0
	s_nop 0
	s_nop 0
	s_nop 0
	s_nop 0
	s_nop 0
	s_nop 0
	s_nop 0
	s_nop 0
	s_nop 0
	s_nop 0
	s_nop 0
	s_nop 0
	s_nop 0
	s_nop 0
	s_nop 0
	s_nop 0
	s_nop 0
	s_nop 0
	s_nop 0
	s_nop 0
	s_nop 0
	s_nop 0

; #define LAS __attribute__((address_space(3)))
; __device__ __forceinline__ void phase_m1(PP P, int l, LAS unsigned char* lds, const Ids I) {
;     ...
;             __syncthreads();
; #pragma unroll
;             for (int i = 0; i < 2; ++i) { const int idx = tid + 512 * i, tok = idx >> 6, c8 = (idx & 63) * 8; const size_t o = (size_t)(r0 + tok) * 512 + c8; const LAS bf16_t* ob = OR + tok * 512 + c8;
;                 *(u32x4*)(arr + A_R * AS + o) = *(const LAS u32x4*)(ob); *(u32x4*)(arr + A_EW * AS + o) = *(const LAS u32x4*)(ob + 8192); *(u32x4*)(arr + A_KF * AS + o) = *(const LAS u32x4*)(ob + 2 * 8192);
;                 *(u32x4*)(arr + A_V * AS + o) = *(const LAS u32x4*)(ob + 3 * 8192); *(u32x4*)(arr + A_KK * AS + o) = *(const LAS u32x4*)(ob + 4 * 8192); *(u32x4*)(arr + A_BB * AS + o) = *(const LAS u32x4*)(ob + 5 * 8192); }
;         }
.Lp2_tail2:
	s_or_b64 exec, exec, s[68:69]
	s_cmp_eq_u32 s100, 0
	s_cbranch_scc1 .LBB0_226
	v_readlane_b32 s0, v254, 35
	v_readlane_b32 s1, v254, 36
	v_readlane_b32 s6, v254, 37
	v_readlane_b32 s7, v254, 38
	v_readlane_b32 s50, v254, 39
	v_readlane_b32 s51, v254, 40
	s_nop 3
	v_add_u32_e32 v68, s54, v97
	ds_read_b128 v[64:67], v232
	v_ashrrev_i32_e32 v69, 31, v68
	v_lshlrev_b64 v[68:69], 10, v[68:69]
	v_or_b32_e32 v68, v68, v241
	v_lshl_add_u64 v[70:71], s[0:1], 0, v[68:69]
	s_waitcnt lgkmcnt(0)
	global_store_dwordx4 v[70:71], v[64:67], off
	ds_read_b128 v[64:67], v232 offset:16384
	v_lshl_add_u64 v[70:71], s[74:75], 0, v[68:69]
	v_add_u32_e32 v97, s2, v97
	s_waitcnt lgkmcnt(0)
	global_store_dwordx4 v[70:71], v[64:67], off
	ds_read_b128 v[64:67], v232 offset:32768
	v_lshl_add_u64 v[70:71], s[6:7], 0, v[68:69]
	s_waitcnt lgkmcnt(0)
	global_store_dwordx4 v[70:71], v[64:67], off
	ds_read_b128 v[64:67], v232 offset:49152
	v_lshl_add_u64 v[70:71], s[50:51], 0, v[68:69]
	s_waitcnt lgkmcnt(0)
	global_store_dwordx4 v[70:71], v[64:67], off
	ds_read_b128 v[64:67], v233
	v_lshl_add_u64 v[70:71], s[52:53], 0, v[68:69]
	v_lshl_add_u64 v[68:69], s[70:71], 0, v[68:69]
	s_waitcnt lgkmcnt(0)
	global_store_dwordx4 v[70:71], v[64:67], off
	ds_read_b128 v[64:67], v234
	s_waitcnt lgkmcnt(0)
	global_store_dwordx4 v[68:69], v[64:67], off
	v_add_u32_e32 v68, s54, v235
	ds_read_b128 v[64:67], v236
	v_ashrrev_i32_e32 v69, 31, v68
	v_lshlrev_b64 v[68:69], 10, v[68:69]
	v_or_b32_e32 v68, v68, v241
	v_lshl_add_u64 v[70:71], s[0:1], 0, v[68:69]
	s_waitcnt lgkmcnt(0)
	global_store_dwordx4 v[70:71], v[64:67], off
	ds_read_b128 v[64:67], v236 offset:16384
	v_lshl_add_u64 v[70:71], s[74:75], 0, v[68:69]
	v_add_u32_e32 v235, s2, v235
	s_waitcnt lgkmcnt(0)
	global_store_dwordx4 v[70:71], v[64:67], off
	ds_read_b128 v[64:67], v236 offset:32768
	v_lshl_add_u64 v[70:71], s[6:7], 0, v[68:69]
	s_waitcnt lgkmcnt(0)
	global_store_dwordx4 v[70:71], v[64:67], off
	ds_read_b128 v[64:67], v236 offset:49152
	v_lshl_add_u64 v[70:71], s[50:51], 0, v[68:69]
	s_waitcnt lgkmcnt(0)
	global_store_dwordx4 v[70:71], v[64:67], off
	ds_read_b128 v[64:67], v237
	v_lshl_add_u64 v[70:71], s[52:53], 0, v[68:69]
	v_lshl_add_u64 v[68:69], s[70:71], 0, v[68:69]
	s_waitcnt lgkmcnt(0)
	global_store_dwordx4 v[70:71], v[64:67], off
	ds_read_b128 v[64:67], v238
	s_waitcnt lgkmcnt(0)
	global_store_dwordx4 v[68:69], v[64:67], off
	s_branch .LBB0_226
	s_nop 0
	s_nop 0
	s_nop 0
	s_nop 0
	s_nop 0
	s_nop 0
	s_nop 0
	s_nop 0
	s_nop 0
	s_nop 0
	s_nop 0
	s_nop 0
	s_nop 0
	s_nop 0
	s_nop 0

; #define PG8_STAGE(bufoff, gbase, voff) do { _Pragma("unroll") for (int _i = 0; _i < 2; ++_i) \
;         __builtin_amdgcn_global_load_lds((const unsigned*)((const char*)(gbase) + (voff)[_i]), (LAS unsigned*)(lds + (bufoff) + ldsw + _i * 8192), 16, 0, 0); } while (0)
; #define PG8_LDA(dst, b, h) do { _Pragma("unroll") for (int m = 0; m < 4; ++m) _Pragma("unroll") for (int k = 0; k < 2; ++k) dst[m][k] = *(const LAS bf16x8*)(lds + PG8_SA(b, h) + aoff + m * 2048 + k * 1024); } while (0)
; #define PG8_LDB(dst, b, h) do { _Pragma("unroll") for (int n = 0; n < 2; ++n) _Pragma("unroll") for (int k = 0; k < 2; ++k) dst[n][k] = *(const LAS bf16x8*)(lds + PG8_SB(b, h) + boff + n * 2048 + k * 1024); } while (0)
; #define PG8_MMA(ai, bj, At, Bt) do { __builtin_amdgcn_s_setprio(1); _Pragma("unroll") for (int m = 0; m < 4; ++m) _Pragma("unroll") for (int n = 0; n < 2; ++n) _Pragma("unroll") for (int k = 0; k < 2; ++k) \
;         acc[ai][bj][m][n] = __builtin_amdgcn_mfma_f32_16x16x32_bf16(Bt[n][k], At[m][k], acc[ai][bj][m][n], 0, 0, 0); __builtin_amdgcn_s_setprio(0); } while (0)
; #define PG8_WAIT_V(n) asm volatile("s_waitcnt vmcnt(" #n ")" ::: "memory")
; #define PG8_WAIT_L(n) asm volatile("s_waitcnt lgkmcnt(" #n ")" ::: "memory")
; #define PG8_BAR __builtin_amdgcn_s_barrier()
; #define PG8_SCHED __builtin_amdgcn_sched_barrier(0)
; template <class Epi, class Sched>
; __device__ __forceinline__ void gemm_phase(LAS unsigned char* lds, const Gemm g, const Sched& S, const Epi& E, const Ids I) {
;     ...
;             PG8_LDB(B0, 0, 0); PG8_SCHED; PG8_LDA(At, 0, 0); PG8_STAGE(PG8_SA(1, 1), a1 + hstep, voffA);
;             PG8_WAIT_L(8); PG8_BAR; PG8_WAIT_L(0); PG8_MMA(0, 0, At, B0); PG8_BAR; PG8_SCHED;
;             PG8_LDB(B1, 0, 1); PG8_STAGE(PG8_SB(0, 0), b2, voffB);
;             PG8_BAR; PG8_WAIT_L(0); PG8_MMA(0, 1, At, B1); PG8_BAR;
;             PG8_LDA(At, 0, 1); PG8_STAGE(PG8_SA(0, 0), a2, voffA);
;             PG8_BAR; PG8_WAIT_L(0); PG8_MMA(1, 0, At, B0); PG8_BAR; PG8_SCHED;
;             PG8_STAGE(PG8_SB(0, 1), b2 + hstep, voffB);
;             PG8_WAIT_V(6); PG8_BAR; PG8_MMA(1, 1, At, B1); PG8_BAR;
.LBB0_602:
	s_add_u32 s30, s28, 0xfffc0080
	s_addc_u32 s31, s29, -1
	s_add_i32 s60, 0, 0x10000
	v_add_u32_e32 v137, s60, v131
	ds_read_b128 v[158:161], v137
	ds_read_b128 v[162:165], v137 offset:1024
	ds_read_b128 v[166:169], v137 offset:2048
	ds_read_b128 v[170:173], v137 offset:3072
	s_cmp_eq_u32 s57, 12
	s_cselect_b32 s35, s23, s31
	s_cselect_b32 s34, s51, s30
	s_cselect_b32 s31, s3, s54
	s_cselect_b32 s30, s52, s53
	v_lshl_add_u64 v[176:177], s[28:29], 0, v[154:155]
	s_add_i32 m0, s41, 0xc000
	ds_read_b128 v[188:191], v135
	ds_read_b128 v[192:195], v135 offset:1024
	ds_read_b128 v[196:199], v135 offset:2048
	ds_read_b128 v[200:203], v135 offset:3072
	ds_read_b128 v[204:207], v135 offset:4096
	ds_read_b128 v[208:211], v135 offset:5120
	ds_read_b128 v[212:215], v135 offset:6144
	ds_read_b128 v[216:219], v135 offset:7168
	global_load_lds_dwordx4 v[176:177], off
	v_lshl_add_u64 v[176:177], s[28:29], 0, v[156:157]
	s_add_i32 m0, s41, 0xe000
	s_nop 0
	global_load_lds_dwordx4 v[176:177], off
	s_waitcnt lgkmcnt(8)
	s_barrier
	s_waitcnt lgkmcnt(0)
	s_setprio 1
	s_waitcnt lgkmcnt(0)
	v_mfma_f32_16x16x32_bf16 v[124:127], v[158:161], v[188:191], v[124:127]
	v_mfma_f32_16x16x32_bf16 v[120:123], v[166:169], v[188:191], v[120:123]
	v_mfma_f32_16x16x32_bf16 v[108:111], v[158:161], v[196:199], v[108:111]
	v_mfma_f32_16x16x32_bf16 v[104:107], v[166:169], v[196:199], v[104:107]
	v_mfma_f32_16x16x32_bf16 v[92:95], v[158:161], v[204:207], v[92:95]
	v_mfma_f32_16x16x32_bf16 v[88:91], v[166:169], v[204:207], v[88:91]
	v_mfma_f32_16x16x32_bf16 v[76:79], v[158:161], v[212:215], v[76:79]
	v_mfma_f32_16x16x32_bf16 v[72:75], v[166:169], v[212:215], v[72:75]
	v_mfma_f32_16x16x32_bf16 v[124:127], v[162:165], v[192:195], v[124:127]
	v_mfma_f32_16x16x32_bf16 v[120:123], v[170:173], v[192:195], v[120:123]
	v_mfma_f32_16x16x32_bf16 v[108:111], v[162:165], v[200:203], v[108:111]
	v_mfma_f32_16x16x32_bf16 v[104:107], v[170:173], v[200:203], v[104:107]
	v_mfma_f32_16x16x32_bf16 v[92:95], v[162:165], v[208:211], v[92:95]
	v_mfma_f32_16x16x32_bf16 v[88:91], v[170:173], v[208:211], v[88:91]
	v_mfma_f32_16x16x32_bf16 v[76:79], v[162:165], v[216:219], v[76:79]
	v_mfma_f32_16x16x32_bf16 v[72:75], v[170:173], v[216:219], v[72:75]
	s_setprio 0
	s_barrier
	s_add_i32 s66, 0, 0x14000
	s_add_i32 s60, s60, s40
	v_add_u32_e32 v137, s66, v131
	v_lshl_add_u64 v[176:177], s[30:31], 0, v[144:145]
	s_mov_b32 m0, s60
	ds_read_b128 v[220:223], v137
	ds_read_b128 v[224:227], v137 offset:1024
	ds_read_b128 v[228:231], v137 offset:2048
	ds_read_b128 v[232:235], v137 offset:3072
	global_load_lds_dwordx4 v[176:177], off
	v_lshl_add_u64 v[178:179], s[30:31], 0, v[128:129]
	s_add_i32 m0, s60, 0x2000
	s_nop 0
	global_load_lds_dwordx4 v[178:179], off
	s_barrier
	s_waitcnt lgkmcnt(0)
	s_setprio 1
	s_waitcnt lgkmcnt(0)
	v_mfma_f32_16x16x32_bf16 v[116:119], v[220:223], v[188:191], v[116:119]
	v_mfma_f32_16x16x32_bf16 v[112:115], v[228:231], v[188:191], v[112:115]
	v_mfma_f32_16x16x32_bf16 v[100:103], v[220:223], v[196:199], v[100:103]
	v_mfma_f32_16x16x32_bf16 v[96:99], v[228:231], v[196:199], v[96:99]
	v_mfma_f32_16x16x32_bf16 v[84:87], v[220:223], v[204:207], v[84:87]
	v_mfma_f32_16x16x32_bf16 v[80:83], v[228:231], v[204:207], v[80:83]
	v_mfma_f32_16x16x32_bf16 v[68:71], v[220:223], v[212:215], v[68:71]
	v_mfma_f32_16x16x32_bf16 v[64:67], v[228:231], v[212:215], v[64:67]
	v_mfma_f32_16x16x32_bf16 v[116:119], v[224:227], v[192:195], v[116:119]
	v_mfma_f32_16x16x32_bf16 v[112:115], v[232:235], v[192:195], v[112:115]
	v_mfma_f32_16x16x32_bf16 v[100:103], v[224:227], v[200:203], v[100:103]
	v_mfma_f32_16x16x32_bf16 v[96:99], v[232:235], v[200:203], v[96:99]
	v_mfma_f32_16x16x32_bf16 v[84:87], v[224:227], v[208:211], v[84:87]
	v_mfma_f32_16x16x32_bf16 v[80:83], v[232:235], v[208:211], v[80:83]
	v_mfma_f32_16x16x32_bf16 v[68:71], v[224:227], v[216:219], v[68:71]
	v_mfma_f32_16x16x32_bf16 v[64:67], v[232:235], v[216:219], v[64:67]
	s_setprio 0
	s_mov_b32 m0, s41
	v_lshl_add_u64 v[180:181], s[34:35], 0, v[144:145]
	s_barrier
	ds_read_b128 v[188:191], v135 offset:16384
	ds_read_b128 v[192:195], v135 offset:17408
	ds_read_b128 v[196:199], v135 offset:18432
	ds_read_b128 v[200:203], v135 offset:19456
	ds_read_b128 v[204:207], v135 offset:20480
	ds_read_b128 v[208:211], v135 offset:21504
	ds_read_b128 v[212:215], v135 offset:22528
	ds_read_b128 v[216:219], v135 offset:23552
	global_load_lds_dwordx4 v[180:181], off
	v_lshl_add_u64 v[182:183], s[34:35], 0, v[128:129]
	s_mov_b32 m0, s42
	s_nop 0
	global_load_lds_dwordx4 v[182:183], off
	s_barrier
	s_waitcnt lgkmcnt(0)
	s_setprio 1
	s_waitcnt lgkmcnt(0)
	v_mfma_f32_16x16x32_bf16 v[60:63], v[158:161], v[188:191], v[60:63]
	v_mfma_f32_16x16x32_bf16 v[56:59], v[166:169], v[188:191], v[56:59]
	v_mfma_f32_16x16x32_bf16 v[44:47], v[158:161], v[196:199], v[44:47]
	v_mfma_f32_16x16x32_bf16 v[40:43], v[166:169], v[196:199], v[40:43]
	v_mfma_f32_16x16x32_bf16 v[28:31], v[158:161], v[204:207], v[28:31]
	v_mfma_f32_16x16x32_bf16 v[24:27], v[166:169], v[204:207], v[24:27]
	v_mfma_f32_16x16x32_bf16 v[12:15], v[158:161], v[212:215], v[12:15]
	v_mfma_f32_16x16x32_bf16 v[8:11], v[166:169], v[212:215], v[8:11]
	v_mfma_f32_16x16x32_bf16 v[60:63], v[162:165], v[192:195], v[60:63]
	v_mfma_f32_16x16x32_bf16 v[56:59], v[170:173], v[192:195], v[56:59]
	v_mfma_f32_16x16x32_bf16 v[44:47], v[162:165], v[200:203], v[44:47]
	v_mfma_f32_16x16x32_bf16 v[40:43], v[170:173], v[200:203], v[40:43]
	v_mfma_f32_16x16x32_bf16 v[28:31], v[162:165], v[208:211], v[28:31]
	v_mfma_f32_16x16x32_bf16 v[24:27], v[170:173], v[208:211], v[24:27]
	v_mfma_f32_16x16x32_bf16 v[12:15], v[162:165], v[216:219], v[12:15]
	v_mfma_f32_16x16x32_bf16 v[8:11], v[170:173], v[216:219], v[8:11]
	s_setprio 0
	s_barrier
; #define PG8_STAGE(bufoff, gbase, voff) do { _Pragma("unroll") for (int _i = 0; _i < 2; ++_i) \
;         __builtin_amdgcn_global_load_lds((const unsigned*)((const char*)(gbase) + (voff)[_i]), (LAS unsigned*)(lds + (bufoff) + ldsw + _i * 8192), 16, 0, 0); } while (0)
; #define PG8_LDA(dst, b, h) do { _Pragma("unroll") for (int m = 0; m < 4; ++m) _Pragma("unroll") for (int k = 0; k < 2; ++k) dst[m][k] = *(const LAS bf16x8*)(lds + PG8_SA(b, h) + aoff + m * 2048 + k * 1024); } while (0)
; #define PG8_LDB(dst, b, h) do { _Pragma("unroll") for (int n = 0; n < 2; ++n) _Pragma("unroll") for (int k = 0; k < 2; ++k) dst[n][k] = *(const LAS bf16x8*)(lds + PG8_SB(b, h) + boff + n * 2048 + k * 1024); } while (0)
; #define PG8_MMA(ai, bj, At, Bt) do { __builtin_amdgcn_s_setprio(1); _Pragma("unroll") for (int m = 0; m < 4; ++m) _Pragma("unroll") for (int n = 0; n < 2; ++n) _Pragma("unroll") for (int k = 0; k < 2; ++k) \
;         acc[ai][bj][m][n] = __builtin_amdgcn_mfma_f32_16x16x32_bf16(Bt[n][k], At[m][k], acc[ai][bj][m][n], 0, 0, 0); __builtin_amdgcn_s_setprio(0); } while (0)
; #define PG8_WAIT_V(n) asm volatile("s_waitcnt vmcnt(" #n ")" ::: "memory")
; #define PG8_WAIT_L(n) asm volatile("s_waitcnt lgkmcnt(" #n ")" ::: "memory")
; #define PG8_BAR __builtin_amdgcn_s_barrier()
; #define PG8_SCHED __builtin_amdgcn_sched_barrier(0)
; template <class Epi, class Sched>
; __device__ __forceinline__ void gemm_phase(LAS unsigned char* lds, const Gemm g, const Sched& S, const Epi& E, const Ids I) {
;     ...
;             PG8_LDB(B0, 1, 0); PG8_SCHED; PG8_LDA(At, 1, 0); PG8_STAGE(PG8_SA(0, 1), a2 + hstep, voffA);
;             PG8_WAIT_L(8); PG8_BAR; PG8_WAIT_L(0); PG8_MMA(0, 0, At, B0); PG8_BAR; PG8_SCHED;
;             PG8_LDB(B1, 1, 1); PG8_STAGE(PG8_SB(1, 0), b3, voffB);
;             PG8_BAR; PG8_WAIT_L(0); PG8_MMA(0, 1, At, B1); PG8_BAR;
;             PG8_LDA(At, 1, 1); PG8_STAGE(PG8_SA(1, 0), a3, voffA);
;             PG8_BAR; PG8_WAIT_L(0); PG8_MMA(1, 0, At, B0); PG8_BAR; PG8_SCHED;
;             PG8_STAGE(PG8_SB(1, 1), b3 + hstep, voffB);
;             PG8_WAIT_V(6); PG8_BAR; PG8_MMA(1, 1, At, B1); PG8_BAR;
	s_add_u32 s60, s30, 0x40000
	s_addc_u32 s61, s31, 0
	s_add_i32 s66, s66, s40
	v_lshl_add_u64 v[158:159], s[60:61], 0, v[144:145]
	s_mov_b32 m0, s66
	s_nop 0
	global_load_lds_dwordx4 v[158:159], off
	v_lshl_add_u64 v[158:159], s[60:61], 0, v[128:129]
	s_add_i32 m0, s66, 0x2000
	s_nop 0
	global_load_lds_dwordx4 v[158:159], off
	s_waitcnt vmcnt(6)
	s_barrier
	s_setprio 1
	v_mfma_f32_16x16x32_bf16 v[52:55], v[220:223], v[188:191], v[52:55]
	v_mfma_f32_16x16x32_bf16 v[48:51], v[228:231], v[188:191], v[48:51]
	v_mfma_f32_16x16x32_bf16 v[36:39], v[220:223], v[196:199], v[36:39]
	v_mfma_f32_16x16x32_bf16 v[32:35], v[228:231], v[196:199], v[32:35]
	v_mfma_f32_16x16x32_bf16 v[20:23], v[220:223], v[204:207], v[20:23]
	v_mfma_f32_16x16x32_bf16 v[16:19], v[228:231], v[204:207], v[16:19]
	v_mfma_f32_16x16x32_bf16 v[4:7], v[220:223], v[212:215], v[4:7]
	v_mfma_f32_16x16x32_bf16 v[0:3], v[228:231], v[212:215], v[0:3]
	v_mfma_f32_16x16x32_bf16 v[52:55], v[224:227], v[192:195], v[52:55]
	v_mfma_f32_16x16x32_bf16 v[48:51], v[232:235], v[192:195], v[48:51]
	v_mfma_f32_16x16x32_bf16 v[36:39], v[224:227], v[200:203], v[36:39]
	v_mfma_f32_16x16x32_bf16 v[32:35], v[232:235], v[200:203], v[32:35]
	v_mfma_f32_16x16x32_bf16 v[20:23], v[224:227], v[208:211], v[20:23]
	v_mfma_f32_16x16x32_bf16 v[16:19], v[232:235], v[208:211], v[16:19]
	v_mfma_f32_16x16x32_bf16 v[4:7], v[224:227], v[216:219], v[4:7]
	v_mfma_f32_16x16x32_bf16 v[0:3], v[232:235], v[216:219], v[0:3]
	s_setprio 0
	s_add_i32 s60, 0, 0x18000
	v_add_u32_e32 v137, s60, v131
	s_barrier
	ds_read_b128 v[158:161], v137
	ds_read_b128 v[162:165], v137 offset:1024
	ds_read_b128 v[166:169], v137 offset:2048
	ds_read_b128 v[170:173], v137 offset:3072
	s_add_u32 s34, s34, 0x40000
	s_addc_u32 s35, s35, 0
	s_mov_b32 m0, s43
	v_lshl_add_u64 v[220:221], s[34:35], 0, v[144:145]
	ds_read_b128 v[188:191], v135 offset:32768
	ds_read_b128 v[192:195], v135 offset:33792
	ds_read_b128 v[196:199], v135 offset:34816
	ds_read_b128 v[200:203], v135 offset:35840
	ds_read_b128 v[204:207], v135 offset:36864
	ds_read_b128 v[208:211], v135 offset:37888
	ds_read_b128 v[212:215], v135 offset:38912
	ds_read_b128 v[216:219], v135 offset:39936
	global_load_lds_dwordx4 v[220:221], off
	v_lshl_add_u64 v[220:221], s[34:35], 0, v[128:129]
	s_mov_b32 m0, s44
	s_nop 0
	global_load_lds_dwordx4 v[220:221], off
	s_waitcnt lgkmcnt(8)
	s_barrier
	s_waitcnt lgkmcnt(0)
	s_setprio 1
	s_waitcnt lgkmcnt(0)
	v_mfma_f32_16x16x32_bf16 v[124:127], v[158:161], v[188:191], v[124:127]
	v_mfma_f32_16x16x32_bf16 v[120:123], v[166:169], v[188:191], v[120:123]
	v_mfma_f32_16x16x32_bf16 v[108:111], v[158:161], v[196:199], v[108:111]
	v_mfma_f32_16x16x32_bf16 v[104:107], v[166:169], v[196:199], v[104:107]
	v_mfma_f32_16x16x32_bf16 v[92:95], v[158:161], v[204:207], v[92:95]
	v_mfma_f32_16x16x32_bf16 v[88:91], v[166:169], v[204:207], v[88:91]
	v_mfma_f32_16x16x32_bf16 v[76:79], v[158:161], v[212:215], v[76:79]
	v_mfma_f32_16x16x32_bf16 v[72:75], v[166:169], v[212:215], v[72:75]
	v_mfma_f32_16x16x32_bf16 v[124:127], v[162:165], v[192:195], v[124:127]
	v_mfma_f32_16x16x32_bf16 v[120:123], v[170:173], v[192:195], v[120:123]
	v_mfma_f32_16x16x32_bf16 v[108:111], v[162:165], v[200:203], v[108:111]
	v_mfma_f32_16x16x32_bf16 v[104:107], v[170:173], v[200:203], v[104:107]
	v_mfma_f32_16x16x32_bf16 v[92:95], v[162:165], v[208:211], v[92:95]
	v_mfma_f32_16x16x32_bf16 v[88:91], v[170:173], v[208:211], v[88:91]
	v_mfma_f32_16x16x32_bf16 v[76:79], v[162:165], v[216:219], v[76:79]
	v_mfma_f32_16x16x32_bf16 v[72:75], v[170:173], v[216:219], v[72:75]
	s_setprio 0
	s_barrier
	s_add_i32 s34, 0, 0x1c000
	s_add_i32 s35, s60, s40
	v_add_u32_e32 v137, s34, v131
	v_lshl_add_u64 v[176:177], v[176:177], 0, s[64:65]
	s_mov_b32 m0, s35
	ds_read_b128 v[220:223], v137
	ds_read_b128 v[224:227], v137 offset:1024
	ds_read_b128 v[228:231], v137 offset:2048
	ds_read_b128 v[232:235], v137 offset:3072
	global_load_lds_dwordx4 v[176:177], off
	v_lshl_add_u64 v[176:177], v[178:179], 0, s[64:65]
	s_add_i32 m0, s35, 0x2000
	s_nop 0
	global_load_lds_dwordx4 v[176:177], off
	s_barrier
	s_waitcnt lgkmcnt(0)
	s_setprio 1
	s_waitcnt lgkmcnt(0)
	v_mfma_f32_16x16x32_bf16 v[116:119], v[220:223], v[188:191], v[116:119]
	v_mfma_f32_16x16x32_bf16 v[112:115], v[228:231], v[188:191], v[112:115]
	v_mfma_f32_16x16x32_bf16 v[100:103], v[220:223], v[196:199], v[100:103]
	v_mfma_f32_16x16x32_bf16 v[96:99], v[228:231], v[196:199], v[96:99]
	v_mfma_f32_16x16x32_bf16 v[84:87], v[220:223], v[204:207], v[84:87]
	v_mfma_f32_16x16x32_bf16 v[80:83], v[228:231], v[204:207], v[80:83]
	v_mfma_f32_16x16x32_bf16 v[68:71], v[220:223], v[212:215], v[68:71]
	v_mfma_f32_16x16x32_bf16 v[64:67], v[228:231], v[212:215], v[64:67]
	v_mfma_f32_16x16x32_bf16 v[116:119], v[224:227], v[192:195], v[116:119]
	v_mfma_f32_16x16x32_bf16 v[112:115], v[232:235], v[192:195], v[112:115]
	v_mfma_f32_16x16x32_bf16 v[100:103], v[224:227], v[200:203], v[100:103]
	v_mfma_f32_16x16x32_bf16 v[96:99], v[232:235], v[200:203], v[96:99]
	v_mfma_f32_16x16x32_bf16 v[84:87], v[224:227], v[208:211], v[84:87]
	v_mfma_f32_16x16x32_bf16 v[80:83], v[232:235], v[208:211], v[80:83]
	v_mfma_f32_16x16x32_bf16 v[68:71], v[224:227], v[216:219], v[68:71]
	v_mfma_f32_16x16x32_bf16 v[64:67], v[232:235], v[216:219], v[64:67]
	s_setprio 0
	s_mov_b32 m0, s45
	v_lshl_add_u64 v[176:177], v[180:181], 0, s[64:65]
	s_barrier
; #define PG8_MMA(ai, bj, At, Bt) do { __builtin_amdgcn_s_setprio(1); _Pragma("unroll") for (int m = 0; m < 4; ++m) _Pragma("unroll") for (int n = 0; n < 2; ++n) _Pragma("unroll") for (int k = 0; k < 2; ++k) \
;         acc[ai][bj][m][n] = __builtin_amdgcn_mfma_f32_16x16x32_bf16(Bt[n][k], At[m][k], acc[ai][bj][m][n], 0, 0, 0); __builtin_amdgcn_s_setprio(0); } while (0)
; #define PG8_WAIT_V(n) asm volatile("s_waitcnt vmcnt(" #n ")" ::: "memory")
; #define PG8_BAR __builtin_amdgcn_s_barrier()
; template <class Epi, class Sched>
; __device__ __forceinline__ void gemm_phase(LAS unsigned char* lds, const Gemm g, const Sched& S, const Epi& E, const Ids I) {
;     ...
;             PG8_WAIT_V(6); PG8_BAR; PG8_MMA(1, 1, At, B1); PG8_BAR;
;         }
;         E(acc, cur, wr, wc, fr, fq);
;     __device__ __forceinline__ void operator()(const f32x4 (&acc)[2][2][4][2], const pg8::Unit& u, int wr, int wc, int fr, int fq) const {
;         const int row0 = wr * 64 + fr, colg0 = u.pn * 256 + wc * 32 + 4 * fq; const int l = (u.pn >= 36) ? 1 : 0; const int col0 = colg0 - l * 9216;
; #pragma unroll
;         for (int ai = 0; ai < 2; ++ai)
; #pragma unroll
;             for (int m = 0; m < 4; ++m) { const int row = row0 + ai * 128 + m * 16;
;                 if (row < NMR) { float* rowp = mod + ((size_t)l * NMR + row) * 9216 + col0;
; #pragma unroll
;                     for (int bj = 0; bj < 2; ++bj)
; #pragma unroll
;                         for (int n = 0; n < 2; ++n) { const f32x4 bv = *(const f32x4*)(bias + colg0 + bj * 128 + n * 16); *(f32x4*)(rowp + bj * 128 + n * 16) = acc[ai][bj][m][n] + bv; } } }
	ds_read_b128 v[188:191], v135 offset:49152
	ds_read_b128 v[192:195], v135 offset:50176
	ds_read_b128 v[196:199], v135 offset:51200
	ds_read_b128 v[200:203], v135 offset:52224
	ds_read_b128 v[204:207], v135 offset:53248
	ds_read_b128 v[208:211], v135 offset:54272
	ds_read_b128 v[212:215], v135 offset:55296
	ds_read_b128 v[216:219], v135 offset:56320
	global_load_lds_dwordx4 v[176:177], off
	v_lshl_add_u64 v[176:177], v[182:183], 0, s[64:65]
	s_mov_b32 m0, s46
	s_nop 0
	global_load_lds_dwordx4 v[176:177], off
	s_barrier
	s_waitcnt lgkmcnt(0)
	s_setprio 1
	s_waitcnt lgkmcnt(0)
	v_mfma_f32_16x16x32_bf16 v[60:63], v[158:161], v[188:191], v[60:63]
	v_mfma_f32_16x16x32_bf16 v[56:59], v[166:169], v[188:191], v[56:59]
	v_mfma_f32_16x16x32_bf16 v[44:47], v[158:161], v[196:199], v[44:47]
	v_mfma_f32_16x16x32_bf16 v[40:43], v[166:169], v[196:199], v[40:43]
	v_mfma_f32_16x16x32_bf16 v[28:31], v[158:161], v[204:207], v[28:31]
	v_mfma_f32_16x16x32_bf16 v[24:27], v[166:169], v[204:207], v[24:27]
	v_mfma_f32_16x16x32_bf16 v[12:15], v[158:161], v[212:215], v[12:15]
	v_mfma_f32_16x16x32_bf16 v[8:11], v[166:169], v[212:215], v[8:11]
	v_mfma_f32_16x16x32_bf16 v[60:63], v[162:165], v[192:195], v[60:63]
	v_mfma_f32_16x16x32_bf16 v[56:59], v[170:173], v[192:195], v[56:59]
	v_mfma_f32_16x16x32_bf16 v[44:47], v[162:165], v[200:203], v[44:47]
	v_mfma_f32_16x16x32_bf16 v[40:43], v[170:173], v[200:203], v[40:43]
	v_mfma_f32_16x16x32_bf16 v[28:31], v[162:165], v[208:211], v[28:31]
	v_mfma_f32_16x16x32_bf16 v[24:27], v[170:173], v[208:211], v[24:27]
	v_mfma_f32_16x16x32_bf16 v[12:15], v[162:165], v[216:219], v[12:15]
	v_mfma_f32_16x16x32_bf16 v[8:11], v[170:173], v[216:219], v[8:11]
	s_setprio 0
	s_barrier
	s_add_u32 s30, s30, 0x40080
	s_addc_u32 s31, s31, 0
	s_add_i32 s34, s34, s40
	v_lshl_add_u64 v[158:159], s[30:31], 0, v[144:145]
	s_mov_b32 m0, s34
	s_nop 0
	global_load_lds_dwordx4 v[158:159], off
	v_lshl_add_u64 v[158:159], s[30:31], 0, v[128:129]
	s_add_i32 m0, s34, 0x2000
	s_nop 0
	global_load_lds_dwordx4 v[158:159], off
	s_waitcnt vmcnt(6)
	s_barrier
	s_setprio 1
	v_mfma_f32_16x16x32_bf16 v[52:55], v[220:223], v[188:191], v[52:55]
	v_mfma_f32_16x16x32_bf16 v[48:51], v[228:231], v[188:191], v[48:51]
	v_mfma_f32_16x16x32_bf16 v[36:39], v[220:223], v[196:199], v[36:39]
	v_mfma_f32_16x16x32_bf16 v[32:35], v[228:231], v[196:199], v[32:35]
	v_mfma_f32_16x16x32_bf16 v[20:23], v[220:223], v[204:207], v[20:23]
	v_mfma_f32_16x16x32_bf16 v[16:19], v[228:231], v[204:207], v[16:19]
	v_mfma_f32_16x16x32_bf16 v[4:7], v[220:223], v[212:215], v[4:7]
	v_mfma_f32_16x16x32_bf16 v[0:3], v[228:231], v[212:215], v[0:3]
	v_mfma_f32_16x16x32_bf16 v[52:55], v[224:227], v[192:195], v[52:55]
	v_mfma_f32_16x16x32_bf16 v[48:51], v[232:235], v[192:195], v[48:51]
	v_mfma_f32_16x16x32_bf16 v[36:39], v[224:227], v[200:203], v[36:39]
	v_mfma_f32_16x16x32_bf16 v[32:35], v[232:235], v[200:203], v[32:35]
	v_mfma_f32_16x16x32_bf16 v[20:23], v[224:227], v[208:211], v[20:23]
	v_mfma_f32_16x16x32_bf16 v[16:19], v[232:235], v[208:211], v[16:19]
	v_mfma_f32_16x16x32_bf16 v[4:7], v[224:227], v[216:219], v[4:7]
	v_mfma_f32_16x16x32_bf16 v[0:3], v[232:235], v[216:219], v[0:3]
	s_setprio 0
	s_add_i32 s57, s57, 2
	s_add_u32 s28, s28, 0x100
	s_addc_u32 s29, s29, 0
	s_add_u32 s53, s53, 0x100
	s_addc_u32 s54, s54, 0
	s_cmp_gt_u32 s57, 13
	s_barrier
	s_cbranch_scc0 .LBB0_602
	s_load_dwordx2 s[28:29], s[88:89], 0x48
	s_cmp_gt_i32 s50, 35
	v_lshl_or_b32 v158, s50, 8, v133
	s_cselect_b32 s3, 0xffffdc00, 0
	v_add_u32_e32 v160, s3, v158
	v_ashrrev_i32_e32 v159, 31, v158
	s_cselect_b32 s3, 0x88, 0
	v_ashrrev_i32_e32 v161, 31, v160
	s_waitcnt lgkmcnt(0)
	v_lshl_add_u64 v[158:159], v[158:159], 2, s[28:29]
	global_load_dwordx4 v[188:191], v[158:159], off
	global_load_dwordx4 v[192:195], v[158:159], off offset:64
	global_load_dwordx4 v[196:199], v[158:159], off offset:512
	global_load_dwordx4 v[200:203], v[158:159], off offset:576
	s_waitcnt vmcnt(0)
	s_and_saveexec_b64 s[28:29], s[4:5]
	s_cbranch_execz .LBB0_611
	v_add_u32_e32 v137, s3, v130
	v_mov_b64_e32 v[162:163], s[80:81]
	v_mad_i64_i32 v[162:163], s[30:31], v137, s59, v[162:163]
	v_lshl_add_u64 v[166:167], v[160:161], 2, v[162:163]
	v_pk_add_f32 v[126:127], v[126:127], v[190:191]
	v_pk_add_f32 v[124:125], v[124:125], v[188:189]
	global_store_dwordx4 v[166:167], v[124:127], off
	v_pk_add_f32 v[122:123], v[122:123], v[194:195]
	v_pk_add_f32 v[120:121], v[120:121], v[192:193]
	global_store_dwordx4 v[166:167], v[120:123], off offset:64
	v_pk_add_f32 v[118:119], v[118:119], v[198:199]
	v_pk_add_f32 v[116:117], v[116:117], v[196:197]
	global_store_dwordx4 v[166:167], v[116:119], off offset:512
	v_pk_add_f32 v[114:115], v[114:115], v[202:203]
	v_pk_add_f32 v[112:113], v[112:113], v[200:201]
	global_store_dwordx4 v[166:167], v[112:115], off offset:576
	s_or_b64 exec, exec, s[28:29]
	s_and_saveexec_b64 s[28:29], s[6:7]
	s_mov_b32 s57, 0x80000
	s_cbranch_execnz .LBB0_612

;     __device__ __forceinline__ void operator()(const f32x4 (&acc)[2][2][4][2], const pg8::Unit& u, int wr, int wc, int fr, int fq) const {
;     ...
;                 if (row < NMR) { float* rowp = mod + ((size_t)l * NMR + row) * 9216 + col0;
; #pragma unroll
;                     for (int bj = 0; bj < 2; ++bj)
; #pragma unroll
;                         for (int n = 0; n < 2; ++n) { const f32x4 bv = *(const f32x4*)(bias + colg0 + bj * 128 + n * 16); *(f32x4*)(rowp + bj * 128 + n * 16) = acc[ai][bj][m][n] + bv; } } }
.LBB0_606:
	v_add_u32_e32 v98, s3, v134
	v_mov_b64_e32 v[96:97], s[80:81]
	v_mad_i64_i32 v[96:97], s[30:31], v98, s59, v[96:97]
	v_lshl_add_u64 v[100:101], v[160:161], 2, v[96:97]
	v_pk_add_f32 v[94:95], v[94:95], v[190:191]
	v_pk_add_f32 v[92:93], v[92:93], v[188:189]
	global_store_dwordx4 v[100:101], v[92:95], off
	v_pk_add_f32 v[90:91], v[90:91], v[194:195]
	v_pk_add_f32 v[88:89], v[88:89], v[192:193]
	global_store_dwordx4 v[100:101], v[88:91], off offset:64
	v_pk_add_f32 v[86:87], v[86:87], v[198:199]
	v_pk_add_f32 v[84:85], v[84:85], v[196:197]
	global_store_dwordx4 v[100:101], v[84:87], off offset:512
	v_pk_add_f32 v[82:83], v[82:83], v[202:203]
	v_pk_add_f32 v[80:81], v[80:81], v[200:201]
	global_store_dwordx4 v[100:101], v[80:83], off offset:576
	s_or_b64 exec, exec, s[28:29]
	s_and_saveexec_b64 s[28:29], s[10:11]
	s_movk_i32 s66, 0x104
	s_cbranch_execnz .LBB0_614

;     __device__ __forceinline__ void operator()(const f32x4 (&acc)[2][2][4][2], const pg8::Unit& u, int wr, int wc, int fr, int fq) const {
;     ...
;                 if (row < NMR) { float* rowp = mod + ((size_t)l * NMR + row) * 9216 + col0;
; #pragma unroll
;                     for (int bj = 0; bj < 2; ++bj)
; #pragma unroll
;                         for (int n = 0; n < 2; ++n) { const f32x4 bv = *(const f32x4*)(bias + colg0 + bj * 128 + n * 16); *(f32x4*)(rowp + bj * 128 + n * 16) = acc[ai][bj][m][n] + bv; } } }
.LBB0_608:
	v_add_u32_e32 v66, s3, v138
	v_mov_b64_e32 v[64:65], s[80:81]
	v_mad_i64_i32 v[64:65], s[30:31], v66, s59, v[64:65]
	v_lshl_add_u64 v[68:69], v[160:161], 2, v[64:65]
	v_pk_add_f32 v[62:63], v[62:63], v[190:191]
	v_pk_add_f32 v[60:61], v[60:61], v[188:189]
	global_store_dwordx4 v[68:69], v[60:63], off
	v_pk_add_f32 v[58:59], v[58:59], v[194:195]
	v_pk_add_f32 v[56:57], v[56:57], v[192:193]
	global_store_dwordx4 v[68:69], v[56:59], off offset:64
	v_pk_add_f32 v[54:55], v[54:55], v[198:199]
	v_pk_add_f32 v[52:53], v[52:53], v[196:197]
	global_store_dwordx4 v[68:69], v[52:55], off offset:512
	v_pk_add_f32 v[50:51], v[50:51], v[202:203]
	v_pk_add_f32 v[48:49], v[48:49], v[200:201]
	global_store_dwordx4 v[68:69], v[48:51], off offset:576
	s_or_b64 exec, exec, s[28:29]
	s_and_saveexec_b64 s[28:29], s[14:15]
	s_cbranch_execnz .LBB0_616

;     __device__ __forceinline__ void operator()(const f32x4 (&acc)[2][2][4][2], const pg8::Unit& u, int wr, int wc, int fr, int fq) const {
;     ...
;                 if (row < NMR) { float* rowp = mod + ((size_t)l * NMR + row) * 9216 + col0;
; #pragma unroll
;                     for (int bj = 0; bj < 2; ++bj)
; #pragma unroll
;                         for (int n = 0; n < 2; ++n) { const f32x4 bv = *(const f32x4*)(bias + colg0 + bj * 128 + n * 16); *(f32x4*)(rowp + bj * 128 + n * 16) = acc[ai][bj][m][n] + bv; } } }
.LBB0_610:
	v_add_u32_e32 v34, s3, v142
	v_mov_b64_e32 v[32:33], s[80:81]
	v_mad_i64_i32 v[32:33], s[30:31], v34, s59, v[32:33]
	v_lshl_add_u64 v[36:37], v[160:161], 2, v[32:33]
	v_pk_add_f32 v[30:31], v[30:31], v[190:191]
	v_pk_add_f32 v[28:29], v[28:29], v[188:189]
	global_store_dwordx4 v[36:37], v[28:31], off
	v_pk_add_f32 v[26:27], v[26:27], v[194:195]
	v_pk_add_f32 v[24:25], v[24:25], v[192:193]
	global_store_dwordx4 v[36:37], v[24:27], off offset:64
	v_pk_add_f32 v[22:23], v[22:23], v[198:199]
	v_pk_add_f32 v[20:21], v[20:21], v[196:197]
	global_store_dwordx4 v[36:37], v[20:23], off offset:512
	v_pk_add_f32 v[18:19], v[18:19], v[202:203]
	v_pk_add_f32 v[16:17], v[16:17], v[200:201]
	global_store_dwordx4 v[36:37], v[16:19], off offset:576
	s_or_b64 exec, exec, s[28:29]
	s_and_saveexec_b64 s[28:29], s[18:19]
	s_cbranch_execz .LBB0_598
	s_branch .LBB0_618

;     __device__ __forceinline__ void operator()(const f32x4 (&acc)[2][2][4][2], const pg8::Unit& u, int wr, int wc, int fr, int fq) const {
;     ...
;                 if (row < NMR) { float* rowp = mod + ((size_t)l * NMR + row) * 9216 + col0;
; #pragma unroll
;                     for (int bj = 0; bj < 2; ++bj)
; #pragma unroll
;                         for (int n = 0; n < 2; ++n) { const f32x4 bv = *(const f32x4*)(bias + colg0 + bj * 128 + n * 16); *(f32x4*)(rowp + bj * 128 + n * 16) = acc[ai][bj][m][n] + bv; } } }
.LBB0_612:
	v_add_u32_e32 v114, s3, v132
	v_mov_b64_e32 v[112:113], s[80:81]
	v_mad_i64_i32 v[112:113], s[30:31], v114, s59, v[112:113]
	v_lshl_add_u64 v[116:117], v[160:161], 2, v[112:113]
	v_pk_add_f32 v[110:111], v[110:111], v[190:191]
	v_pk_add_f32 v[108:109], v[108:109], v[188:189]
	global_store_dwordx4 v[116:117], v[108:111], off
	v_pk_add_f32 v[106:107], v[106:107], v[194:195]
	v_pk_add_f32 v[104:105], v[104:105], v[192:193]
	global_store_dwordx4 v[116:117], v[104:107], off offset:64
	v_pk_add_f32 v[102:103], v[102:103], v[198:199]
	v_pk_add_f32 v[100:101], v[100:101], v[196:197]
	global_store_dwordx4 v[116:117], v[100:103], off offset:512
	v_pk_add_f32 v[98:99], v[98:99], v[202:203]
	v_pk_add_f32 v[96:97], v[96:97], v[200:201]
	global_store_dwordx4 v[116:117], v[96:99], off offset:576
	s_or_b64 exec, exec, s[28:29]
	s_and_saveexec_b64 s[28:29], s[8:9]
	s_cbranch_execnz .LBB0_606

;     __device__ __forceinline__ void operator()(const f32x4 (&acc)[2][2][4][2], const pg8::Unit& u, int wr, int wc, int fr, int fq) const {
;     ...
;                 if (row < NMR) { float* rowp = mod + ((size_t)l * NMR + row) * 9216 + col0;
; #pragma unroll
;                     for (int bj = 0; bj < 2; ++bj)
; #pragma unroll
;                         for (int n = 0; n < 2; ++n) { const f32x4 bv = *(const f32x4*)(bias + colg0 + bj * 128 + n * 16); *(f32x4*)(rowp + bj * 128 + n * 16) = acc[ai][bj][m][n] + bv; } } }
.LBB0_614:
	v_add_u32_e32 v82, s3, v136
	v_mov_b64_e32 v[80:81], s[80:81]
	v_mad_i64_i32 v[80:81], s[30:31], v82, s59, v[80:81]
	v_lshl_add_u64 v[84:85], v[160:161], 2, v[80:81]
	v_pk_add_f32 v[78:79], v[78:79], v[190:191]
	v_pk_add_f32 v[76:77], v[76:77], v[188:189]
	global_store_dwordx4 v[84:85], v[76:79], off
	v_pk_add_f32 v[74:75], v[74:75], v[194:195]
	v_pk_add_f32 v[72:73], v[72:73], v[192:193]
	global_store_dwordx4 v[84:85], v[72:75], off offset:64
	v_pk_add_f32 v[70:71], v[70:71], v[198:199]
	v_pk_add_f32 v[68:69], v[68:69], v[196:197]
	global_store_dwordx4 v[84:85], v[68:71], off offset:512
	v_pk_add_f32 v[66:67], v[66:67], v[202:203]
	v_pk_add_f32 v[64:65], v[64:65], v[200:201]
	global_store_dwordx4 v[84:85], v[64:67], off offset:576
	s_or_b64 exec, exec, s[28:29]
	s_and_saveexec_b64 s[28:29], s[12:13]
	s_cbranch_execnz .LBB0_608

;     __device__ __forceinline__ void operator()(const f32x4 (&acc)[2][2][4][2], const pg8::Unit& u, int wr, int wc, int fr, int fq) const {
;     ...
;                 if (row < NMR) { float* rowp = mod + ((size_t)l * NMR + row) * 9216 + col0;
; #pragma unroll
;                     for (int bj = 0; bj < 2; ++bj)
; #pragma unroll
;                         for (int n = 0; n < 2; ++n) { const f32x4 bv = *(const f32x4*)(bias + colg0 + bj * 128 + n * 16); *(f32x4*)(rowp + bj * 128 + n * 16) = acc[ai][bj][m][n] + bv; } } }
.LBB0_616:
	v_add_u32_e32 v50, s3, v140
	v_mov_b64_e32 v[48:49], s[80:81]
	v_mad_i64_i32 v[48:49], s[30:31], v50, s59, v[48:49]
	v_lshl_add_u64 v[52:53], v[160:161], 2, v[48:49]
	v_pk_add_f32 v[46:47], v[46:47], v[190:191]
	v_pk_add_f32 v[44:45], v[44:45], v[188:189]
	global_store_dwordx4 v[52:53], v[44:47], off
	v_pk_add_f32 v[42:43], v[42:43], v[194:195]
	v_pk_add_f32 v[40:41], v[40:41], v[192:193]
	global_store_dwordx4 v[52:53], v[40:43], off offset:64
	v_pk_add_f32 v[38:39], v[38:39], v[198:199]
	v_pk_add_f32 v[36:37], v[36:37], v[196:197]
	global_store_dwordx4 v[52:53], v[36:39], off offset:512
	v_pk_add_f32 v[34:35], v[34:35], v[202:203]
	v_pk_add_f32 v[32:33], v[32:33], v[200:201]
	global_store_dwordx4 v[52:53], v[32:35], off offset:576
	s_or_b64 exec, exec, s[28:29]
	s_and_saveexec_b64 s[28:29], s[16:17]
	s_cbranch_execnz .LBB0_610

;     __device__ __forceinline__ void operator()(const f32x4 (&acc)[2][2][4][2], const pg8::Unit& u, int wr, int wc, int fr, int fq) const {
;     ...
;                 if (row < NMR) { float* rowp = mod + ((size_t)l * NMR + row) * 9216 + col0;
; #pragma unroll
;                     for (int bj = 0; bj < 2; ++bj)
; #pragma unroll
;                         for (int n = 0; n < 2; ++n) { const f32x4 bv = *(const f32x4*)(bias + colg0 + bj * 128 + n * 16); *(f32x4*)(rowp + bj * 128 + n * 16) = acc[ai][bj][m][n] + bv; } } }
.LBB0_618:
	v_add_u32_e32 v18, s3, v152
	v_mov_b64_e32 v[16:17], s[80:81]
	v_mad_i64_i32 v[16:17], s[30:31], v18, s59, v[16:17]
	v_lshl_add_u64 v[20:21], v[160:161], 2, v[16:17]
	v_pk_add_f32 v[14:15], v[14:15], v[190:191]
	v_pk_add_f32 v[12:13], v[12:13], v[188:189]
	global_store_dwordx4 v[20:21], v[12:15], off
	v_pk_add_f32 v[10:11], v[10:11], v[194:195]
	v_pk_add_f32 v[8:9], v[8:9], v[192:193]
	global_store_dwordx4 v[20:21], v[8:11], off offset:64
	v_pk_add_f32 v[6:7], v[6:7], v[198:199]
	v_pk_add_f32 v[4:5], v[4:5], v[196:197]
	global_store_dwordx4 v[20:21], v[4:7], off offset:512
	v_pk_add_f32 v[2:3], v[2:3], v[202:203]
	v_pk_add_f32 v[0:1], v[0:1], v[200:201]
	global_store_dwordx4 v[20:21], v[0:3], off offset:576
	s_branch .LBB0_598
	s_nop 0
	s_nop 0
	s_nop 0
	s_nop 0
	s_nop 0
	s_nop 0
	s_nop 0
	s_nop 0
	s_nop 0
	s_nop 0
	s_nop 0
	s_nop 0
	s_nop 0
	s_nop 0
	s_nop 0
	s_nop 0
	s_nop 0
	s_nop 0
	s_nop 0
	s_nop 0
	s_nop 0
	s_nop 0
	s_nop 0

; #define PG8_STAGE(bufoff, gbase, voff) do { _Pragma("unroll") for (int _i = 0; _i < 2; ++_i) \
;         __builtin_amdgcn_global_load_lds((const unsigned*)((const char*)(gbase) + (voff)[_i]), (LAS unsigned*)(lds + (bufoff) + ldsw + _i * 8192), 16, 0, 0); } while (0)
; #define PG8_LDA(dst, b, h) do { _Pragma("unroll") for (int m = 0; m < 4; ++m) _Pragma("unroll") for (int k = 0; k < 2; ++k) dst[m][k] = *(const LAS bf16x8*)(lds + PG8_SA(b, h) + aoff + m * 2048 + k * 1024); } while (0)
; #define PG8_LDB(dst, b, h) do { _Pragma("unroll") for (int n = 0; n < 2; ++n) _Pragma("unroll") for (int k = 0; k < 2; ++k) dst[n][k] = *(const LAS bf16x8*)(lds + PG8_SB(b, h) + boff + n * 2048 + k * 1024); } while (0)
; #define PG8_MMA(ai, bj, At, Bt) do { __builtin_amdgcn_s_setprio(1); _Pragma("unroll") for (int m = 0; m < 4; ++m) _Pragma("unroll") for (int n = 0; n < 2; ++n) _Pragma("unroll") for (int k = 0; k < 2; ++k) \
;         acc[ai][bj][m][n] = __builtin_amdgcn_mfma_f32_16x16x32_bf16(Bt[n][k], At[m][k], acc[ai][bj][m][n], 0, 0, 0); __builtin_amdgcn_s_setprio(0); } while (0)
; #define PG8_WAIT_V(n) asm volatile("s_waitcnt vmcnt(" #n ")" ::: "memory")
; #define PG8_WAIT_L(n) asm volatile("s_waitcnt lgkmcnt(" #n ")" ::: "memory")
; #define PG8_BAR __builtin_amdgcn_s_barrier()
; #define PG8_SCHED __builtin_amdgcn_sched_barrier(0)
; template <class Epi, class Sched>
; __device__ __forceinline__ void gemm_phase(LAS unsigned char* lds, const Gemm g, const Sched& S, const Epi& E, const Ids I) {
;     ...
;             PG8_LDB(B0, 0, 0); PG8_SCHED; PG8_LDA(At, 0, 0); PG8_STAGE(PG8_SA(1, 1), a1 + hstep, voffA);
;             PG8_WAIT_L(8); PG8_BAR; PG8_WAIT_L(0); PG8_MMA(0, 0, At, B0); PG8_BAR; PG8_SCHED;
;             PG8_LDB(B1, 0, 1); PG8_STAGE(PG8_SB(0, 0), b2, voffB);
;             PG8_BAR; PG8_WAIT_L(0); PG8_MMA(0, 1, At, B1); PG8_BAR;
;             PG8_LDA(At, 0, 1); PG8_STAGE(PG8_SA(0, 0), a2, voffA);
;             PG8_BAR; PG8_WAIT_L(0); PG8_MMA(1, 0, At, B0); PG8_BAR; PG8_SCHED;
;             PG8_STAGE(PG8_SB(0, 1), b2 + hstep, voffB);
;             PG8_WAIT_V(6); PG8_BAR; PG8_MMA(1, 1, At, B1); PG8_BAR;
.LBB0_696:
	s_add_u32 s28, s26, 0xfffc0080
	s_addc_u32 s29, s27, -1
	s_add_i32 s49, 0, 0x10000
	v_add_u32_e32 v137, s49, v131
	ds_read_b128 v[158:161], v137
	ds_read_b128 v[162:165], v137 offset:1024
	ds_read_b128 v[166:169], v137 offset:2048
	ds_read_b128 v[170:173], v137 offset:3072
	s_cmp_eq_u32 s48, 12
	s_cselect_b32 s31, s3, s29
	s_cselect_b32 s30, s44, s28
	s_cselect_b32 s29, s1, s47
	s_cselect_b32 s28, s45, s46
	v_lshl_add_u64 v[176:177], s[26:27], 0, v[154:155]
	s_add_i32 m0, s36, 0xc000
	ds_read_b128 v[188:191], v135
	ds_read_b128 v[192:195], v135 offset:1024
	ds_read_b128 v[196:199], v135 offset:2048
	ds_read_b128 v[200:203], v135 offset:3072
	ds_read_b128 v[204:207], v135 offset:4096
	ds_read_b128 v[208:211], v135 offset:5120
	ds_read_b128 v[212:215], v135 offset:6144
	ds_read_b128 v[216:219], v135 offset:7168
	global_load_lds_dwordx4 v[176:177], off
	v_lshl_add_u64 v[176:177], s[26:27], 0, v[156:157]
	s_add_i32 m0, s36, 0xe000
	s_nop 0
	global_load_lds_dwordx4 v[176:177], off
	s_waitcnt lgkmcnt(8)
	s_barrier
	s_waitcnt lgkmcnt(0)
	s_setprio 1
	s_waitcnt lgkmcnt(0)
	v_mfma_f32_16x16x32_bf16 v[124:127], v[158:161], v[188:191], v[124:127]
	v_mfma_f32_16x16x32_bf16 v[120:123], v[166:169], v[188:191], v[120:123]
	v_mfma_f32_16x16x32_bf16 v[108:111], v[158:161], v[196:199], v[108:111]
	v_mfma_f32_16x16x32_bf16 v[104:107], v[166:169], v[196:199], v[104:107]
	v_mfma_f32_16x16x32_bf16 v[92:95], v[158:161], v[204:207], v[92:95]
	v_mfma_f32_16x16x32_bf16 v[88:91], v[166:169], v[204:207], v[88:91]
	v_mfma_f32_16x16x32_bf16 v[76:79], v[158:161], v[212:215], v[76:79]
	v_mfma_f32_16x16x32_bf16 v[72:75], v[166:169], v[212:215], v[72:75]
	v_mfma_f32_16x16x32_bf16 v[124:127], v[162:165], v[192:195], v[124:127]
	v_mfma_f32_16x16x32_bf16 v[120:123], v[170:173], v[192:195], v[120:123]
	v_mfma_f32_16x16x32_bf16 v[108:111], v[162:165], v[200:203], v[108:111]
	v_mfma_f32_16x16x32_bf16 v[104:107], v[170:173], v[200:203], v[104:107]
	v_mfma_f32_16x16x32_bf16 v[92:95], v[162:165], v[208:211], v[92:95]
	v_mfma_f32_16x16x32_bf16 v[88:91], v[170:173], v[208:211], v[88:91]
	v_mfma_f32_16x16x32_bf16 v[76:79], v[162:165], v[216:219], v[76:79]
	v_mfma_f32_16x16x32_bf16 v[72:75], v[170:173], v[216:219], v[72:75]
	s_setprio 0
	s_barrier
	s_add_i32 s52, 0, 0x14000
	s_add_i32 s49, s49, s35
	v_add_u32_e32 v137, s52, v131
	v_lshl_add_u64 v[176:177], s[28:29], 0, v[144:145]
	s_mov_b32 m0, s49
	ds_read_b128 v[220:223], v137
	ds_read_b128 v[224:227], v137 offset:1024
	ds_read_b128 v[228:231], v137 offset:2048
	ds_read_b128 v[232:235], v137 offset:3072
	global_load_lds_dwordx4 v[176:177], off
	v_lshl_add_u64 v[178:179], s[28:29], 0, v[128:129]
	s_add_i32 m0, s49, 0x2000
	s_nop 0
	global_load_lds_dwordx4 v[178:179], off
	s_barrier
	s_waitcnt lgkmcnt(0)
	s_setprio 1
	s_waitcnt lgkmcnt(0)
	v_mfma_f32_16x16x32_bf16 v[116:119], v[220:223], v[188:191], v[116:119]
	v_mfma_f32_16x16x32_bf16 v[112:115], v[228:231], v[188:191], v[112:115]
	v_mfma_f32_16x16x32_bf16 v[100:103], v[220:223], v[196:199], v[100:103]
	v_mfma_f32_16x16x32_bf16 v[96:99], v[228:231], v[196:199], v[96:99]
	v_mfma_f32_16x16x32_bf16 v[84:87], v[220:223], v[204:207], v[84:87]
	v_mfma_f32_16x16x32_bf16 v[80:83], v[228:231], v[204:207], v[80:83]
	v_mfma_f32_16x16x32_bf16 v[68:71], v[220:223], v[212:215], v[68:71]
	v_mfma_f32_16x16x32_bf16 v[64:67], v[228:231], v[212:215], v[64:67]
	v_mfma_f32_16x16x32_bf16 v[116:119], v[224:227], v[192:195], v[116:119]
	v_mfma_f32_16x16x32_bf16 v[112:115], v[232:235], v[192:195], v[112:115]
	v_mfma_f32_16x16x32_bf16 v[100:103], v[224:227], v[200:203], v[100:103]
	v_mfma_f32_16x16x32_bf16 v[96:99], v[232:235], v[200:203], v[96:99]
	v_mfma_f32_16x16x32_bf16 v[84:87], v[224:227], v[208:211], v[84:87]
	v_mfma_f32_16x16x32_bf16 v[80:83], v[232:235], v[208:211], v[80:83]
	v_mfma_f32_16x16x32_bf16 v[68:71], v[224:227], v[216:219], v[68:71]
	v_mfma_f32_16x16x32_bf16 v[64:67], v[232:235], v[216:219], v[64:67]
	s_setprio 0
	s_mov_b32 m0, s36
	v_lshl_add_u64 v[180:181], s[30:31], 0, v[144:145]
	s_barrier
	ds_read_b128 v[188:191], v135 offset:16384
	ds_read_b128 v[192:195], v135 offset:17408
	ds_read_b128 v[196:199], v135 offset:18432
	ds_read_b128 v[200:203], v135 offset:19456
	ds_read_b128 v[204:207], v135 offset:20480
	ds_read_b128 v[208:211], v135 offset:21504
	ds_read_b128 v[212:215], v135 offset:22528
	ds_read_b128 v[216:219], v135 offset:23552
	global_load_lds_dwordx4 v[180:181], off
	v_lshl_add_u64 v[182:183], s[30:31], 0, v[128:129]
	s_mov_b32 m0, s37
	s_nop 0
	global_load_lds_dwordx4 v[182:183], off
	s_barrier
	s_waitcnt lgkmcnt(0)
	s_setprio 1
	s_waitcnt lgkmcnt(0)
	v_mfma_f32_16x16x32_bf16 v[60:63], v[158:161], v[188:191], v[60:63]
	v_mfma_f32_16x16x32_bf16 v[56:59], v[166:169], v[188:191], v[56:59]
	v_mfma_f32_16x16x32_bf16 v[44:47], v[158:161], v[196:199], v[44:47]
	v_mfma_f32_16x16x32_bf16 v[40:43], v[166:169], v[196:199], v[40:43]
	v_mfma_f32_16x16x32_bf16 v[28:31], v[158:161], v[204:207], v[28:31]
	v_mfma_f32_16x16x32_bf16 v[24:27], v[166:169], v[204:207], v[24:27]
	v_mfma_f32_16x16x32_bf16 v[12:15], v[158:161], v[212:215], v[12:15]
	v_mfma_f32_16x16x32_bf16 v[8:11], v[166:169], v[212:215], v[8:11]
	v_mfma_f32_16x16x32_bf16 v[60:63], v[162:165], v[192:195], v[60:63]
	v_mfma_f32_16x16x32_bf16 v[56:59], v[170:173], v[192:195], v[56:59]
	v_mfma_f32_16x16x32_bf16 v[44:47], v[162:165], v[200:203], v[44:47]
	v_mfma_f32_16x16x32_bf16 v[40:43], v[170:173], v[200:203], v[40:43]
	v_mfma_f32_16x16x32_bf16 v[28:31], v[162:165], v[208:211], v[28:31]
	v_mfma_f32_16x16x32_bf16 v[24:27], v[170:173], v[208:211], v[24:27]
	v_mfma_f32_16x16x32_bf16 v[12:15], v[162:165], v[216:219], v[12:15]
	v_mfma_f32_16x16x32_bf16 v[8:11], v[170:173], v[216:219], v[8:11]
	s_setprio 0
	s_barrier
; #define PG8_STAGE(bufoff, gbase, voff) do { _Pragma("unroll") for (int _i = 0; _i < 2; ++_i) \
;         __builtin_amdgcn_global_load_lds((const unsigned*)((const char*)(gbase) + (voff)[_i]), (LAS unsigned*)(lds + (bufoff) + ldsw + _i * 8192), 16, 0, 0); } while (0)
; #define PG8_LDA(dst, b, h) do { _Pragma("unroll") for (int m = 0; m < 4; ++m) _Pragma("unroll") for (int k = 0; k < 2; ++k) dst[m][k] = *(const LAS bf16x8*)(lds + PG8_SA(b, h) + aoff + m * 2048 + k * 1024); } while (0)
; #define PG8_LDB(dst, b, h) do { _Pragma("unroll") for (int n = 0; n < 2; ++n) _Pragma("unroll") for (int k = 0; k < 2; ++k) dst[n][k] = *(const LAS bf16x8*)(lds + PG8_SB(b, h) + boff + n * 2048 + k * 1024); } while (0)
; #define PG8_MMA(ai, bj, At, Bt) do { __builtin_amdgcn_s_setprio(1); _Pragma("unroll") for (int m = 0; m < 4; ++m) _Pragma("unroll") for (int n = 0; n < 2; ++n) _Pragma("unroll") for (int k = 0; k < 2; ++k) \
;         acc[ai][bj][m][n] = __builtin_amdgcn_mfma_f32_16x16x32_bf16(Bt[n][k], At[m][k], acc[ai][bj][m][n], 0, 0, 0); __builtin_amdgcn_s_setprio(0); } while (0)
; #define PG8_WAIT_V(n) asm volatile("s_waitcnt vmcnt(" #n ")" ::: "memory")
; #define PG8_WAIT_L(n) asm volatile("s_waitcnt lgkmcnt(" #n ")" ::: "memory")
; #define PG8_BAR __builtin_amdgcn_s_barrier()
; #define PG8_SCHED __builtin_amdgcn_sched_barrier(0)
; template <class Epi, class Sched>
; __device__ __forceinline__ void gemm_phase(LAS unsigned char* lds, const Gemm g, const Sched& S, const Epi& E, const Ids I) {
;     ...
;             PG8_LDB(B0, 1, 0); PG8_SCHED; PG8_LDA(At, 1, 0); PG8_STAGE(PG8_SA(0, 1), a2 + hstep, voffA);
;             PG8_WAIT_L(8); PG8_BAR; PG8_WAIT_L(0); PG8_MMA(0, 0, At, B0); PG8_BAR; PG8_SCHED;
;             PG8_LDB(B1, 1, 1); PG8_STAGE(PG8_SB(1, 0), b3, voffB);
;             PG8_BAR; PG8_WAIT_L(0); PG8_MMA(0, 1, At, B1); PG8_BAR;
;             PG8_LDA(At, 1, 1); PG8_STAGE(PG8_SA(1, 0), a3, voffA);
;             PG8_BAR; PG8_WAIT_L(0); PG8_MMA(1, 0, At, B0); PG8_BAR; PG8_SCHED;
;             PG8_STAGE(PG8_SB(1, 1), b3 + hstep, voffB);
;             PG8_WAIT_V(6); PG8_BAR; PG8_MMA(1, 1, At, B1); PG8_BAR;
	s_add_u32 s50, s28, 0x40000
	s_addc_u32 s51, s29, 0
	s_add_i32 s49, s52, s35
	v_lshl_add_u64 v[158:159], s[50:51], 0, v[144:145]
	s_mov_b32 m0, s49
	s_nop 0
	global_load_lds_dwordx4 v[158:159], off
	v_lshl_add_u64 v[158:159], s[50:51], 0, v[128:129]
	s_add_i32 m0, s49, 0x2000
	s_nop 0
	global_load_lds_dwordx4 v[158:159], off
	s_waitcnt vmcnt(6)
	s_barrier
	s_setprio 1
	v_mfma_f32_16x16x32_bf16 v[52:55], v[220:223], v[188:191], v[52:55]
	v_mfma_f32_16x16x32_bf16 v[48:51], v[228:231], v[188:191], v[48:51]
	v_mfma_f32_16x16x32_bf16 v[36:39], v[220:223], v[196:199], v[36:39]
	v_mfma_f32_16x16x32_bf16 v[32:35], v[228:231], v[196:199], v[32:35]
	v_mfma_f32_16x16x32_bf16 v[20:23], v[220:223], v[204:207], v[20:23]
	v_mfma_f32_16x16x32_bf16 v[16:19], v[228:231], v[204:207], v[16:19]
	v_mfma_f32_16x16x32_bf16 v[4:7], v[220:223], v[212:215], v[4:7]
	v_mfma_f32_16x16x32_bf16 v[0:3], v[228:231], v[212:215], v[0:3]
	v_mfma_f32_16x16x32_bf16 v[52:55], v[224:227], v[192:195], v[52:55]
	v_mfma_f32_16x16x32_bf16 v[48:51], v[232:235], v[192:195], v[48:51]
	v_mfma_f32_16x16x32_bf16 v[36:39], v[224:227], v[200:203], v[36:39]
	v_mfma_f32_16x16x32_bf16 v[32:35], v[232:235], v[200:203], v[32:35]
	v_mfma_f32_16x16x32_bf16 v[20:23], v[224:227], v[208:211], v[20:23]
	v_mfma_f32_16x16x32_bf16 v[16:19], v[232:235], v[208:211], v[16:19]
	v_mfma_f32_16x16x32_bf16 v[4:7], v[224:227], v[216:219], v[4:7]
	v_mfma_f32_16x16x32_bf16 v[0:3], v[232:235], v[216:219], v[0:3]
	s_setprio 0
	s_add_i32 s49, 0, 0x18000
	v_add_u32_e32 v137, s49, v131
	s_barrier
	ds_read_b128 v[158:161], v137
	ds_read_b128 v[162:165], v137 offset:1024
	ds_read_b128 v[166:169], v137 offset:2048
	ds_read_b128 v[170:173], v137 offset:3072
	s_add_u32 s30, s30, 0x40000
	s_addc_u32 s31, s31, 0
	s_mov_b32 m0, s38
	v_lshl_add_u64 v[220:221], s[30:31], 0, v[144:145]
	ds_read_b128 v[188:191], v135 offset:32768
	ds_read_b128 v[192:195], v135 offset:33792
	ds_read_b128 v[196:199], v135 offset:34816
	ds_read_b128 v[200:203], v135 offset:35840
	ds_read_b128 v[204:207], v135 offset:36864
	ds_read_b128 v[208:211], v135 offset:37888
	ds_read_b128 v[212:215], v135 offset:38912
	ds_read_b128 v[216:219], v135 offset:39936
	global_load_lds_dwordx4 v[220:221], off
	v_lshl_add_u64 v[220:221], s[30:31], 0, v[128:129]
	s_mov_b32 m0, s39
	s_nop 0
	global_load_lds_dwordx4 v[220:221], off
	s_waitcnt lgkmcnt(8)
	s_barrier
	s_waitcnt lgkmcnt(0)
	s_setprio 1
	s_waitcnt lgkmcnt(0)
	v_mfma_f32_16x16x32_bf16 v[124:127], v[158:161], v[188:191], v[124:127]
	v_mfma_f32_16x16x32_bf16 v[120:123], v[166:169], v[188:191], v[120:123]
	v_mfma_f32_16x16x32_bf16 v[108:111], v[158:161], v[196:199], v[108:111]
	v_mfma_f32_16x16x32_bf16 v[104:107], v[166:169], v[196:199], v[104:107]
	v_mfma_f32_16x16x32_bf16 v[92:95], v[158:161], v[204:207], v[92:95]
	v_mfma_f32_16x16x32_bf16 v[88:91], v[166:169], v[204:207], v[88:91]
	v_mfma_f32_16x16x32_bf16 v[76:79], v[158:161], v[212:215], v[76:79]
	v_mfma_f32_16x16x32_bf16 v[72:75], v[166:169], v[212:215], v[72:75]
	v_mfma_f32_16x16x32_bf16 v[124:127], v[162:165], v[192:195], v[124:127]
	v_mfma_f32_16x16x32_bf16 v[120:123], v[170:173], v[192:195], v[120:123]
	v_mfma_f32_16x16x32_bf16 v[108:111], v[162:165], v[200:203], v[108:111]
	v_mfma_f32_16x16x32_bf16 v[104:107], v[170:173], v[200:203], v[104:107]
	v_mfma_f32_16x16x32_bf16 v[92:95], v[162:165], v[208:211], v[92:95]
	v_mfma_f32_16x16x32_bf16 v[88:91], v[170:173], v[208:211], v[88:91]
	v_mfma_f32_16x16x32_bf16 v[76:79], v[162:165], v[216:219], v[76:79]
	v_mfma_f32_16x16x32_bf16 v[72:75], v[170:173], v[216:219], v[72:75]
	s_setprio 0
	s_barrier
	s_add_i32 s30, 0, 0x1c000
	s_add_i32 s31, s49, s35
	v_add_u32_e32 v137, s30, v131
	v_lshl_add_u64 v[176:177], v[176:177], 0, s[64:65]
	s_mov_b32 m0, s31
	ds_read_b128 v[220:223], v137
	ds_read_b128 v[224:227], v137 offset:1024
	ds_read_b128 v[228:231], v137 offset:2048
	ds_read_b128 v[232:235], v137 offset:3072
	global_load_lds_dwordx4 v[176:177], off
	v_lshl_add_u64 v[176:177], v[178:179], 0, s[64:65]
	s_add_i32 m0, s31, 0x2000
	s_nop 0
	global_load_lds_dwordx4 v[176:177], off
	s_barrier
	s_waitcnt lgkmcnt(0)
	s_setprio 1
	s_waitcnt lgkmcnt(0)
	v_mfma_f32_16x16x32_bf16 v[116:119], v[220:223], v[188:191], v[116:119]
	v_mfma_f32_16x16x32_bf16 v[112:115], v[228:231], v[188:191], v[112:115]
	v_mfma_f32_16x16x32_bf16 v[100:103], v[220:223], v[196:199], v[100:103]
	v_mfma_f32_16x16x32_bf16 v[96:99], v[228:231], v[196:199], v[96:99]
	v_mfma_f32_16x16x32_bf16 v[84:87], v[220:223], v[204:207], v[84:87]
	v_mfma_f32_16x16x32_bf16 v[80:83], v[228:231], v[204:207], v[80:83]
	v_mfma_f32_16x16x32_bf16 v[68:71], v[220:223], v[212:215], v[68:71]
	v_mfma_f32_16x16x32_bf16 v[64:67], v[228:231], v[212:215], v[64:67]
	v_mfma_f32_16x16x32_bf16 v[116:119], v[224:227], v[192:195], v[116:119]
	v_mfma_f32_16x16x32_bf16 v[112:115], v[232:235], v[192:195], v[112:115]
	v_mfma_f32_16x16x32_bf16 v[100:103], v[224:227], v[200:203], v[100:103]
	v_mfma_f32_16x16x32_bf16 v[96:99], v[232:235], v[200:203], v[96:99]
	v_mfma_f32_16x16x32_bf16 v[84:87], v[224:227], v[208:211], v[84:87]
	v_mfma_f32_16x16x32_bf16 v[80:83], v[232:235], v[208:211], v[80:83]
	v_mfma_f32_16x16x32_bf16 v[68:71], v[224:227], v[216:219], v[68:71]
	v_mfma_f32_16x16x32_bf16 v[64:67], v[232:235], v[216:219], v[64:67]
	s_setprio 0
	s_mov_b32 m0, s40
	v_lshl_add_u64 v[176:177], v[180:181], 0, s[64:65]
	s_barrier
; #define PG8_MMA(ai, bj, At, Bt) do { __builtin_amdgcn_s_setprio(1); _Pragma("unroll") for (int m = 0; m < 4; ++m) _Pragma("unroll") for (int n = 0; n < 2; ++n) _Pragma("unroll") for (int k = 0; k < 2; ++k) \
;         acc[ai][bj][m][n] = __builtin_amdgcn_mfma_f32_16x16x32_bf16(Bt[n][k], At[m][k], acc[ai][bj][m][n], 0, 0, 0); __builtin_amdgcn_s_setprio(0); } while (0)
; #define PG8_WAIT_V(n) asm volatile("s_waitcnt vmcnt(" #n ")" ::: "memory")
; #define PG8_BAR __builtin_amdgcn_s_barrier()
; template <class Epi, class Sched>
; __device__ __forceinline__ void gemm_phase(LAS unsigned char* lds, const Gemm g, const Sched& S, const Epi& E, const Ids I) {
;     ...
;             PG8_WAIT_V(6); PG8_BAR; PG8_MMA(1, 1, At, B1); PG8_BAR;
;         }
;         E(acc, cur, wr, wc, fr, fq);
;     __device__ __forceinline__ void operator()(const f32x4 (&acc)[2][2][4][2], const pg8::Unit& u, int wr, int wc, int fr, int fq) const {
;         const int row0 = wr * 64 + fr, colg0 = u.pn * 256 + wc * 32 + 4 * fq; const int l = (u.pn >= 36) ? 1 : 0; const int col0 = colg0 - l * 9216;
; #pragma unroll
;         for (int ai = 0; ai < 2; ++ai)
; #pragma unroll
;             for (int m = 0; m < 4; ++m) { const int row = row0 + ai * 128 + m * 16;
;                 if (row < NMR) { float* rowp = mod + ((size_t)l * NMR + row) * 9216 + col0;
; #pragma unroll
;                     for (int bj = 0; bj < 2; ++bj)
; #pragma unroll
;                         for (int n = 0; n < 2; ++n) { const f32x4 bv = *(const f32x4*)(bias + colg0 + bj * 128 + n * 16); *(f32x4*)(rowp + bj * 128 + n * 16) = acc[ai][bj][m][n] + bv; } } }
	ds_read_b128 v[188:191], v135 offset:49152
	ds_read_b128 v[192:195], v135 offset:50176
	ds_read_b128 v[196:199], v135 offset:51200
	ds_read_b128 v[200:203], v135 offset:52224
	ds_read_b128 v[204:207], v135 offset:53248
	ds_read_b128 v[208:211], v135 offset:54272
	ds_read_b128 v[212:215], v135 offset:55296
	ds_read_b128 v[216:219], v135 offset:56320
	global_load_lds_dwordx4 v[176:177], off
	v_lshl_add_u64 v[176:177], v[182:183], 0, s[64:65]
	s_mov_b32 m0, s41
	s_nop 0
	global_load_lds_dwordx4 v[176:177], off
	s_barrier
	s_waitcnt lgkmcnt(0)
	s_setprio 1
	s_waitcnt lgkmcnt(0)
	v_mfma_f32_16x16x32_bf16 v[60:63], v[158:161], v[188:191], v[60:63]
	v_mfma_f32_16x16x32_bf16 v[56:59], v[166:169], v[188:191], v[56:59]
	v_mfma_f32_16x16x32_bf16 v[44:47], v[158:161], v[196:199], v[44:47]
	v_mfma_f32_16x16x32_bf16 v[40:43], v[166:169], v[196:199], v[40:43]
	v_mfma_f32_16x16x32_bf16 v[28:31], v[158:161], v[204:207], v[28:31]
	v_mfma_f32_16x16x32_bf16 v[24:27], v[166:169], v[204:207], v[24:27]
	v_mfma_f32_16x16x32_bf16 v[12:15], v[158:161], v[212:215], v[12:15]
	v_mfma_f32_16x16x32_bf16 v[8:11], v[166:169], v[212:215], v[8:11]
	v_mfma_f32_16x16x32_bf16 v[60:63], v[162:165], v[192:195], v[60:63]
	v_mfma_f32_16x16x32_bf16 v[56:59], v[170:173], v[192:195], v[56:59]
	v_mfma_f32_16x16x32_bf16 v[44:47], v[162:165], v[200:203], v[44:47]
	v_mfma_f32_16x16x32_bf16 v[40:43], v[170:173], v[200:203], v[40:43]
	v_mfma_f32_16x16x32_bf16 v[28:31], v[162:165], v[208:211], v[28:31]
	v_mfma_f32_16x16x32_bf16 v[24:27], v[170:173], v[208:211], v[24:27]
	v_mfma_f32_16x16x32_bf16 v[12:15], v[162:165], v[216:219], v[12:15]
	v_mfma_f32_16x16x32_bf16 v[8:11], v[170:173], v[216:219], v[8:11]
	s_setprio 0
	s_barrier
	s_add_u32 s28, s28, 0x40080
	s_addc_u32 s29, s29, 0
	s_add_i32 s30, s30, s35
	v_lshl_add_u64 v[158:159], s[28:29], 0, v[144:145]
	s_mov_b32 m0, s30
	s_nop 0
	global_load_lds_dwordx4 v[158:159], off
	v_lshl_add_u64 v[158:159], s[28:29], 0, v[128:129]
	s_add_i32 m0, s30, 0x2000
	s_nop 0
	global_load_lds_dwordx4 v[158:159], off
	s_waitcnt vmcnt(6)
	s_barrier
	s_setprio 1
	v_mfma_f32_16x16x32_bf16 v[52:55], v[220:223], v[188:191], v[52:55]
	v_mfma_f32_16x16x32_bf16 v[48:51], v[228:231], v[188:191], v[48:51]
	v_mfma_f32_16x16x32_bf16 v[36:39], v[220:223], v[196:199], v[36:39]
	v_mfma_f32_16x16x32_bf16 v[32:35], v[228:231], v[196:199], v[32:35]
	v_mfma_f32_16x16x32_bf16 v[20:23], v[220:223], v[204:207], v[20:23]
	v_mfma_f32_16x16x32_bf16 v[16:19], v[228:231], v[204:207], v[16:19]
	v_mfma_f32_16x16x32_bf16 v[4:7], v[220:223], v[212:215], v[4:7]
	v_mfma_f32_16x16x32_bf16 v[0:3], v[228:231], v[212:215], v[0:3]
	v_mfma_f32_16x16x32_bf16 v[52:55], v[224:227], v[192:195], v[52:55]
	v_mfma_f32_16x16x32_bf16 v[48:51], v[232:235], v[192:195], v[48:51]
	v_mfma_f32_16x16x32_bf16 v[36:39], v[224:227], v[200:203], v[36:39]
	v_mfma_f32_16x16x32_bf16 v[32:35], v[232:235], v[200:203], v[32:35]
	v_mfma_f32_16x16x32_bf16 v[20:23], v[224:227], v[208:211], v[20:23]
	v_mfma_f32_16x16x32_bf16 v[16:19], v[232:235], v[208:211], v[16:19]
	v_mfma_f32_16x16x32_bf16 v[4:7], v[224:227], v[216:219], v[4:7]
	v_mfma_f32_16x16x32_bf16 v[0:3], v[232:235], v[216:219], v[0:3]
	s_setprio 0
	s_add_i32 s48, s48, 2
	s_add_u32 s26, s26, 0x100
	s_addc_u32 s27, s27, 0
	s_add_u32 s46, s46, 0x100
	s_addc_u32 s47, s47, 0
	s_cmp_gt_u32 s48, 13
	s_barrier
	s_cbranch_scc0 .LBB0_696
	s_load_dwordx2 s[26:27], s[88:89], 0x48
	s_cmp_gt_i32 s43, 35
	v_lshl_or_b32 v158, s43, 8, v133
	s_cselect_b32 s1, 0xffffdc00, 0
	v_add_u32_e32 v160, s1, v158
	v_ashrrev_i32_e32 v159, 31, v158
	s_cselect_b32 s1, 0x88, 0
	v_ashrrev_i32_e32 v161, 31, v160
	s_waitcnt lgkmcnt(0)
	v_lshl_add_u64 v[158:159], v[158:159], 2, s[26:27]
	global_load_dwordx4 v[188:191], v[158:159], off
	global_load_dwordx4 v[192:195], v[158:159], off offset:64
	global_load_dwordx4 v[196:199], v[158:159], off offset:512
	global_load_dwordx4 v[200:203], v[158:159], off offset:576
	s_waitcnt vmcnt(0)
	s_and_saveexec_b64 s[26:27], s[4:5]
	s_cbranch_execz .LBB0_705
	v_add_u32_e32 v137, s1, v130
	v_mov_b64_e32 v[162:163], s[80:81]
	v_mad_i64_i32 v[162:163], s[28:29], v137, s59, v[162:163]
	v_lshl_add_u64 v[166:167], v[160:161], 2, v[162:163]
	v_pk_add_f32 v[126:127], v[126:127], v[190:191]
	v_pk_add_f32 v[124:125], v[124:125], v[188:189]
	global_store_dwordx4 v[166:167], v[124:127], off
	v_pk_add_f32 v[122:123], v[122:123], v[194:195]
	v_pk_add_f32 v[120:121], v[120:121], v[192:193]
	global_store_dwordx4 v[166:167], v[120:123], off offset:64
	v_pk_add_f32 v[118:119], v[118:119], v[198:199]
	v_pk_add_f32 v[116:117], v[116:117], v[196:197]
	global_store_dwordx4 v[166:167], v[116:119], off offset:512
	v_pk_add_f32 v[114:115], v[114:115], v[202:203]
	v_pk_add_f32 v[112:113], v[112:113], v[200:201]
	global_store_dwordx4 v[166:167], v[112:115], off offset:576
	s_or_b64 exec, exec, s[26:27]
	s_and_saveexec_b64 s[26:27], s[6:7]
	s_cbranch_execnz .LBB0_706

;     __device__ __forceinline__ void operator()(const f32x4 (&acc)[2][2][4][2], const pg8::Unit& u, int wr, int wc, int fr, int fq) const {
;     ...
;                 if (row < NMR) { float* rowp = mod + ((size_t)l * NMR + row) * 9216 + col0;
; #pragma unroll
;                     for (int bj = 0; bj < 2; ++bj)
; #pragma unroll
;                         for (int n = 0; n < 2; ++n) { const f32x4 bv = *(const f32x4*)(bias + colg0 + bj * 128 + n * 16); *(f32x4*)(rowp + bj * 128 + n * 16) = acc[ai][bj][m][n] + bv; } } }
.LBB0_700:
	v_add_u32_e32 v98, s1, v134
	v_mov_b64_e32 v[96:97], s[80:81]
	v_mad_i64_i32 v[96:97], s[28:29], v98, s59, v[96:97]
	v_lshl_add_u64 v[100:101], v[160:161], 2, v[96:97]
	v_pk_add_f32 v[94:95], v[94:95], v[190:191]
	v_pk_add_f32 v[92:93], v[92:93], v[188:189]
	global_store_dwordx4 v[100:101], v[92:95], off
	v_pk_add_f32 v[90:91], v[90:91], v[194:195]
	v_pk_add_f32 v[88:89], v[88:89], v[192:193]
	global_store_dwordx4 v[100:101], v[88:91], off offset:64
	v_pk_add_f32 v[86:87], v[86:87], v[198:199]
	v_pk_add_f32 v[84:85], v[84:85], v[196:197]
	global_store_dwordx4 v[100:101], v[84:87], off offset:512
	v_pk_add_f32 v[82:83], v[82:83], v[202:203]
	v_pk_add_f32 v[80:81], v[80:81], v[200:201]
	global_store_dwordx4 v[100:101], v[80:83], off offset:576
	s_or_b64 exec, exec, s[26:27]
	s_and_saveexec_b64 s[26:27], s[10:11]
	s_cbranch_execnz .LBB0_708

;     __device__ __forceinline__ void operator()(const f32x4 (&acc)[2][2][4][2], const pg8::Unit& u, int wr, int wc, int fr, int fq) const {
;     ...
;                 if (row < NMR) { float* rowp = mod + ((size_t)l * NMR + row) * 9216 + col0;
; #pragma unroll
;                     for (int bj = 0; bj < 2; ++bj)
; #pragma unroll
;                         for (int n = 0; n < 2; ++n) { const f32x4 bv = *(const f32x4*)(bias + colg0 + bj * 128 + n * 16); *(f32x4*)(rowp + bj * 128 + n * 16) = acc[ai][bj][m][n] + bv; } } }
.LBB0_702:
	v_add_u32_e32 v66, s1, v138
	v_mov_b64_e32 v[64:65], s[80:81]
	v_mad_i64_i32 v[64:65], s[28:29], v66, s59, v[64:65]
	v_lshl_add_u64 v[68:69], v[160:161], 2, v[64:65]
	v_pk_add_f32 v[62:63], v[62:63], v[190:191]
	v_pk_add_f32 v[60:61], v[60:61], v[188:189]
	global_store_dwordx4 v[68:69], v[60:63], off
	v_pk_add_f32 v[58:59], v[58:59], v[194:195]
	v_pk_add_f32 v[56:57], v[56:57], v[192:193]
	global_store_dwordx4 v[68:69], v[56:59], off offset:64
	v_pk_add_f32 v[54:55], v[54:55], v[198:199]
	v_pk_add_f32 v[52:53], v[52:53], v[196:197]
	global_store_dwordx4 v[68:69], v[52:55], off offset:512
	v_pk_add_f32 v[50:51], v[50:51], v[202:203]
	v_pk_add_f32 v[48:49], v[48:49], v[200:201]
	global_store_dwordx4 v[68:69], v[48:51], off offset:576
	s_or_b64 exec, exec, s[26:27]
	s_and_saveexec_b64 s[26:27], s[14:15]
	s_cbranch_execnz .LBB0_710

;     __device__ __forceinline__ void operator()(const f32x4 (&acc)[2][2][4][2], const pg8::Unit& u, int wr, int wc, int fr, int fq) const {
;     ...
;                 if (row < NMR) { float* rowp = mod + ((size_t)l * NMR + row) * 9216 + col0;
; #pragma unroll
;                     for (int bj = 0; bj < 2; ++bj)
; #pragma unroll
;                         for (int n = 0; n < 2; ++n) { const f32x4 bv = *(const f32x4*)(bias + colg0 + bj * 128 + n * 16); *(f32x4*)(rowp + bj * 128 + n * 16) = acc[ai][bj][m][n] + bv; } } }
.LBB0_704:
	v_add_u32_e32 v34, s1, v142
	v_mov_b64_e32 v[32:33], s[80:81]
	v_mad_i64_i32 v[32:33], s[28:29], v34, s59, v[32:33]
	v_lshl_add_u64 v[36:37], v[160:161], 2, v[32:33]
	v_pk_add_f32 v[30:31], v[30:31], v[190:191]
	v_pk_add_f32 v[28:29], v[28:29], v[188:189]
	global_store_dwordx4 v[36:37], v[28:31], off
	v_pk_add_f32 v[26:27], v[26:27], v[194:195]
	v_pk_add_f32 v[24:25], v[24:25], v[192:193]
	global_store_dwordx4 v[36:37], v[24:27], off offset:64
	v_pk_add_f32 v[22:23], v[22:23], v[198:199]
	v_pk_add_f32 v[20:21], v[20:21], v[196:197]
	global_store_dwordx4 v[36:37], v[20:23], off offset:512
	v_pk_add_f32 v[18:19], v[18:19], v[202:203]
	v_pk_add_f32 v[16:17], v[16:17], v[200:201]
	global_store_dwordx4 v[36:37], v[16:19], off offset:576
	s_or_b64 exec, exec, s[26:27]
	s_and_saveexec_b64 s[26:27], s[18:19]
	s_cbranch_execz .LBB0_692
	s_branch .LBB0_712
	s_nop 0
	s_nop 0
	s_nop 0
	s_nop 0
	s_nop 0
	s_nop 0
	s_nop 0
	s_nop 0
	s_nop 0
	s_nop 0
	s_nop 0
	s_nop 0
	s_nop 0
	s_nop 0
	s_nop 0
	s_nop 0
	s_nop 0
	s_nop 0
	s_nop 0
	s_nop 0
	s_nop 0
	s_nop 0
	s_nop 0

;     __device__ __forceinline__ void operator()(const f32x4 (&acc)[2][2][4][2], const pg8::Unit& u, int wr, int wc, int fr, int fq) const {
;     ...
;                 if (row < NMR) { float* rowp = mod + ((size_t)l * NMR + row) * 9216 + col0;
; #pragma unroll
;                     for (int bj = 0; bj < 2; ++bj)
; #pragma unroll
;                         for (int n = 0; n < 2; ++n) { const f32x4 bv = *(const f32x4*)(bias + colg0 + bj * 128 + n * 16); *(f32x4*)(rowp + bj * 128 + n * 16) = acc[ai][bj][m][n] + bv; } } }
.LBB0_706:
	v_add_u32_e32 v114, s1, v132
	v_mov_b64_e32 v[112:113], s[80:81]
	v_mad_i64_i32 v[112:113], s[28:29], v114, s59, v[112:113]
	v_lshl_add_u64 v[116:117], v[160:161], 2, v[112:113]
	v_pk_add_f32 v[110:111], v[110:111], v[190:191]
	v_pk_add_f32 v[108:109], v[108:109], v[188:189]
	global_store_dwordx4 v[116:117], v[108:111], off
	v_pk_add_f32 v[106:107], v[106:107], v[194:195]
	v_pk_add_f32 v[104:105], v[104:105], v[192:193]
	global_store_dwordx4 v[116:117], v[104:107], off offset:64
	v_pk_add_f32 v[102:103], v[102:103], v[198:199]
	v_pk_add_f32 v[100:101], v[100:101], v[196:197]
	global_store_dwordx4 v[116:117], v[100:103], off offset:512
	v_pk_add_f32 v[98:99], v[98:99], v[202:203]
	v_pk_add_f32 v[96:97], v[96:97], v[200:201]
	global_store_dwordx4 v[116:117], v[96:99], off offset:576
	s_or_b64 exec, exec, s[26:27]
	s_and_saveexec_b64 s[26:27], s[8:9]
	s_cbranch_execnz .LBB0_700

;     __device__ __forceinline__ void operator()(const f32x4 (&acc)[2][2][4][2], const pg8::Unit& u, int wr, int wc, int fr, int fq) const {
;     ...
;                 if (row < NMR) { float* rowp = mod + ((size_t)l * NMR + row) * 9216 + col0;
; #pragma unroll
;                     for (int bj = 0; bj < 2; ++bj)
; #pragma unroll
;                         for (int n = 0; n < 2; ++n) { const f32x4 bv = *(const f32x4*)(bias + colg0 + bj * 128 + n * 16); *(f32x4*)(rowp + bj * 128 + n * 16) = acc[ai][bj][m][n] + bv; } } }
.LBB0_708:
	v_add_u32_e32 v82, s1, v136
	v_mov_b64_e32 v[80:81], s[80:81]
	v_mad_i64_i32 v[80:81], s[28:29], v82, s59, v[80:81]
	v_lshl_add_u64 v[84:85], v[160:161], 2, v[80:81]
	v_pk_add_f32 v[78:79], v[78:79], v[190:191]
	v_pk_add_f32 v[76:77], v[76:77], v[188:189]
	global_store_dwordx4 v[84:85], v[76:79], off
	v_pk_add_f32 v[74:75], v[74:75], v[194:195]
	v_pk_add_f32 v[72:73], v[72:73], v[192:193]
	global_store_dwordx4 v[84:85], v[72:75], off offset:64
	v_pk_add_f32 v[70:71], v[70:71], v[198:199]
	v_pk_add_f32 v[68:69], v[68:69], v[196:197]
	global_store_dwordx4 v[84:85], v[68:71], off offset:512
	v_pk_add_f32 v[66:67], v[66:67], v[202:203]
	v_pk_add_f32 v[64:65], v[64:65], v[200:201]
	global_store_dwordx4 v[84:85], v[64:67], off offset:576
	s_or_b64 exec, exec, s[26:27]
	s_and_saveexec_b64 s[26:27], s[12:13]
	s_cbranch_execnz .LBB0_702

;     __device__ __forceinline__ void operator()(const f32x4 (&acc)[2][2][4][2], const pg8::Unit& u, int wr, int wc, int fr, int fq) const {
;     ...
;                 if (row < NMR) { float* rowp = mod + ((size_t)l * NMR + row) * 9216 + col0;
; #pragma unroll
;                     for (int bj = 0; bj < 2; ++bj)
; #pragma unroll
;                         for (int n = 0; n < 2; ++n) { const f32x4 bv = *(const f32x4*)(bias + colg0 + bj * 128 + n * 16); *(f32x4*)(rowp + bj * 128 + n * 16) = acc[ai][bj][m][n] + bv; } } }
.LBB0_710:
	v_add_u32_e32 v50, s1, v140
	v_mov_b64_e32 v[48:49], s[80:81]
	v_mad_i64_i32 v[48:49], s[28:29], v50, s59, v[48:49]
	v_lshl_add_u64 v[52:53], v[160:161], 2, v[48:49]
	v_pk_add_f32 v[46:47], v[46:47], v[190:191]
	v_pk_add_f32 v[44:45], v[44:45], v[188:189]
	global_store_dwordx4 v[52:53], v[44:47], off
	v_pk_add_f32 v[42:43], v[42:43], v[194:195]
	v_pk_add_f32 v[40:41], v[40:41], v[192:193]
	global_store_dwordx4 v[52:53], v[40:43], off offset:64
	v_pk_add_f32 v[38:39], v[38:39], v[198:199]
	v_pk_add_f32 v[36:37], v[36:37], v[196:197]
	global_store_dwordx4 v[52:53], v[36:39], off offset:512
	v_pk_add_f32 v[34:35], v[34:35], v[202:203]
	v_pk_add_f32 v[32:33], v[32:33], v[200:201]
	global_store_dwordx4 v[52:53], v[32:35], off offset:576
	s_or_b64 exec, exec, s[26:27]
	s_and_saveexec_b64 s[26:27], s[16:17]
	s_cbranch_execnz .LBB0_704

;     __device__ __forceinline__ void operator()(const f32x4 (&acc)[2][2][4][2], const pg8::Unit& u, int wr, int wc, int fr, int fq) const {
;     ...
;                 if (row < NMR) { float* rowp = mod + ((size_t)l * NMR + row) * 9216 + col0;
; #pragma unroll
;                     for (int bj = 0; bj < 2; ++bj)
; #pragma unroll
;                         for (int n = 0; n < 2; ++n) { const f32x4 bv = *(const f32x4*)(bias + colg0 + bj * 128 + n * 16); *(f32x4*)(rowp + bj * 128 + n * 16) = acc[ai][bj][m][n] + bv; } } }
.LBB0_712:
	v_add_u32_e32 v18, s1, v152
	v_mov_b64_e32 v[16:17], s[80:81]
	v_mad_i64_i32 v[16:17], s[28:29], v18, s59, v[16:17]
	v_lshl_add_u64 v[20:21], v[160:161], 2, v[16:17]
	v_pk_add_f32 v[14:15], v[14:15], v[190:191]
	v_pk_add_f32 v[12:13], v[12:13], v[188:189]
	global_store_dwordx4 v[20:21], v[12:15], off
	v_pk_add_f32 v[10:11], v[10:11], v[194:195]
	v_pk_add_f32 v[8:9], v[8:9], v[192:193]
	global_store_dwordx4 v[20:21], v[8:11], off offset:64
	v_pk_add_f32 v[6:7], v[6:7], v[198:199]
	v_pk_add_f32 v[4:5], v[4:5], v[196:197]
	global_store_dwordx4 v[20:21], v[4:7], off offset:512
	v_pk_add_f32 v[2:3], v[2:3], v[202:203]
	v_pk_add_f32 v[0:1], v[0:1], v[200:201]
	global_store_dwordx4 v[20:21], v[0:3], off offset:576
	s_branch .LBB0_692
